# v9: v4 + nt (streaming) hint on the P0 conversion stores
# speedup vs baseline: 1.0064x; 1.0035x over previous
; template <bool GAIN = false>
; __device__ __forceinline__ void tr_super(const float* W, size_t ldw, int k0, int c0, bf16* WT, int nd0, int K, LAS unsigned char* lds, int wave, int lane, int kd0, const float* gk = nullptr) {
;     ...
;     for (int r = 0; r < 8; ++r)
; #pragma unroll
;         for (int h = 0; h < 8; ++h) tile[(8 * wave + r) * 513 + 64 * h + lane] = __builtin_nontemporal_load(W + (size_t)(k0 + 8 * wave + r) * ldw + c0 + 64 * h + lane);
;     __syncthreads();
; __global__ void __launch_bounds__(NTHR, 2) mk_fwd(Args args) {
;     ...
;         for (int o = bx; o < 1024; o += G) {
;             if (o < 256) tr_super(args.in[11], D, 64 * (o >> 3), 512 * (o & 7), WPA, 512 * (o & 7), D, lds, wave, lane, 64 * (o >> 3));
;             else if (o < 512) tr_super(args.in[12], D, 64 * ((o - 256) >> 3), 512 * (o & 7), WPA, 512 * (o & 7), D, lds, wave, lane, 2048 + 64 * ((o - 256) >> 3));
;             else tr_super(args.in[13], D, 64 * ((o - 512) >> 3), 512 * (o & 7), WOUT, 512 * (o & 7), D, lds, wave, lane, 64 * ((o - 512) >> 3));
.LBB0_15:
	s_cmpk_gt_i32 s26, 0xff
	s_mov_b64 s[42:43], -1
	s_cbranch_scc0 .LBB0_21
	s_cmpk_gt_u32 s26, 0x1ff
	s_cbranch_scc0 .LBB0_18
	s_and_b32 s27, s24, 0x7fffffc0
	s_addk_i32 s27, 0xf000
	s_and_b32 s30, s25, 0xe00
	s_add_i32 s42, s27, s3
	s_lshl_b32 s0, s30, 2
	s_mov_b32 s43, s1
	v_lshl_add_u64 v[58:59], v[2:3], 0, s[0:1]
	s_lshl_b64 s[28:29], s[42:43], 14
	s_or_b32 s0, s42, 1
	v_lshl_add_u64 v[60:61], v[58:59], 0, s[28:29]
	s_lshl_b64 s[28:29], s[0:1], 14
	s_or_b32 s0, s42, 2
	global_load_dword v62, v[60:61], off nt
	global_load_dword v63, v[60:61], off offset:256 nt
	global_load_dword v64, v[60:61], off offset:512 nt
	global_load_dword v65, v[60:61], off offset:768 nt
	global_load_dword v66, v[60:61], off offset:1024 nt
	global_load_dword v67, v[60:61], off offset:1280 nt
	global_load_dword v68, v[60:61], off offset:1536 nt
	global_load_dword v69, v[60:61], off offset:1792 nt
	v_lshl_add_u64 v[60:61], v[58:59], 0, s[28:29]
	s_lshl_b64 s[28:29], s[0:1], 14
	s_or_b32 s0, s42, 3
	global_load_dword v70, v[60:61], off nt
	global_load_dword v71, v[60:61], off offset:256 nt
	global_load_dword v72, v[60:61], off offset:512 nt
	global_load_dword v73, v[60:61], off offset:768 nt
	global_load_dword v74, v[60:61], off offset:1024 nt
	global_load_dword v75, v[60:61], off offset:1280 nt
	global_load_dword v76, v[60:61], off offset:1536 nt
	global_load_dword v77, v[60:61], off offset:1792 nt
	v_lshl_add_u64 v[60:61], v[58:59], 0, s[28:29]
	s_lshl_b64 s[28:29], s[0:1], 14
	s_or_b32 s0, s42, 4
	global_load_dword v78, v[60:61], off nt
	global_load_dword v79, v[60:61], off offset:256 nt
	global_load_dword v80, v[60:61], off offset:512 nt
	global_load_dword v81, v[60:61], off offset:768 nt
	global_load_dword v82, v[60:61], off offset:1024 nt
	global_load_dword v83, v[60:61], off offset:1280 nt
	global_load_dword v84, v[60:61], off offset:1536 nt
	global_load_dword v85, v[60:61], off offset:1792 nt
	v_lshl_add_u64 v[60:61], v[58:59], 0, s[28:29]
	s_lshl_b64 s[28:29], s[0:1], 14
	s_or_b32 s0, s42, 5
	global_load_dword v86, v[60:61], off nt
	global_load_dword v87, v[60:61], off offset:256 nt
	global_load_dword v88, v[60:61], off offset:512 nt
	global_load_dword v89, v[60:61], off offset:768 nt
	global_load_dword v90, v[60:61], off offset:1024 nt
	global_load_dword v91, v[60:61], off offset:1280 nt
	global_load_dword v92, v[60:61], off offset:1536 nt
	global_load_dword v93, v[60:61], off offset:1792 nt
	v_lshl_add_u64 v[60:61], v[58:59], 0, s[28:29]
	s_lshl_b64 s[28:29], s[0:1], 14
	s_or_b32 s0, s42, 6
	global_load_dword v94, v[60:61], off nt
	global_load_dword v95, v[60:61], off offset:256 nt
	global_load_dword v96, v[60:61], off offset:512 nt
	global_load_dword v97, v[60:61], off offset:768 nt
	global_load_dword v98, v[60:61], off offset:1024 nt
	global_load_dword v99, v[60:61], off offset:1280 nt
	global_load_dword v100, v[60:61], off offset:1536 nt
	global_load_dword v101, v[60:61], off offset:1792 nt
	v_lshl_add_u64 v[60:61], v[58:59], 0, s[28:29]
	s_lshl_b64 s[28:29], s[0:1], 14
	s_or_b32 s0, s42, 7
	global_load_dword v102, v[60:61], off nt
	global_load_dword v103, v[60:61], off offset:256 nt
	global_load_dword v104, v[60:61], off offset:512 nt
	global_load_dword v105, v[60:61], off offset:768 nt
	global_load_dword v106, v[60:61], off offset:1024 nt
	global_load_dword v107, v[60:61], off offset:1280 nt
	global_load_dword v108, v[60:61], off offset:1536 nt
	global_load_dword v109, v[60:61], off offset:1792 nt
	v_lshl_add_u64 v[60:61], v[58:59], 0, s[28:29]
	s_lshl_b64 s[28:29], s[0:1], 14
	global_load_dword v110, v[60:61], off nt
	global_load_dword v111, v[60:61], off offset:256 nt
	global_load_dword v112, v[60:61], off offset:512 nt
	global_load_dword v113, v[60:61], off offset:768 nt
	global_load_dword v114, v[60:61], off offset:1024 nt
	global_load_dword v115, v[60:61], off offset:1280 nt
	global_load_dword v116, v[60:61], off offset:1536 nt
	s_nop 0
	global_load_dword v60, v[60:61], off offset:1792 nt
	v_lshl_add_u64 v[58:59], v[58:59], 0, s[28:29]
	global_load_dword v61, v[58:59], off nt
	global_load_dword v117, v[58:59], off offset:256 nt
	global_load_dword v118, v[58:59], off offset:512 nt
	global_load_dword v119, v[58:59], off offset:768 nt
	global_load_dword v120, v[58:59], off offset:1024 nt
	global_load_dword v121, v[58:59], off offset:1280 nt
	global_load_dword v122, v[58:59], off offset:1536 nt
	s_nop 0
	global_load_dword v58, v[58:59], off offset:1792 nt
	v_add_u32_e32 v59, 4, v48
	s_add_i32 s30, s30, s6
	s_lshr_b32 s0, s27, 6
	s_ashr_i32 s27, s30, 2
	s_andn2_b32 s27, s27, 63
	s_add_i32 s28, s27, s0
	s_ashr_i32 s29, s28, 31
	s_lshl_b64 s[42:43], s[28:29], 15
	s_waitcnt vmcnt(62)
	ds_write2st64_b32 v48, v62, v63 offset1:1
	s_waitcnt vmcnt(60)
	ds_write2st64_b32 v48, v64, v65 offset0:2 offset1:3
	s_waitcnt vmcnt(58)
	ds_write2st64_b32 v48, v66, v67 offset0:4 offset1:5
	s_waitcnt vmcnt(56)
	ds_write2st64_b32 v48, v68, v69 offset0:6 offset1:7
	s_waitcnt vmcnt(54)
	ds_write2st64_b32 v59, v70, v71 offset0:8 offset1:9
	s_waitcnt vmcnt(52)
	ds_write2st64_b32 v59, v72, v73 offset0:10 offset1:11
	s_waitcnt vmcnt(50)
	ds_write2st64_b32 v59, v74, v75 offset0:12 offset1:13
	s_waitcnt vmcnt(48)
	ds_write2st64_b32 v59, v76, v77 offset0:14 offset1:15
	v_add_u32_e32 v59, 8, v48
	s_waitcnt vmcnt(46)
	ds_write2st64_b32 v59, v78, v79 offset0:16 offset1:17
	s_waitcnt vmcnt(44)
	ds_write2st64_b32 v59, v80, v81 offset0:18 offset1:19
	s_waitcnt vmcnt(42)
	ds_write2st64_b32 v59, v82, v83 offset0:20 offset1:21
	s_waitcnt vmcnt(40)
	ds_write2st64_b32 v59, v84, v85 offset0:22 offset1:23
	v_add_u32_e32 v59, 12, v48
	s_waitcnt vmcnt(38)
; #define LAS __attribute__((address_space(3)))
; __host__ __device__ __forceinline__ size_t blk(int r, int k, int K) { return (((size_t)((r >> 8) * (K >> 6) + (k >> 6))) << 14) + (size_t)(((r & 255) << 6) + (k & 63)); }
; __device__ __forceinline__ unsigned pk2(float lo, float hi) { f32x2 v = {lo, hi}; bf16x2_t b = __builtin_convertvector(v, bf16x2_t); return __builtin_bit_cast(unsigned, b); }
; template <bool GAIN = false>
; __device__ __forceinline__ void tr_super(const float* W, size_t ldw, int k0, int c0, bf16* WT, int nd0, int K, LAS unsigned char* lds, int wave, int lane, int kd0, const float* gk = nullptr) {
;     ...
;     for (int r = 0; r < 8; ++r)
; #pragma unroll
;         for (int h = 0; h < 8; ++h) tile[(8 * wave + r) * 513 + 64 * h + lane] = __builtin_nontemporal_load(W + (size_t)(k0 + 8 * wave + r) * ldw + c0 + 64 * h + lane);
;     __syncthreads();
;     const int c = lane & 7;
;     f32x4 g0 = {1.f, 1.f, 1.f, 1.f}, g1 = g0;
;     if (GAIN) { g0 = *(const f32x4*)(gk + k0 + 8 * c); g1 = *(const f32x4*)(gk + k0 + 8 * c + 4); }
; #pragma unroll
;     for (int j = 0; j < 8; ++j) { const int n = (lane >> 3) + 8 * j; const LAS float* t = tile + (8 * c) * 513 + 64 * wave + n;
;         u32x4 o; o.x = pk2(t[0 * 513] * g0.x, t[1 * 513] * g0.y); o.y = pk2(t[2 * 513] * g0.z, t[3 * 513] * g0.w); o.z = pk2(t[4 * 513] * g1.x, t[5 * 513] * g1.y); o.w = pk2(t[6 * 513] * g1.z, t[7 * 513] * g1.w);
;         *(u32x4*)(WT + blk(nd0 + 64 * wave + n, kd0 + 8 * c, K)) = o; }
;     __syncthreads();
	ds_write2st64_b32 v59, v86, v87 offset0:24 offset1:25
	s_waitcnt vmcnt(36)
	ds_write2st64_b32 v59, v88, v89 offset0:26 offset1:27
	s_waitcnt vmcnt(34)
	ds_write2st64_b32 v59, v90, v91 offset0:28 offset1:29
	s_waitcnt vmcnt(32)
	ds_write2st64_b32 v59, v92, v93 offset0:30 offset1:31
	v_add_u32_e32 v59, 16, v48
	s_waitcnt vmcnt(30)
	ds_write2st64_b32 v59, v94, v95 offset0:32 offset1:33
	s_waitcnt vmcnt(28)
	ds_write2st64_b32 v59, v96, v97 offset0:34 offset1:35
	s_waitcnt vmcnt(26)
	ds_write2st64_b32 v59, v98, v99 offset0:36 offset1:37
	s_waitcnt vmcnt(24)
	ds_write2st64_b32 v59, v100, v101 offset0:38 offset1:39
	v_add_u32_e32 v59, 20, v48
	s_waitcnt vmcnt(22)
	ds_write2st64_b32 v59, v102, v103 offset0:40 offset1:41
	s_waitcnt vmcnt(20)
	ds_write2st64_b32 v59, v104, v105 offset0:42 offset1:43
	s_waitcnt vmcnt(18)
	ds_write2st64_b32 v59, v106, v107 offset0:44 offset1:45
	s_waitcnt vmcnt(16)
	ds_write2st64_b32 v59, v108, v109 offset0:46 offset1:47
	v_add_u32_e32 v59, 24, v48
	s_waitcnt vmcnt(14)
	ds_write2st64_b32 v59, v110, v111 offset0:48 offset1:49
	s_waitcnt vmcnt(12)
	ds_write2st64_b32 v59, v112, v113 offset0:50 offset1:51
	s_waitcnt vmcnt(10)
	ds_write2st64_b32 v59, v114, v115 offset0:52 offset1:53
	s_waitcnt vmcnt(8)
	ds_write2st64_b32 v59, v116, v60 offset0:54 offset1:55
	v_add_u32_e32 v59, 28, v48
	v_add_u32_e32 v80, 0x800, v49
	v_add_u32_e32 v81, 0x1000, v49
	v_add_u32_e32 v82, 0x1800, v49
	v_add_u32_e32 v83, 0x2000, v49
	v_add_u32_e32 v84, 0x2800, v49
	v_add_u32_e32 v85, 0x3000, v49
	v_add_u32_e32 v86, 0x3800, v49
	s_waitcnt vmcnt(6)
	ds_write2st64_b32 v59, v61, v117 offset0:56 offset1:57
	s_waitcnt vmcnt(4)
	ds_write2st64_b32 v59, v118, v119 offset0:58 offset1:59
	s_waitcnt vmcnt(2)
	ds_write2st64_b32 v59, v120, v121 offset0:60 offset1:61
	s_waitcnt vmcnt(0)
	ds_write2st64_b32 v59, v122, v58 offset0:62 offset1:63
	s_waitcnt lgkmcnt(0)
	s_barrier
	ds_read2_b32 v[62:63], v80 offset0:1 offset1:9
	ds_read2_b32 v[64:65], v49 offset1:8
	ds_read2_b32 v[66:67], v81 offset0:2 offset1:10
	ds_read2_b32 v[68:69], v82 offset0:3 offset1:11
	ds_read2_b32 v[70:71], v83 offset0:4 offset1:12
	ds_read2_b32 v[72:73], v84 offset0:5 offset1:13
	ds_read2_b32 v[74:75], v85 offset0:6 offset1:14
	ds_read2_b32 v[76:77], v86 offset0:7 offset1:15
	s_waitcnt lgkmcnt(6)
	v_cvt_pk_bf16_f32 v58, v64, v62
	s_waitcnt lgkmcnt(4)
	v_cvt_pk_bf16_f32 v59, v66, v68
	s_waitcnt lgkmcnt(2)
	v_cvt_pk_bf16_f32 v60, v70, v72
	v_lshl_add_u64 v[78:79], v[4:5], 0, s[42:43]
	s_waitcnt lgkmcnt(0)
	v_cvt_pk_bf16_f32 v61, v74, v76
	global_store_dwordx4 v[78:79], v[58:61], off nt
	s_nop 1
	v_cvt_pk_bf16_f32 v58, v65, v63
	v_cvt_pk_bf16_f32 v59, v67, v69
	v_cvt_pk_bf16_f32 v60, v71, v73
	v_cvt_pk_bf16_f32 v61, v75, v77
	ds_read2_b32 v[64:65], v49 offset0:16 offset1:24
	ds_read2_b32 v[66:67], v80 offset0:17 offset1:25
	ds_read2_b32 v[68:69], v81 offset0:18 offset1:26
	ds_read2_b32 v[70:71], v82 offset0:19 offset1:27
	ds_read2_b32 v[72:73], v83 offset0:20 offset1:28
	ds_read2_b32 v[74:75], v84 offset0:21 offset1:29
	ds_read2_b32 v[76:77], v85 offset0:22 offset1:30
	ds_read2_b32 v[78:79], v86 offset0:23 offset1:31
	v_lshl_add_u64 v[62:63], v[6:7], 0, s[42:43]
	global_store_dwordx4 v[62:63], v[58:61], off nt
	v_lshl_add_u64 v[62:63], v[8:9], 0, s[42:43]
	s_waitcnt lgkmcnt(6)
	v_cvt_pk_bf16_f32 v58, v64, v66
	s_waitcnt lgkmcnt(4)
	v_cvt_pk_bf16_f32 v59, v68, v70
	s_waitcnt lgkmcnt(2)
	v_cvt_pk_bf16_f32 v60, v72, v74
	s_waitcnt lgkmcnt(0)
	v_cvt_pk_bf16_f32 v61, v76, v78
	global_store_dwordx4 v[62:63], v[58:61], off nt
	v_lshl_add_u64 v[62:63], v[10:11], 0, s[42:43]
	s_nop 0
	v_cvt_pk_bf16_f32 v58, v65, v67
	v_cvt_pk_bf16_f32 v59, v69, v71
	v_cvt_pk_bf16_f32 v60, v73, v75
	v_cvt_pk_bf16_f32 v61, v77, v79
	ds_read2_b32 v[64:65], v49 offset0:32 offset1:40
	ds_read2_b32 v[66:67], v80 offset0:33 offset1:41
	ds_read2_b32 v[68:69], v81 offset0:34 offset1:42
	ds_read2_b32 v[70:71], v82 offset0:35 offset1:43
	ds_read2_b32 v[72:73], v83 offset0:36 offset1:44
	ds_read2_b32 v[74:75], v84 offset0:37 offset1:45
	ds_read2_b32 v[76:77], v85 offset0:38 offset1:46
	ds_read2_b32 v[78:79], v86 offset0:39 offset1:47
	global_store_dwordx4 v[62:63], v[58:61], off nt
	v_lshl_add_u64 v[62:63], v[12:13], 0, s[42:43]
	s_waitcnt lgkmcnt(6)
	v_cvt_pk_bf16_f32 v58, v64, v66
	s_waitcnt lgkmcnt(4)
	v_cvt_pk_bf16_f32 v59, v68, v70
	s_waitcnt lgkmcnt(2)
	v_cvt_pk_bf16_f32 v60, v72, v74
	s_waitcnt lgkmcnt(0)
	v_cvt_pk_bf16_f32 v61, v76, v78
	global_store_dwordx4 v[62:63], v[58:61], off nt
	v_lshl_add_u64 v[62:63], v[14:15], 0, s[42:43]
	s_nop 0
	v_cvt_pk_bf16_f32 v58, v65, v67
	v_cvt_pk_bf16_f32 v59, v69, v71
	v_cvt_pk_bf16_f32 v60, v73, v75
	v_cvt_pk_bf16_f32 v61, v77, v79
	ds_read2_b32 v[64:65], v49 offset0:48 offset1:56
	ds_read2_b32 v[66:67], v80 offset0:49 offset1:57
	ds_read2_b32 v[68:69], v81 offset0:50 offset1:58
	ds_read2_b32 v[70:71], v82 offset0:51 offset1:59
	ds_read2_b32 v[72:73], v83 offset0:52 offset1:60
	ds_read2_b32 v[74:75], v84 offset0:53 offset1:61
	ds_read2_b32 v[76:77], v85 offset0:54 offset1:62
	ds_read2_b32 v[78:79], v86 offset0:55 offset1:63
	global_store_dwordx4 v[62:63], v[58:61], off nt
	v_lshl_add_u64 v[62:63], v[16:17], 0, s[42:43]
	s_waitcnt lgkmcnt(6)
	v_cvt_pk_bf16_f32 v58, v64, v66
	s_waitcnt lgkmcnt(4)
	v_cvt_pk_bf16_f32 v59, v68, v70
	s_waitcnt lgkmcnt(2)
	v_cvt_pk_bf16_f32 v60, v72, v74
	s_waitcnt lgkmcnt(0)
	v_cvt_pk_bf16_f32 v61, v76, v78
	global_store_dwordx4 v[62:63], v[58:61], off nt
	v_lshl_add_u64 v[62:63], v[18:19], 0, s[42:43]
	s_mov_b64 s[42:43], 0
	v_cvt_pk_bf16_f32 v58, v65, v67
	v_cvt_pk_bf16_f32 v59, v69, v71
	v_cvt_pk_bf16_f32 v60, v73, v75
	v_cvt_pk_bf16_f32 v61, v77, v79
	global_store_dwordx4 v[62:63], v[58:61], off nt
	s_barrier
; template <bool GAIN = false>
; __device__ __forceinline__ void tr_super(const float* W, size_t ldw, int k0, int c0, bf16* WT, int nd0, int K, LAS unsigned char* lds, int wave, int lane, int kd0, const float* gk = nullptr) {
;     ...
;     for (int r = 0; r < 8; ++r)
; #pragma unroll
;         for (int h = 0; h < 8; ++h) tile[(8 * wave + r) * 513 + 64 * h + lane] = __builtin_nontemporal_load(W + (size_t)(k0 + 8 * wave + r) * ldw + c0 + 64 * h + lane);
;     __syncthreads();
; __global__ void __launch_bounds__(NTHR, 2) mk_fwd(Args args) {
;     ...
;         for (int o = bx; o < 1024; o += G) {
;             if (o < 256) tr_super(args.in[11], D, 64 * (o >> 3), 512 * (o & 7), WPA, 512 * (o & 7), D, lds, wave, lane, 64 * (o >> 3));
;             else if (o < 512) tr_super(args.in[12], D, 64 * ((o - 256) >> 3), 512 * (o & 7), WPA, 512 * (o & 7), D, lds, wave, lane, 2048 + 64 * ((o - 256) >> 3));
.LBB0_18:
	s_andn2_b64 vcc, exec, s[42:43]
	s_cbranch_vccnz .LBB0_20
	s_and_b32 s0, s24, 0xfc0
	s_and_b32 s27, s25, 0xe00
	s_add_i32 s42, s7, s0
	s_lshl_b32 s0, s27, 2
	s_mov_b32 s43, s1
	v_lshl_add_u64 v[58:59], v[20:21], 0, s[0:1]
	s_lshl_b64 s[28:29], s[42:43], 14
	s_or_b32 s0, s42, 1
	v_lshl_add_u64 v[60:61], v[58:59], 0, s[28:29]
	s_lshl_b64 s[28:29], s[0:1], 14
	s_or_b32 s0, s42, 2
	global_load_dword v62, v[60:61], off nt
	global_load_dword v63, v[60:61], off offset:256 nt
	global_load_dword v64, v[60:61], off offset:512 nt
	global_load_dword v65, v[60:61], off offset:768 nt
	global_load_dword v66, v[60:61], off offset:1024 nt
	global_load_dword v67, v[60:61], off offset:1280 nt
	global_load_dword v68, v[60:61], off offset:1536 nt
	global_load_dword v69, v[60:61], off offset:1792 nt
	v_lshl_add_u64 v[60:61], v[58:59], 0, s[28:29]
	s_lshl_b64 s[28:29], s[0:1], 14
	s_or_b32 s0, s42, 3
	global_load_dword v70, v[60:61], off nt
	global_load_dword v71, v[60:61], off offset:256 nt
	global_load_dword v72, v[60:61], off offset:512 nt
	global_load_dword v73, v[60:61], off offset:768 nt
	global_load_dword v74, v[60:61], off offset:1024 nt
	global_load_dword v75, v[60:61], off offset:1280 nt
	global_load_dword v76, v[60:61], off offset:1536 nt
	global_load_dword v77, v[60:61], off offset:1792 nt
	v_lshl_add_u64 v[60:61], v[58:59], 0, s[28:29]
	s_lshl_b64 s[28:29], s[0:1], 14
	s_or_b32 s0, s42, 4
	global_load_dword v78, v[60:61], off nt
	global_load_dword v79, v[60:61], off offset:256 nt
	global_load_dword v80, v[60:61], off offset:512 nt
	global_load_dword v81, v[60:61], off offset:768 nt
	global_load_dword v82, v[60:61], off offset:1024 nt
	global_load_dword v83, v[60:61], off offset:1280 nt
	global_load_dword v84, v[60:61], off offset:1536 nt
	global_load_dword v85, v[60:61], off offset:1792 nt
	v_lshl_add_u64 v[60:61], v[58:59], 0, s[28:29]
	s_lshl_b64 s[28:29], s[0:1], 14
	s_or_b32 s0, s42, 5
	global_load_dword v86, v[60:61], off nt
	global_load_dword v87, v[60:61], off offset:256 nt
	global_load_dword v88, v[60:61], off offset:512 nt
	global_load_dword v89, v[60:61], off offset:768 nt
	global_load_dword v90, v[60:61], off offset:1024 nt
	global_load_dword v91, v[60:61], off offset:1280 nt
	global_load_dword v92, v[60:61], off offset:1536 nt
	global_load_dword v93, v[60:61], off offset:1792 nt
	v_lshl_add_u64 v[60:61], v[58:59], 0, s[28:29]
	s_lshl_b64 s[28:29], s[0:1], 14
	s_or_b32 s0, s42, 6
	global_load_dword v94, v[60:61], off nt
	global_load_dword v95, v[60:61], off offset:256 nt
	global_load_dword v96, v[60:61], off offset:512 nt
	global_load_dword v97, v[60:61], off offset:768 nt
	global_load_dword v98, v[60:61], off offset:1024 nt
	global_load_dword v99, v[60:61], off offset:1280 nt
	global_load_dword v100, v[60:61], off offset:1536 nt
	global_load_dword v101, v[60:61], off offset:1792 nt
	v_lshl_add_u64 v[60:61], v[58:59], 0, s[28:29]
	s_lshl_b64 s[28:29], s[0:1], 14
	s_or_b32 s0, s42, 7
	global_load_dword v102, v[60:61], off nt
	global_load_dword v103, v[60:61], off offset:256 nt
	global_load_dword v104, v[60:61], off offset:512 nt
	global_load_dword v105, v[60:61], off offset:768 nt
	global_load_dword v106, v[60:61], off offset:1024 nt
	global_load_dword v107, v[60:61], off offset:1280 nt
	global_load_dword v108, v[60:61], off offset:1536 nt
	global_load_dword v109, v[60:61], off offset:1792 nt
	v_lshl_add_u64 v[60:61], v[58:59], 0, s[28:29]
	s_lshl_b64 s[28:29], s[0:1], 14
	global_load_dword v110, v[60:61], off nt
	global_load_dword v111, v[60:61], off offset:256 nt
	global_load_dword v112, v[60:61], off offset:512 nt
	global_load_dword v113, v[60:61], off offset:768 nt
	global_load_dword v114, v[60:61], off offset:1024 nt
	global_load_dword v115, v[60:61], off offset:1280 nt
	global_load_dword v116, v[60:61], off offset:1536 nt
	s_nop 0
	global_load_dword v60, v[60:61], off offset:1792 nt
	v_lshl_add_u64 v[58:59], v[58:59], 0, s[28:29]
	global_load_dword v61, v[58:59], off nt
	global_load_dword v117, v[58:59], off offset:256 nt
	global_load_dword v118, v[58:59], off offset:512 nt
	global_load_dword v119, v[58:59], off offset:768 nt
	global_load_dword v120, v[58:59], off offset:1024 nt
	global_load_dword v121, v[58:59], off offset:1280 nt
	global_load_dword v122, v[58:59], off offset:1536 nt
	s_nop 0
	global_load_dword v58, v[58:59], off offset:1792 nt
	v_add_u32_e32 v59, 4, v48
	s_add_i32 s27, s27, s6
	s_ashr_i32 s27, s27, 2
	s_lshr_b32 s0, s26, 3
	s_andn2_b32 s27, s27, 63
	s_or_b32 s28, s27, s0
	s_ashr_i32 s29, s28, 31
	s_lshl_b64 s[42:43], s[28:29], 15
	s_waitcnt vmcnt(62)
	ds_write2st64_b32 v48, v62, v63 offset1:1
	s_waitcnt vmcnt(60)
	ds_write2st64_b32 v48, v64, v65 offset0:2 offset1:3
	s_waitcnt vmcnt(58)
	ds_write2st64_b32 v48, v66, v67 offset0:4 offset1:5
	s_waitcnt vmcnt(56)
	ds_write2st64_b32 v48, v68, v69 offset0:6 offset1:7
	s_waitcnt vmcnt(54)
	ds_write2st64_b32 v59, v70, v71 offset0:8 offset1:9
	s_waitcnt vmcnt(52)
	ds_write2st64_b32 v59, v72, v73 offset0:10 offset1:11
	s_waitcnt vmcnt(50)
	ds_write2st64_b32 v59, v74, v75 offset0:12 offset1:13
	s_waitcnt vmcnt(48)
	ds_write2st64_b32 v59, v76, v77 offset0:14 offset1:15
	v_add_u32_e32 v59, 8, v48
	s_waitcnt vmcnt(46)
	ds_write2st64_b32 v59, v78, v79 offset0:16 offset1:17
	s_waitcnt vmcnt(44)
	ds_write2st64_b32 v59, v80, v81 offset0:18 offset1:19
	s_waitcnt vmcnt(42)
	ds_write2st64_b32 v59, v82, v83 offset0:20 offset1:21
	s_waitcnt vmcnt(40)
	ds_write2st64_b32 v59, v84, v85 offset0:22 offset1:23
	v_add_u32_e32 v59, 12, v48
	s_waitcnt vmcnt(38)
	ds_write2st64_b32 v59, v86, v87 offset0:24 offset1:25
	s_waitcnt vmcnt(36)
; #define LAS __attribute__((address_space(3)))
; __host__ __device__ __forceinline__ size_t blk(int r, int k, int K) { return (((size_t)((r >> 8) * (K >> 6) + (k >> 6))) << 14) + (size_t)(((r & 255) << 6) + (k & 63)); }
; __device__ __forceinline__ unsigned pk2(float lo, float hi) { f32x2 v = {lo, hi}; bf16x2_t b = __builtin_convertvector(v, bf16x2_t); return __builtin_bit_cast(unsigned, b); }
; template <bool GAIN = false>
; __device__ __forceinline__ void tr_super(const float* W, size_t ldw, int k0, int c0, bf16* WT, int nd0, int K, LAS unsigned char* lds, int wave, int lane, int kd0, const float* gk = nullptr) {
;     ...
;     for (int r = 0; r < 8; ++r)
; #pragma unroll
;         for (int h = 0; h < 8; ++h) tile[(8 * wave + r) * 513 + 64 * h + lane] = __builtin_nontemporal_load(W + (size_t)(k0 + 8 * wave + r) * ldw + c0 + 64 * h + lane);
;     __syncthreads();
;     const int c = lane & 7;
;     f32x4 g0 = {1.f, 1.f, 1.f, 1.f}, g1 = g0;
;     if (GAIN) { g0 = *(const f32x4*)(gk + k0 + 8 * c); g1 = *(const f32x4*)(gk + k0 + 8 * c + 4); }
; #pragma unroll
;     for (int j = 0; j < 8; ++j) { const int n = (lane >> 3) + 8 * j; const LAS float* t = tile + (8 * c) * 513 + 64 * wave + n;
;         u32x4 o; o.x = pk2(t[0 * 513] * g0.x, t[1 * 513] * g0.y); o.y = pk2(t[2 * 513] * g0.z, t[3 * 513] * g0.w); o.z = pk2(t[4 * 513] * g1.x, t[5 * 513] * g1.y); o.w = pk2(t[6 * 513] * g1.z, t[7 * 513] * g1.w);
;         *(u32x4*)(WT + blk(nd0 + 64 * wave + n, kd0 + 8 * c, K)) = o; }
;     __syncthreads();
	ds_write2st64_b32 v59, v88, v89 offset0:26 offset1:27
	s_waitcnt vmcnt(34)
	ds_write2st64_b32 v59, v90, v91 offset0:28 offset1:29
	s_waitcnt vmcnt(32)
	ds_write2st64_b32 v59, v92, v93 offset0:30 offset1:31
	v_add_u32_e32 v59, 16, v48
	s_waitcnt vmcnt(30)
	ds_write2st64_b32 v59, v94, v95 offset0:32 offset1:33
	s_waitcnt vmcnt(28)
	ds_write2st64_b32 v59, v96, v97 offset0:34 offset1:35
	s_waitcnt vmcnt(26)
	ds_write2st64_b32 v59, v98, v99 offset0:36 offset1:37
	s_waitcnt vmcnt(24)
	ds_write2st64_b32 v59, v100, v101 offset0:38 offset1:39
	v_add_u32_e32 v59, 20, v48
	s_waitcnt vmcnt(22)
	ds_write2st64_b32 v59, v102, v103 offset0:40 offset1:41
	s_waitcnt vmcnt(20)
	ds_write2st64_b32 v59, v104, v105 offset0:42 offset1:43
	s_waitcnt vmcnt(18)
	ds_write2st64_b32 v59, v106, v107 offset0:44 offset1:45
	s_waitcnt vmcnt(16)
	ds_write2st64_b32 v59, v108, v109 offset0:46 offset1:47
	v_add_u32_e32 v59, 24, v48
	s_waitcnt vmcnt(14)
	ds_write2st64_b32 v59, v110, v111 offset0:48 offset1:49
	s_waitcnt vmcnt(12)
	ds_write2st64_b32 v59, v112, v113 offset0:50 offset1:51
	s_waitcnt vmcnt(10)
	ds_write2st64_b32 v59, v114, v115 offset0:52 offset1:53
	s_waitcnt vmcnt(8)
	ds_write2st64_b32 v59, v116, v60 offset0:54 offset1:55
	v_add_u32_e32 v59, 28, v48
	v_add_u32_e32 v80, 0x800, v49
	v_add_u32_e32 v81, 0x1000, v49
	v_add_u32_e32 v82, 0x1800, v49
	v_add_u32_e32 v83, 0x2000, v49
	v_add_u32_e32 v84, 0x2800, v49
	v_add_u32_e32 v85, 0x3000, v49
	v_add_u32_e32 v86, 0x3800, v49
	s_waitcnt vmcnt(6)
	ds_write2st64_b32 v59, v61, v117 offset0:56 offset1:57
	s_waitcnt vmcnt(4)
	ds_write2st64_b32 v59, v118, v119 offset0:58 offset1:59
	s_waitcnt vmcnt(2)
	ds_write2st64_b32 v59, v120, v121 offset0:60 offset1:61
	s_waitcnt vmcnt(0)
	ds_write2st64_b32 v59, v122, v58 offset0:62 offset1:63
	s_waitcnt lgkmcnt(0)
	s_barrier
	ds_read2_b32 v[62:63], v80 offset0:1 offset1:9
	ds_read2_b32 v[64:65], v49 offset1:8
	ds_read2_b32 v[66:67], v81 offset0:2 offset1:10
	ds_read2_b32 v[68:69], v82 offset0:3 offset1:11
	ds_read2_b32 v[70:71], v83 offset0:4 offset1:12
	ds_read2_b32 v[72:73], v84 offset0:5 offset1:13
	ds_read2_b32 v[74:75], v85 offset0:6 offset1:14
	ds_read2_b32 v[76:77], v86 offset0:7 offset1:15
	s_waitcnt lgkmcnt(6)
	v_cvt_pk_bf16_f32 v58, v64, v62
	s_waitcnt lgkmcnt(4)
	v_cvt_pk_bf16_f32 v59, v66, v68
	s_waitcnt lgkmcnt(2)
	v_cvt_pk_bf16_f32 v60, v70, v72
	v_lshl_add_u64 v[78:79], v[22:23], 0, s[42:43]
	s_waitcnt lgkmcnt(0)
	v_cvt_pk_bf16_f32 v61, v74, v76
	global_store_dwordx4 v[78:79], v[58:61], off nt
	s_nop 1
	v_cvt_pk_bf16_f32 v58, v65, v63
	v_cvt_pk_bf16_f32 v59, v67, v69
	v_cvt_pk_bf16_f32 v60, v71, v73
	v_cvt_pk_bf16_f32 v61, v75, v77
	ds_read2_b32 v[64:65], v49 offset0:16 offset1:24
	ds_read2_b32 v[66:67], v80 offset0:17 offset1:25
	ds_read2_b32 v[68:69], v81 offset0:18 offset1:26
	ds_read2_b32 v[70:71], v82 offset0:19 offset1:27
	ds_read2_b32 v[72:73], v83 offset0:20 offset1:28
	ds_read2_b32 v[74:75], v84 offset0:21 offset1:29
	ds_read2_b32 v[76:77], v85 offset0:22 offset1:30
	ds_read2_b32 v[78:79], v86 offset0:23 offset1:31
	v_lshl_add_u64 v[62:63], v[24:25], 0, s[42:43]
	global_store_dwordx4 v[62:63], v[58:61], off nt
	v_lshl_add_u64 v[62:63], v[26:27], 0, s[42:43]
	s_waitcnt lgkmcnt(6)
	v_cvt_pk_bf16_f32 v58, v64, v66
	s_waitcnt lgkmcnt(4)
	v_cvt_pk_bf16_f32 v59, v68, v70
	s_waitcnt lgkmcnt(2)
	v_cvt_pk_bf16_f32 v60, v72, v74
	s_waitcnt lgkmcnt(0)
	v_cvt_pk_bf16_f32 v61, v76, v78
	global_store_dwordx4 v[62:63], v[58:61], off nt
	v_lshl_add_u64 v[62:63], v[28:29], 0, s[42:43]
	s_nop 0
	v_cvt_pk_bf16_f32 v58, v65, v67
	v_cvt_pk_bf16_f32 v59, v69, v71
	v_cvt_pk_bf16_f32 v60, v73, v75
	v_cvt_pk_bf16_f32 v61, v77, v79
	ds_read2_b32 v[64:65], v49 offset0:32 offset1:40
	ds_read2_b32 v[66:67], v80 offset0:33 offset1:41
	ds_read2_b32 v[68:69], v81 offset0:34 offset1:42
	ds_read2_b32 v[70:71], v82 offset0:35 offset1:43
	ds_read2_b32 v[72:73], v83 offset0:36 offset1:44
	ds_read2_b32 v[74:75], v84 offset0:37 offset1:45
	ds_read2_b32 v[76:77], v85 offset0:38 offset1:46
	ds_read2_b32 v[78:79], v86 offset0:39 offset1:47
	global_store_dwordx4 v[62:63], v[58:61], off nt
	v_lshl_add_u64 v[62:63], v[30:31], 0, s[42:43]
	s_waitcnt lgkmcnt(6)
	v_cvt_pk_bf16_f32 v58, v64, v66
	s_waitcnt lgkmcnt(4)
	v_cvt_pk_bf16_f32 v59, v68, v70
	s_waitcnt lgkmcnt(2)
	v_cvt_pk_bf16_f32 v60, v72, v74
	s_waitcnt lgkmcnt(0)
	v_cvt_pk_bf16_f32 v61, v76, v78
	global_store_dwordx4 v[62:63], v[58:61], off nt
	v_lshl_add_u64 v[62:63], v[32:33], 0, s[42:43]
	s_nop 0
	v_cvt_pk_bf16_f32 v58, v65, v67
	v_cvt_pk_bf16_f32 v59, v69, v71
	v_cvt_pk_bf16_f32 v60, v73, v75
	v_cvt_pk_bf16_f32 v61, v77, v79
	ds_read2_b32 v[64:65], v49 offset0:48 offset1:56
	ds_read2_b32 v[66:67], v80 offset0:49 offset1:57
	ds_read2_b32 v[68:69], v81 offset0:50 offset1:58
	ds_read2_b32 v[70:71], v82 offset0:51 offset1:59
	ds_read2_b32 v[72:73], v83 offset0:52 offset1:60
	ds_read2_b32 v[74:75], v84 offset0:53 offset1:61
	ds_read2_b32 v[76:77], v85 offset0:54 offset1:62
	ds_read2_b32 v[78:79], v86 offset0:55 offset1:63
	global_store_dwordx4 v[62:63], v[58:61], off nt
	v_lshl_add_u64 v[62:63], v[34:35], 0, s[42:43]
	s_waitcnt lgkmcnt(6)
	v_cvt_pk_bf16_f32 v58, v64, v66
	s_waitcnt lgkmcnt(4)
	v_cvt_pk_bf16_f32 v59, v68, v70
	s_waitcnt lgkmcnt(2)
	v_cvt_pk_bf16_f32 v60, v72, v74
	s_waitcnt lgkmcnt(0)
	v_cvt_pk_bf16_f32 v61, v76, v78
	global_store_dwordx4 v[62:63], v[58:61], off nt
	v_lshl_add_u64 v[62:63], v[36:37], 0, s[42:43]
	s_nop 0
	v_cvt_pk_bf16_f32 v58, v65, v67
	v_cvt_pk_bf16_f32 v59, v69, v71
	v_cvt_pk_bf16_f32 v60, v73, v75
	v_cvt_pk_bf16_f32 v61, v77, v79
	global_store_dwordx4 v[62:63], v[58:61], off nt
	s_barrier

; template <bool GAIN = false>
; __device__ __forceinline__ void tr_super(const float* W, size_t ldw, int k0, int c0, bf16* WT, int nd0, int K, LAS unsigned char* lds, int wave, int lane, int kd0, const float* gk = nullptr) {
;     ...
;     for (int r = 0; r < 8; ++r)
; #pragma unroll
;         for (int h = 0; h < 8; ++h) tile[(8 * wave + r) * 513 + 64 * h + lane] = __builtin_nontemporal_load(W + (size_t)(k0 + 8 * wave + r) * ldw + c0 + 64 * h + lane);
;     __syncthreads();
; __global__ void __launch_bounds__(NTHR, 2) mk_fwd(Args args) {
;     ...
;         for (int o = bx; o < 1024; o += G) {
;             if (o < 256) tr_super(args.in[11], D, 64 * (o >> 3), 512 * (o & 7), WPA, 512 * (o & 7), D, lds, wave, lane, 64 * (o >> 3));
.LBB0_21:
	s_andn2_b64 vcc, exec, s[42:43]
	s_cbranch_vccnz .LBB0_14
	s_and_b32 s0, s26, 0x1ffffff8
	s_add_i32 s0, s0, s61
	s_and_b32 s27, s25, 0xe00
	s_lshl_b32 s42, s0, 3
	s_lshl_b32 s0, s27, 2
	s_ashr_i32 s43, s42, 31
	v_lshl_add_u64 v[58:59], v[38:39], 0, s[0:1]
	s_lshl_b64 s[28:29], s[42:43], 14
	v_lshl_add_u64 v[60:61], v[58:59], 0, s[28:29]
	s_or_b32 s28, s42, 1
	s_ashr_i32 s29, s28, 31
	s_lshl_b64 s[28:29], s[28:29], 14
	global_load_dword v66, v[60:61], off nt
	global_load_dword v67, v[60:61], off offset:256 nt
	global_load_dword v68, v[60:61], off offset:512 nt
	global_load_dword v69, v[60:61], off offset:768 nt
	global_load_dword v70, v[60:61], off offset:1024 nt
	global_load_dword v71, v[60:61], off offset:1280 nt
	global_load_dword v72, v[60:61], off offset:1536 nt
	global_load_dword v73, v[60:61], off offset:1792 nt
	v_lshl_add_u64 v[60:61], v[58:59], 0, s[28:29]
	s_or_b32 s28, s42, 2
	s_ashr_i32 s29, s28, 31
	s_lshl_b64 s[28:29], s[28:29], 14
	global_load_dword v74, v[60:61], off nt
	global_load_dword v75, v[60:61], off offset:256 nt
	global_load_dword v76, v[60:61], off offset:512 nt
	global_load_dword v77, v[60:61], off offset:768 nt
	global_load_dword v78, v[60:61], off offset:1024 nt
	global_load_dword v79, v[60:61], off offset:1280 nt
	global_load_dword v80, v[60:61], off offset:1536 nt
	global_load_dword v81, v[60:61], off offset:1792 nt
	v_lshl_add_u64 v[60:61], v[58:59], 0, s[28:29]
	s_or_b32 s28, s42, 3
	s_ashr_i32 s29, s28, 31
	s_lshl_b64 s[28:29], s[28:29], 14
	global_load_dword v82, v[60:61], off nt
	global_load_dword v83, v[60:61], off offset:256 nt
	global_load_dword v84, v[60:61], off offset:512 nt
	global_load_dword v85, v[60:61], off offset:768 nt
	global_load_dword v86, v[60:61], off offset:1024 nt
	global_load_dword v87, v[60:61], off offset:1280 nt
	global_load_dword v88, v[60:61], off offset:1536 nt
	global_load_dword v89, v[60:61], off offset:1792 nt
	v_lshl_add_u64 v[60:61], v[58:59], 0, s[28:29]
	s_or_b32 s28, s42, 4
	s_ashr_i32 s29, s28, 31
	s_or_b32 s30, s42, 5
	s_lshl_b64 s[28:29], s[28:29], 14
	s_ashr_i32 s31, s30, 31
	v_lshl_add_u64 v[62:63], v[58:59], 0, s[28:29]
	s_or_b32 s28, s42, 6
	s_lshl_b64 s[30:31], s[30:31], 14
	s_ashr_i32 s29, s28, 31
	v_lshl_add_u64 v[64:65], v[58:59], 0, s[30:31]
	s_lshl_b64 s[28:29], s[28:29], 14
	global_load_dword v90, v[60:61], off nt
	global_load_dword v91, v[60:61], off offset:256 nt
	global_load_dword v92, v[60:61], off offset:512 nt
	global_load_dword v93, v[60:61], off offset:768 nt
	global_load_dword v94, v[60:61], off offset:1024 nt
	global_load_dword v95, v[60:61], off offset:1280 nt
	global_load_dword v96, v[60:61], off offset:1536 nt
	global_load_dword v97, v[60:61], off offset:1792 nt
	global_load_dword v98, v[62:63], off nt
	global_load_dword v99, v[62:63], off offset:256 nt
	global_load_dword v100, v[62:63], off offset:512 nt
	global_load_dword v101, v[62:63], off offset:768 nt
	global_load_dword v102, v[62:63], off offset:1024 nt
	global_load_dword v103, v[62:63], off offset:1280 nt
	global_load_dword v104, v[62:63], off offset:1536 nt
	s_nop 0
	global_load_dword v62, v[62:63], off offset:1792 nt
	s_nop 0
	global_load_dword v63, v[64:65], off nt
	global_load_dword v105, v[64:65], off offset:256 nt
	global_load_dword v106, v[64:65], off offset:512 nt
	global_load_dword v107, v[64:65], off offset:768 nt
	global_load_dword v108, v[64:65], off offset:1024 nt
	global_load_dword v109, v[64:65], off offset:1280 nt
	global_load_dword v110, v[64:65], off offset:1536 nt
	s_nop 0
	global_load_dword v64, v[64:65], off offset:1792 nt
	v_lshl_add_u64 v[60:61], v[58:59], 0, s[28:29]
	s_or_b32 s28, s42, 7
	s_ashr_i32 s29, s28, 31
	s_lshl_b64 s[28:29], s[28:29], 14
	global_load_dword v65, v[60:61], off nt
	global_load_dword v111, v[60:61], off offset:256 nt
	global_load_dword v112, v[60:61], off offset:512 nt
	global_load_dword v113, v[60:61], off offset:768 nt
	global_load_dword v114, v[60:61], off offset:1024 nt
	global_load_dword v115, v[60:61], off offset:1280 nt
	global_load_dword v116, v[60:61], off offset:1536 nt
	s_nop 0
	global_load_dword v60, v[60:61], off offset:1792 nt
	v_lshl_add_u64 v[58:59], v[58:59], 0, s[28:29]
	global_load_dword v61, v[58:59], off nt
	global_load_dword v117, v[58:59], off offset:256 nt
	global_load_dword v118, v[58:59], off offset:512 nt
	global_load_dword v119, v[58:59], off offset:768 nt
	global_load_dword v120, v[58:59], off offset:1024 nt
	global_load_dword v121, v[58:59], off offset:1280 nt
	global_load_dword v122, v[58:59], off offset:1536 nt
	s_nop 0
	global_load_dword v58, v[58:59], off offset:1792 nt
	v_add_u32_e32 v59, 4, v48
	v_add_u32_e32 v123, 8, v48
	v_add_u32_e32 v124, 12, v48
	s_add_i32 s27, s27, s6
	s_ashr_i32 s27, s27, 2
	s_ashr_i32 s0, s26, 3
	s_andn2_b32 s27, s27, 63
	s_add_i32 s28, s27, s0
	s_ashr_i32 s29, s28, 31
	s_lshl_b64 s[42:43], s[28:29], 15
	s_waitcnt vmcnt(62)
	ds_write2st64_b32 v48, v66, v67 offset1:1
	s_waitcnt vmcnt(60)
	ds_write2st64_b32 v48, v68, v69 offset0:2 offset1:3
	s_waitcnt vmcnt(58)
	ds_write2st64_b32 v48, v70, v71 offset0:4 offset1:5
	s_waitcnt vmcnt(56)
	ds_write2st64_b32 v48, v72, v73 offset0:6 offset1:7
	s_waitcnt vmcnt(54)
	ds_write2st64_b32 v59, v74, v75 offset0:8 offset1:9
	s_waitcnt vmcnt(52)
	ds_write2st64_b32 v59, v76, v77 offset0:10 offset1:11
	s_waitcnt vmcnt(50)
	ds_write2st64_b32 v59, v78, v79 offset0:12 offset1:13
	s_waitcnt vmcnt(48)
	ds_write2st64_b32 v59, v80, v81 offset0:14 offset1:15
	s_waitcnt vmcnt(46)
	ds_write2st64_b32 v123, v82, v83 offset0:16 offset1:17
	s_waitcnt vmcnt(44)
	ds_write2st64_b32 v123, v84, v85 offset0:18 offset1:19
	s_waitcnt vmcnt(42)
; #define LAS __attribute__((address_space(3)))
; __host__ __device__ __forceinline__ size_t blk(int r, int k, int K) { return (((size_t)((r >> 8) * (K >> 6) + (k >> 6))) << 14) + (size_t)(((r & 255) << 6) + (k & 63)); }
; __device__ __forceinline__ unsigned pk2(float lo, float hi) { f32x2 v = {lo, hi}; bf16x2_t b = __builtin_convertvector(v, bf16x2_t); return __builtin_bit_cast(unsigned, b); }
; template <bool GAIN = false>
; __device__ __forceinline__ void tr_super(const float* W, size_t ldw, int k0, int c0, bf16* WT, int nd0, int K, LAS unsigned char* lds, int wave, int lane, int kd0, const float* gk = nullptr) {
;     ...
;     for (int r = 0; r < 8; ++r)
; #pragma unroll
;         for (int h = 0; h < 8; ++h) tile[(8 * wave + r) * 513 + 64 * h + lane] = __builtin_nontemporal_load(W + (size_t)(k0 + 8 * wave + r) * ldw + c0 + 64 * h + lane);
;     __syncthreads();
;     const int c = lane & 7;
;     f32x4 g0 = {1.f, 1.f, 1.f, 1.f}, g1 = g0;
;     if (GAIN) { g0 = *(const f32x4*)(gk + k0 + 8 * c); g1 = *(const f32x4*)(gk + k0 + 8 * c + 4); }
; #pragma unroll
;     for (int j = 0; j < 8; ++j) { const int n = (lane >> 3) + 8 * j; const LAS float* t = tile + (8 * c) * 513 + 64 * wave + n;
;         u32x4 o; o.x = pk2(t[0 * 513] * g0.x, t[1 * 513] * g0.y); o.y = pk2(t[2 * 513] * g0.z, t[3 * 513] * g0.w); o.z = pk2(t[4 * 513] * g1.x, t[5 * 513] * g1.y); o.w = pk2(t[6 * 513] * g1.z, t[7 * 513] * g1.w);
;         *(u32x4*)(WT + blk(nd0 + 64 * wave + n, kd0 + 8 * c, K)) = o; }
;     __syncthreads();
	ds_write2st64_b32 v123, v86, v87 offset0:20 offset1:21
	s_waitcnt vmcnt(40)
	ds_write2st64_b32 v123, v88, v89 offset0:22 offset1:23
	s_waitcnt vmcnt(38)
	ds_write2st64_b32 v124, v90, v91 offset0:24 offset1:25
	s_waitcnt vmcnt(36)
	ds_write2st64_b32 v124, v92, v93 offset0:26 offset1:27
	s_waitcnt vmcnt(34)
	ds_write2st64_b32 v124, v94, v95 offset0:28 offset1:29
	s_waitcnt vmcnt(32)
	ds_write2st64_b32 v124, v96, v97 offset0:30 offset1:31
	v_add_u32_e32 v59, 16, v48
	s_waitcnt vmcnt(30)
	ds_write2st64_b32 v59, v98, v99 offset0:32 offset1:33
	s_waitcnt vmcnt(28)
	ds_write2st64_b32 v59, v100, v101 offset0:34 offset1:35
	s_waitcnt vmcnt(26)
	ds_write2st64_b32 v59, v102, v103 offset0:36 offset1:37
	s_waitcnt vmcnt(24)
	ds_write2st64_b32 v59, v104, v62 offset0:38 offset1:39
	v_add_u32_e32 v59, 20, v48
	s_waitcnt vmcnt(22)
	ds_write2st64_b32 v59, v63, v105 offset0:40 offset1:41
	s_waitcnt vmcnt(20)
	ds_write2st64_b32 v59, v106, v107 offset0:42 offset1:43
	s_waitcnt vmcnt(18)
	ds_write2st64_b32 v59, v108, v109 offset0:44 offset1:45
	s_waitcnt vmcnt(16)
	ds_write2st64_b32 v59, v110, v64 offset0:46 offset1:47
	v_add_u32_e32 v59, 24, v48
	s_waitcnt vmcnt(14)
	ds_write2st64_b32 v59, v65, v111 offset0:48 offset1:49
	s_waitcnt vmcnt(12)
	ds_write2st64_b32 v59, v112, v113 offset0:50 offset1:51
	s_waitcnt vmcnt(10)
	ds_write2st64_b32 v59, v114, v115 offset0:52 offset1:53
	s_waitcnt vmcnt(8)
	ds_write2st64_b32 v59, v116, v60 offset0:54 offset1:55
	v_add_u32_e32 v59, 28, v48
	v_add_u32_e32 v80, 0x800, v49
	v_add_u32_e32 v81, 0x1000, v49
	v_add_u32_e32 v82, 0x1800, v49
	v_add_u32_e32 v83, 0x2000, v49
	v_add_u32_e32 v84, 0x2800, v49
	v_add_u32_e32 v85, 0x3000, v49
	v_add_u32_e32 v86, 0x3800, v49
	s_waitcnt vmcnt(6)
	ds_write2st64_b32 v59, v61, v117 offset0:56 offset1:57
	s_waitcnt vmcnt(4)
	ds_write2st64_b32 v59, v118, v119 offset0:58 offset1:59
	s_waitcnt vmcnt(2)
	ds_write2st64_b32 v59, v120, v121 offset0:60 offset1:61
	s_waitcnt vmcnt(0)
	ds_write2st64_b32 v59, v122, v58 offset0:62 offset1:63
	s_waitcnt lgkmcnt(0)
	s_barrier
	ds_read2_b32 v[62:63], v80 offset0:1 offset1:9
	ds_read2_b32 v[64:65], v49 offset1:8
	ds_read2_b32 v[66:67], v81 offset0:2 offset1:10
	ds_read2_b32 v[68:69], v82 offset0:3 offset1:11
	ds_read2_b32 v[70:71], v83 offset0:4 offset1:12
	ds_read2_b32 v[72:73], v84 offset0:5 offset1:13
	ds_read2_b32 v[74:75], v85 offset0:6 offset1:14
	ds_read2_b32 v[76:77], v86 offset0:7 offset1:15
	s_waitcnt lgkmcnt(6)
	v_cvt_pk_bf16_f32 v58, v64, v62
	s_waitcnt lgkmcnt(4)
	v_cvt_pk_bf16_f32 v59, v66, v68
	s_waitcnt lgkmcnt(2)
	v_cvt_pk_bf16_f32 v60, v70, v72
	v_lshl_add_u64 v[78:79], v[22:23], 0, s[42:43]
	s_waitcnt lgkmcnt(0)
	v_cvt_pk_bf16_f32 v61, v74, v76
	global_store_dwordx4 v[78:79], v[58:61], off nt
	s_nop 1
	v_cvt_pk_bf16_f32 v58, v65, v63
	v_cvt_pk_bf16_f32 v59, v67, v69
	v_cvt_pk_bf16_f32 v60, v71, v73
	v_cvt_pk_bf16_f32 v61, v75, v77
	ds_read2_b32 v[64:65], v49 offset0:16 offset1:24
	ds_read2_b32 v[66:67], v80 offset0:17 offset1:25
	ds_read2_b32 v[68:69], v81 offset0:18 offset1:26
	ds_read2_b32 v[70:71], v82 offset0:19 offset1:27
	ds_read2_b32 v[72:73], v83 offset0:20 offset1:28
	ds_read2_b32 v[74:75], v84 offset0:21 offset1:29
	ds_read2_b32 v[76:77], v85 offset0:22 offset1:30
	ds_read2_b32 v[78:79], v86 offset0:23 offset1:31
	v_lshl_add_u64 v[62:63], v[24:25], 0, s[42:43]
	global_store_dwordx4 v[62:63], v[58:61], off nt
	v_lshl_add_u64 v[62:63], v[26:27], 0, s[42:43]
	s_waitcnt lgkmcnt(6)
	v_cvt_pk_bf16_f32 v58, v64, v66
	s_waitcnt lgkmcnt(4)
	v_cvt_pk_bf16_f32 v59, v68, v70
	s_waitcnt lgkmcnt(2)
	v_cvt_pk_bf16_f32 v60, v72, v74
	s_waitcnt lgkmcnt(0)
	v_cvt_pk_bf16_f32 v61, v76, v78
	global_store_dwordx4 v[62:63], v[58:61], off nt
	v_lshl_add_u64 v[62:63], v[28:29], 0, s[42:43]
	s_nop 0
	v_cvt_pk_bf16_f32 v58, v65, v67
	v_cvt_pk_bf16_f32 v59, v69, v71
	v_cvt_pk_bf16_f32 v60, v73, v75
	v_cvt_pk_bf16_f32 v61, v77, v79
	ds_read2_b32 v[64:65], v49 offset0:32 offset1:40
	ds_read2_b32 v[66:67], v80 offset0:33 offset1:41
	ds_read2_b32 v[68:69], v81 offset0:34 offset1:42
	ds_read2_b32 v[70:71], v82 offset0:35 offset1:43
	ds_read2_b32 v[72:73], v83 offset0:36 offset1:44
	ds_read2_b32 v[74:75], v84 offset0:37 offset1:45
	ds_read2_b32 v[76:77], v85 offset0:38 offset1:46
	ds_read2_b32 v[78:79], v86 offset0:39 offset1:47
	global_store_dwordx4 v[62:63], v[58:61], off nt
	v_lshl_add_u64 v[62:63], v[30:31], 0, s[42:43]
	s_waitcnt lgkmcnt(6)
	v_cvt_pk_bf16_f32 v58, v64, v66
	s_waitcnt lgkmcnt(4)
	v_cvt_pk_bf16_f32 v59, v68, v70
	s_waitcnt lgkmcnt(2)
	v_cvt_pk_bf16_f32 v60, v72, v74
	s_waitcnt lgkmcnt(0)
	v_cvt_pk_bf16_f32 v61, v76, v78
	global_store_dwordx4 v[62:63], v[58:61], off nt
	v_lshl_add_u64 v[62:63], v[32:33], 0, s[42:43]
	s_nop 0
	v_cvt_pk_bf16_f32 v58, v65, v67
	v_cvt_pk_bf16_f32 v59, v69, v71
	v_cvt_pk_bf16_f32 v60, v73, v75
	v_cvt_pk_bf16_f32 v61, v77, v79
	ds_read2_b32 v[64:65], v49 offset0:48 offset1:56
	ds_read2_b32 v[66:67], v80 offset0:49 offset1:57
	ds_read2_b32 v[68:69], v81 offset0:50 offset1:58
	ds_read2_b32 v[70:71], v82 offset0:51 offset1:59
	ds_read2_b32 v[72:73], v83 offset0:52 offset1:60
	ds_read2_b32 v[74:75], v84 offset0:53 offset1:61
	ds_read2_b32 v[76:77], v85 offset0:54 offset1:62
	ds_read2_b32 v[78:79], v86 offset0:55 offset1:63
	global_store_dwordx4 v[62:63], v[58:61], off nt
	v_lshl_add_u64 v[62:63], v[34:35], 0, s[42:43]
	s_waitcnt lgkmcnt(6)
	v_cvt_pk_bf16_f32 v58, v64, v66
	s_waitcnt lgkmcnt(4)
	v_cvt_pk_bf16_f32 v59, v68, v70
	s_waitcnt lgkmcnt(2)
	v_cvt_pk_bf16_f32 v60, v72, v74
	s_waitcnt lgkmcnt(0)
	v_cvt_pk_bf16_f32 v61, v76, v78
	global_store_dwordx4 v[62:63], v[58:61], off nt
	v_lshl_add_u64 v[62:63], v[36:37], 0, s[42:43]
	s_nop 0
	v_cvt_pk_bf16_f32 v58, v65, v67
	v_cvt_pk_bf16_f32 v59, v69, v71
	v_cvt_pk_bf16_f32 v60, v73, v75
	v_cvt_pk_bf16_f32 v61, v77, v79
	global_store_dwordx4 v[62:63], v[58:61], off nt
	s_barrier
	s_branch .LBB0_14

; template <bool GAIN = false>
; __device__ __forceinline__ void tr_super(const float* W, size_t ldw, int k0, int c0, bf16* WT, int nd0, int K, LAS unsigned char* lds, int wave, int lane, int kd0, const float* gk = nullptr) {
;     ...
;     for (int r = 0; r < 8; ++r)
; #pragma unroll
;         for (int h = 0; h < 8; ++h) tile[(8 * wave + r) * 513 + 64 * h + lane] = __builtin_nontemporal_load(W + (size_t)(k0 + 8 * wave + r) * ldw + c0 + 64 * h + lane);
; __global__ void __launch_bounds__(NTHR, 2) mk_fwd(Args args) {
;     ...
;         for (int o = bx; o < (D / 64) * (NP / 512); o += G) { const int kb = o / (NP / 512), n0 = 512 * (o % (NP / 512));
;             tr_super<true>(args.in[6], DIN, 64 * kb, n0 + (n0 >= PC_SQ ? 16 : 0), WIN, n0, D, lds, wave, lane, 64 * kb, args.in[5]); }
.LBB0_25:
	s_mul_hi_i32 s0, s24, 0x66666667
	s_lshr_b32 s1, s0, 31
	s_ashr_i32 s25, s0, 4
	s_add_i32 s25, s25, s1
	s_mul_i32 s1, s25, 0xffffffd8
	s_lshl_b32 s0, s25, 6
	s_add_i32 s1, s24, s1
	s_cmp_gt_i32 s1, 11
	s_cselect_b32 s28, 16, 0
	s_mul_i32 s26, s25, 0xffffb000
	s_ashr_i32 s1, s0, 31
	s_add_i32 s29, s6, s7
	s_add_i32 s28, s28, s7
	s_add_i32 s27, s0, s3
	v_lshl_add_u64 v[68:69], s[0:1], 2, v[4:5]
	s_add_i32 s29, s29, s26
	s_add_i32 s0, s28, s26
	s_ashr_i32 s26, s29, 2
	s_ashr_i32 s1, s0, 31
	s_andn2_b32 s26, s26, 63
	v_lshl_add_u64 v[22:23], s[0:1], 2, v[2:3]
	s_or_b32 s30, s27, 1
	s_or_b32 s31, s27, 2
	s_or_b32 s33, s27, 3
	s_or_b32 s35, s27, 4
	s_or_b32 s42, s27, 5
	s_or_b32 s43, s27, 6
	s_or_b32 s44, s27, 7
	s_add_i32 s0, s26, s25
	v_mad_i64_i32 v[24:25], s[26:27], s27, v38, v[22:23]
	v_mad_i64_i32 v[26:27], s[26:27], s30, v38, v[22:23]
	v_mad_i64_i32 v[28:29], s[26:27], s31, v38, v[22:23]
	v_mad_i64_i32 v[30:31], s[26:27], s33, v38, v[22:23]
	v_mad_i64_i32 v[32:33], s[26:27], s35, v38, v[22:23]
	v_mad_i64_i32 v[34:35], s[26:27], s42, v38, v[22:23]
	v_mad_i64_i32 v[36:37], s[26:27], s43, v38, v[22:23]
	v_mad_i64_i32 v[22:23], s[26:27], s44, v38, v[22:23]
	global_load_dword v63, v[24:25], off nt
	global_load_dword v64, v[24:25], off offset:256 nt
	global_load_dword v65, v[24:25], off offset:512 nt
	global_load_dword v66, v[24:25], off offset:768 nt
	global_load_dword v67, v[24:25], off offset:1024 nt
	global_load_dword v70, v[24:25], off offset:1280 nt
	global_load_dword v71, v[24:25], off offset:1536 nt
	global_load_dword v72, v[24:25], off offset:1792 nt
	global_load_dword v73, v[26:27], off nt
	global_load_dword v74, v[26:27], off offset:256 nt
	global_load_dword v75, v[26:27], off offset:512 nt
	global_load_dword v76, v[26:27], off offset:768 nt
	global_load_dword v77, v[26:27], off offset:1024 nt
	global_load_dword v78, v[26:27], off offset:1280 nt
	global_load_dword v79, v[26:27], off offset:1536 nt
	global_load_dword v80, v[26:27], off offset:1792 nt
	global_load_dword v81, v[28:29], off nt
	global_load_dword v82, v[28:29], off offset:256 nt
	global_load_dword v83, v[28:29], off offset:512 nt
	global_load_dword v84, v[28:29], off offset:768 nt
	global_load_dword v85, v[28:29], off offset:1024 nt
	global_load_dword v86, v[28:29], off offset:1280 nt
	global_load_dword v87, v[28:29], off offset:1536 nt
	global_load_dword v88, v[28:29], off offset:1792 nt
	global_load_dword v89, v[30:31], off nt
	global_load_dword v90, v[30:31], off offset:256 nt
	global_load_dword v91, v[30:31], off offset:512 nt
	global_load_dword v92, v[30:31], off offset:768 nt
	global_load_dword v93, v[30:31], off offset:1024 nt
	global_load_dword v94, v[30:31], off offset:1280 nt
	global_load_dword v95, v[30:31], off offset:1536 nt
	global_load_dword v96, v[30:31], off offset:1792 nt
	global_load_dword v97, v[32:33], off nt
	global_load_dword v98, v[32:33], off offset:256 nt
	global_load_dword v99, v[32:33], off offset:512 nt
	global_load_dword v100, v[32:33], off offset:768 nt
	global_load_dword v101, v[32:33], off offset:1024 nt
	global_load_dword v102, v[32:33], off offset:1280 nt
	global_load_dword v103, v[32:33], off offset:1536 nt
	global_load_dword v104, v[32:33], off offset:1792 nt
	global_load_dword v105, v[34:35], off nt
	global_load_dword v106, v[34:35], off offset:256 nt
	global_load_dword v107, v[34:35], off offset:512 nt
	global_load_dword v108, v[34:35], off offset:768 nt
	global_load_dword v109, v[34:35], off offset:1024 nt
	global_load_dword v110, v[34:35], off offset:1280 nt
	global_load_dword v111, v[34:35], off offset:1536 nt
	global_load_dword v112, v[34:35], off offset:1792 nt
	global_load_dword v113, v[36:37], off nt
	global_load_dword v114, v[36:37], off offset:256 nt
	global_load_dword v115, v[36:37], off offset:512 nt
	global_load_dword v116, v[36:37], off offset:768 nt
	global_load_dword v117, v[36:37], off offset:1024 nt
	global_load_dword v118, v[36:37], off offset:1280 nt
	global_load_dword v119, v[36:37], off offset:1536 nt
	global_load_dword v120, v[36:37], off offset:1792 nt
	global_load_dword v121, v[22:23], off nt
	global_load_dword v122, v[22:23], off offset:256 nt
	global_load_dword v123, v[22:23], off offset:512 nt
	global_load_dword v124, v[22:23], off offset:768 nt
	global_load_dword v125, v[22:23], off offset:1024 nt
	global_load_dword v126, v[22:23], off offset:1280 nt
	global_load_dword v127, v[22:23], off offset:1536 nt
	global_load_dword v128, v[22:23], off offset:1792 nt
	s_ashr_i32 s1, s0, 31
	s_add_i32 s24, s24, s60
	s_add_i32 s7, s7, s72
	s_lshl_b64 s[0:1], s[0:1], 15
	v_lshl_add_u64 v[22:23], v[6:7], 0, s[0:1]
	s_cmpk_gt_i32 s24, 0x9ff
	v_lshl_add_u64 v[24:25], v[8:9], 0, s[0:1]
	v_lshl_add_u64 v[26:27], v[10:11], 0, s[0:1]
	v_lshl_add_u64 v[28:29], v[12:13], 0, s[0:1]
	v_lshl_add_u64 v[30:31], v[14:15], 0, s[0:1]
	v_lshl_add_u64 v[32:33], v[16:17], 0, s[0:1]
	v_lshl_add_u64 v[34:35], v[18:19], 0, s[0:1]
	v_lshl_add_u64 v[36:37], v[20:21], 0, s[0:1]
	s_waitcnt vmcnt(62)
	ds_write2st64_b32 v48, v63, v64 offset1:1
	s_waitcnt vmcnt(60)
	ds_write2st64_b32 v48, v65, v66 offset0:2 offset1:3
	s_waitcnt vmcnt(58)
	ds_write2st64_b32 v48, v67, v70 offset0:4 offset1:5
	s_waitcnt vmcnt(56)
	ds_write2st64_b32 v48, v71, v72 offset0:6 offset1:7
	s_waitcnt vmcnt(54)
	ds_write2st64_b32 v39, v73, v74 offset0:8 offset1:9
	s_waitcnt vmcnt(52)
	ds_write2st64_b32 v39, v75, v76 offset0:10 offset1:11
	s_waitcnt vmcnt(50)
	ds_write2st64_b32 v39, v77, v78 offset0:12 offset1:13
	s_waitcnt vmcnt(48)
	ds_write2st64_b32 v39, v79, v80 offset0:14 offset1:15
	s_waitcnt vmcnt(46)
	ds_write2st64_b32 v50, v81, v82 offset0:16 offset1:17
	s_waitcnt vmcnt(44)
; template <bool GAIN = false>
; __device__ __forceinline__ void tr_super(const float* W, size_t ldw, int k0, int c0, bf16* WT, int nd0, int K, LAS unsigned char* lds, int wave, int lane, int kd0, const float* gk = nullptr) {
;     ...
;     for (int r = 0; r < 8; ++r)
; #pragma unroll
;         for (int h = 0; h < 8; ++h) tile[(8 * wave + r) * 513 + 64 * h + lane] = __builtin_nontemporal_load(W + (size_t)(k0 + 8 * wave + r) * ldw + c0 + 64 * h + lane);
;     __syncthreads();
	ds_write2st64_b32 v50, v83, v84 offset0:18 offset1:19
	s_waitcnt vmcnt(42)
	ds_write2st64_b32 v50, v85, v86 offset0:20 offset1:21
	s_waitcnt vmcnt(40)
	ds_write2st64_b32 v50, v87, v88 offset0:22 offset1:23
	s_waitcnt vmcnt(38)
	ds_write2st64_b32 v51, v89, v90 offset0:24 offset1:25
	s_waitcnt vmcnt(36)
	ds_write2st64_b32 v51, v91, v92 offset0:26 offset1:27
	s_waitcnt vmcnt(34)
	ds_write2st64_b32 v51, v93, v94 offset0:28 offset1:29
	s_waitcnt vmcnt(32)
	ds_write2st64_b32 v51, v95, v96 offset0:30 offset1:31
	s_waitcnt vmcnt(30)
	ds_write2st64_b32 v52, v97, v98 offset0:32 offset1:33
	s_waitcnt vmcnt(28)
	ds_write2st64_b32 v52, v99, v100 offset0:34 offset1:35
	s_waitcnt vmcnt(26)
	ds_write2st64_b32 v52, v101, v102 offset0:36 offset1:37
	s_waitcnt vmcnt(24)
	ds_write2st64_b32 v52, v103, v104 offset0:38 offset1:39
	s_waitcnt vmcnt(22)
	ds_write2st64_b32 v53, v105, v106 offset0:40 offset1:41
	s_waitcnt vmcnt(20)
	ds_write2st64_b32 v53, v107, v108 offset0:42 offset1:43
	s_waitcnt vmcnt(18)
	ds_write2st64_b32 v53, v109, v110 offset0:44 offset1:45
	s_waitcnt vmcnt(16)
	ds_write2st64_b32 v53, v111, v112 offset0:46 offset1:47
	s_waitcnt vmcnt(14)
	ds_write2st64_b32 v54, v113, v114 offset0:48 offset1:49
	s_waitcnt vmcnt(12)
	ds_write2st64_b32 v54, v115, v116 offset0:50 offset1:51
	s_waitcnt vmcnt(10)
	ds_write2st64_b32 v54, v117, v118 offset0:52 offset1:53
	s_waitcnt vmcnt(8)
	ds_write2st64_b32 v54, v119, v120 offset0:54 offset1:55
	s_waitcnt vmcnt(6)
	ds_write2st64_b32 v55, v121, v122 offset0:56 offset1:57
	s_waitcnt vmcnt(4)
	ds_write2st64_b32 v55, v123, v124 offset0:58 offset1:59
	s_waitcnt vmcnt(2)
	ds_write2st64_b32 v55, v125, v126 offset0:60 offset1:61
	s_waitcnt vmcnt(0)
	ds_write2st64_b32 v55, v127, v128 offset0:62 offset1:63
	s_waitcnt lgkmcnt(0)
	s_barrier
; #define LAS __attribute__((address_space(3)))
; __host__ __device__ __forceinline__ size_t blk(int r, int k, int K) { return (((size_t)((r >> 8) * (K >> 6) + (k >> 6))) << 14) + (size_t)(((r & 255) << 6) + (k & 63)); }
; __device__ __forceinline__ unsigned pk2(float lo, float hi) { f32x2 v = {lo, hi}; bf16x2_t b = __builtin_convertvector(v, bf16x2_t); return __builtin_bit_cast(unsigned, b); }
; template <bool GAIN = false>
; __device__ __forceinline__ void tr_super(const float* W, size_t ldw, int k0, int c0, bf16* WT, int nd0, int K, LAS unsigned char* lds, int wave, int lane, int kd0, const float* gk = nullptr) {
;     ...
;     const int c = lane & 7;
;     f32x4 g0 = {1.f, 1.f, 1.f, 1.f}, g1 = g0;
;     if (GAIN) { g0 = *(const f32x4*)(gk + k0 + 8 * c); g1 = *(const f32x4*)(gk + k0 + 8 * c + 4); }
; #pragma unroll
;     for (int j = 0; j < 8; ++j) { const int n = (lane >> 3) + 8 * j; const LAS float* t = tile + (8 * c) * 513 + 64 * wave + n;
;         u32x4 o; o.x = pk2(t[0 * 513] * g0.x, t[1 * 513] * g0.y); o.y = pk2(t[2 * 513] * g0.z, t[3 * 513] * g0.w); o.z = pk2(t[4 * 513] * g1.x, t[5 * 513] * g1.y); o.w = pk2(t[6 * 513] * g1.z, t[7 * 513] * g1.w);
;         *(u32x4*)(WT + blk(nd0 + 64 * wave + n, kd0 + 8 * c, K)) = o; }
;     __syncthreads();
	global_load_dwordx4 v[64:67], v[68:69], off offset:16
	s_nop 0
	global_load_dwordx4 v[68:71], v[68:69], off
	ds_read2_b32 v[72:73], v56 offset0:1 offset1:9
	ds_read2_b32 v[74:75], v49 offset1:8
	ds_read2_b32 v[76:77], v57 offset0:2 offset1:10
	ds_read2_b32 v[78:79], v58 offset0:3 offset1:11
	ds_read2_b32 v[80:81], v59 offset0:4 offset1:12
	ds_read2_b32 v[82:83], v60 offset0:5 offset1:13
	ds_read2_b32 v[84:85], v61 offset0:6 offset1:14
	ds_read2_b32 v[86:87], v62 offset0:7 offset1:15
	ds_read2_b32 v[88:89], v49 offset0:16 offset1:24
	ds_read2_b32 v[90:91], v56 offset0:17 offset1:25
	ds_read2_b32 v[92:93], v57 offset0:18 offset1:26
	ds_read2_b32 v[94:95], v58 offset0:19 offset1:27
	ds_read2_b32 v[96:97], v59 offset0:20 offset1:28
	ds_read2_b32 v[98:99], v60 offset0:21 offset1:29
	ds_read2_b32 v[100:101], v61 offset0:22 offset1:30
	ds_read2_b32 v[102:103], v62 offset0:23 offset1:31
	ds_read2_b32 v[104:105], v49 offset0:32 offset1:40
	ds_read2_b32 v[106:107], v56 offset0:33 offset1:41
	ds_read2_b32 v[108:109], v57 offset0:34 offset1:42
	ds_read2_b32 v[110:111], v58 offset0:35 offset1:43
	ds_read2_b32 v[112:113], v59 offset0:36 offset1:44
	ds_read2_b32 v[114:115], v60 offset0:37 offset1:45
	ds_read2_b32 v[116:117], v61 offset0:38 offset1:46
	ds_read2_b32 v[118:119], v62 offset0:39 offset1:47
	ds_read2_b32 v[120:121], v49 offset0:48 offset1:56
	ds_read2_b32 v[122:123], v56 offset0:49 offset1:57
	ds_read2_b32 v[124:125], v57 offset0:50 offset1:58
	ds_read2_b32 v[126:127], v58 offset0:51 offset1:59
	ds_read2_b32 v[128:129], v59 offset0:52 offset1:60
	ds_read2_b32 v[130:131], v60 offset0:53 offset1:61
	ds_read2_b32 v[132:133], v61 offset0:54 offset1:62
	ds_read2_b32 v[134:135], v62 offset0:55 offset1:63
	s_waitcnt lgkmcnt(14)
	v_mov_b32_e32 v136, v74
	v_mov_b32_e32 v137, v72
	v_mov_b32_e32 v138, v76
	v_mov_b32_e32 v139, v78
	v_mov_b32_e32 v140, v80
	v_mov_b32_e32 v141, v82
	v_mov_b32_e32 v142, v84
	v_mov_b32_e32 v143, v86
	v_mov_b32_e32 v72, v75
	v_mov_b32_e32 v78, v77
	v_mov_b32_e32 v82, v81
	v_mov_b32_e32 v86, v85
	v_mov_b32_e32 v74, v88
	v_mov_b32_e32 v75, v90
	v_mov_b32_e32 v76, v92
	v_mov_b32_e32 v77, v94
	v_mov_b32_e32 v80, v96
	v_mov_b32_e32 v81, v98
	v_mov_b32_e32 v84, v100
	v_mov_b32_e32 v85, v102
	v_mov_b32_e32 v90, v89
	v_mov_b32_e32 v94, v93
	v_mov_b32_e32 v98, v97
	v_mov_b32_e32 v102, v101
	v_mov_b32_e32 v88, v104
	v_mov_b32_e32 v89, v106
	s_waitcnt lgkmcnt(13)
	v_mov_b32_e32 v92, v108
	s_waitcnt lgkmcnt(12)
	v_mov_b32_e32 v93, v110
	s_waitcnt lgkmcnt(11)
	v_mov_b32_e32 v96, v112
	s_waitcnt lgkmcnt(10)
	v_mov_b32_e32 v97, v114
	s_waitcnt lgkmcnt(9)
	v_mov_b32_e32 v100, v116
	s_waitcnt lgkmcnt(8)
	v_mov_b32_e32 v101, v118
	v_mov_b32_e32 v106, v105
	v_mov_b32_e32 v110, v109
	v_mov_b32_e32 v114, v113
	v_mov_b32_e32 v118, v117
	s_waitcnt lgkmcnt(7)
	v_mov_b32_e32 v104, v120
	s_waitcnt lgkmcnt(6)
	v_mov_b32_e32 v105, v122
	s_waitcnt lgkmcnt(5)
	v_mov_b32_e32 v108, v124
	s_waitcnt lgkmcnt(4)
	v_mov_b32_e32 v109, v126
	s_waitcnt lgkmcnt(3)
	v_mov_b32_e32 v112, v128
	s_waitcnt lgkmcnt(2)
	v_mov_b32_e32 v113, v130
	s_waitcnt lgkmcnt(1)
	v_mov_b32_e32 v116, v132
	s_waitcnt lgkmcnt(0)
	v_mov_b32_e32 v117, v134
	v_mov_b32_e32 v122, v121
	v_mov_b32_e32 v126, v125
	v_mov_b32_e32 v130, v129
	v_mov_b32_e32 v134, v133
	s_waitcnt vmcnt(1)
	v_pk_mul_f32 v[128:129], v[64:65], v[140:141]
	s_waitcnt vmcnt(0)
	v_pk_mul_f32 v[120:121], v[68:69], v[136:137]
	v_pk_mul_f32 v[124:125], v[70:71], v[138:139]
	v_pk_mul_f32 v[132:133], v[66:67], v[142:143]
	v_pk_mul_f32 v[72:73], v[68:69], v[72:73]
	v_pk_mul_f32 v[78:79], v[70:71], v[78:79]
	v_pk_mul_f32 v[82:83], v[64:65], v[82:83]
	v_pk_mul_f32 v[86:87], v[66:67], v[86:87]
	v_pk_mul_f32 v[74:75], v[68:69], v[74:75]
	v_pk_mul_f32 v[76:77], v[70:71], v[76:77]
	v_pk_mul_f32 v[80:81], v[64:65], v[80:81]
	v_pk_mul_f32 v[84:85], v[66:67], v[84:85]
	v_pk_mul_f32 v[90:91], v[68:69], v[90:91]
	v_pk_mul_f32 v[94:95], v[70:71], v[94:95]
	v_pk_mul_f32 v[98:99], v[64:65], v[98:99]
	v_pk_mul_f32 v[102:103], v[66:67], v[102:103]
	v_pk_mul_f32 v[88:89], v[68:69], v[88:89]
	v_pk_mul_f32 v[92:93], v[70:71], v[92:93]
	v_pk_mul_f32 v[96:97], v[64:65], v[96:97]
	v_pk_mul_f32 v[100:101], v[66:67], v[100:101]
	v_pk_mul_f32 v[106:107], v[68:69], v[106:107]
	v_pk_mul_f32 v[110:111], v[70:71], v[110:111]
	v_pk_mul_f32 v[114:115], v[64:65], v[114:115]
	v_pk_mul_f32 v[118:119], v[66:67], v[118:119]
	v_pk_mul_f32 v[104:105], v[68:69], v[104:105]
	v_pk_mul_f32 v[108:109], v[70:71], v[108:109]
	v_pk_mul_f32 v[112:113], v[64:65], v[112:113]
	v_pk_mul_f32 v[116:117], v[66:67], v[116:117]
	v_pk_mul_f32 v[122:123], v[68:69], v[122:123]
	v_pk_mul_f32 v[126:127], v[70:71], v[126:127]
	v_pk_mul_f32 v[130:131], v[64:65], v[130:131]
	v_pk_mul_f32 v[134:135], v[66:67], v[134:135]
	v_cvt_pk_bf16_f32 v64, v120, v121
	v_cvt_pk_bf16_f32 v65, v124, v125
	v_cvt_pk_bf16_f32 v66, v128, v129
	v_cvt_pk_bf16_f32 v67, v132, v133
	v_cvt_pk_bf16_f32 v68, v72, v73
	v_cvt_pk_bf16_f32 v69, v78, v79
	v_cvt_pk_bf16_f32 v70, v82, v83
	v_cvt_pk_bf16_f32 v71, v86, v87
	v_cvt_pk_bf16_f32 v72, v74, v75
	v_cvt_pk_bf16_f32 v73, v76, v77
	v_cvt_pk_bf16_f32 v74, v80, v81
	v_cvt_pk_bf16_f32 v75, v84, v85
	v_cvt_pk_bf16_f32 v76, v90, v91
	v_cvt_pk_bf16_f32 v77, v94, v95
	v_cvt_pk_bf16_f32 v78, v98, v99
	v_cvt_pk_bf16_f32 v79, v102, v103
	v_cvt_pk_bf16_f32 v80, v88, v89
	v_cvt_pk_bf16_f32 v81, v92, v93
	v_cvt_pk_bf16_f32 v82, v96, v97
	v_cvt_pk_bf16_f32 v83, v100, v101
	v_cvt_pk_bf16_f32 v84, v106, v107
	v_cvt_pk_bf16_f32 v85, v110, v111
	v_cvt_pk_bf16_f32 v86, v114, v115
	v_cvt_pk_bf16_f32 v87, v118, v119
	v_cvt_pk_bf16_f32 v88, v104, v105
	v_cvt_pk_bf16_f32 v89, v108, v109
	v_cvt_pk_bf16_f32 v90, v112, v113
	v_cvt_pk_bf16_f32 v91, v116, v117
	v_cvt_pk_bf16_f32 v92, v122, v123
	v_cvt_pk_bf16_f32 v93, v126, v127
	v_cvt_pk_bf16_f32 v94, v130, v131
	v_cvt_pk_bf16_f32 v95, v134, v135
	global_store_dwordx4 v[22:23], v[64:67], off nt
	global_store_dwordx4 v[24:25], v[68:71], off nt
	global_store_dwordx4 v[26:27], v[72:75], off nt
	global_store_dwordx4 v[28:29], v[76:79], off nt
	global_store_dwordx4 v[30:31], v[80:83], off nt
	global_store_dwordx4 v[32:33], v[84:87], off nt
	global_store_dwordx4 v[34:35], v[88:91], off nt
	global_store_dwordx4 v[36:37], v[92:95], off nt
	s_barrier
	s_cbranch_scc0 .LBB0_25

; #define LAS __attribute__((address_space(3)))
; template <bool GAIN = false>
; __device__ __forceinline__ void tr_item(const float* W, size_t ldw, int k0, int c0, bf16* WT, int nd0, int K, LAS float* scr, int lane, const float* gk = nullptr, int kd0 = -1) {
;     if (kd0 < 0) kd0 = k0;
; #pragma unroll
;     for (int i = 0; i < 64; ++i) scr[i * 65 + lane] = __builtin_nontemporal_load(W + (size_t)(k0 + i) * ldw + c0 + lane);
; template <bool GAIN = false>
; __device__ __forceinline__ void tr_w13(const float* W, int which, bf16* WT, LAS float* scr, int item, int lane, const float* gk = nullptr) {
;     const int nblk = FF / 64, kb = item / nblk, nb = item % nblk, n0 = 64 * nb;
;     tr_item<GAIN>(W, FF, 64 * kb, n0, WT, (n0 >> 7) * 256 + which * 128 + (n0 & 127), D, scr, lane, gk);
.LBB0_29:
	s_cmpk_gt_i32 s50, 0x2aff
	s_mov_b64 s[12:13], -1
	s_cbranch_scc0 .LBB0_39
	s_cmpk_gt_u32 s50, 0x55ff
	s_cbranch_scc0 .LBB0_36
	s_cmpk_gt_u32 s50, 0x80ff
	s_cbranch_scc0 .LBB0_33
	s_add_i32 s0, s50, 0x7f00
	s_and_b32 s12, s0, 0xffff
	s_mul_i32 s12, s12, 0xbe83
	s_lshr_b32 s12, s12, 23
	s_mul_i32 s13, s12, 0xac
	s_sub_i32 s13, s0, s13
	s_and_b32 s14, s13, 0xffff
	s_lshl_b32 s0, s14, 8
	v_lshl_add_u64 v[2:3], v[10:11], 0, s[0:1]
	s_mul_i32 s0, s12, 0x2b0000
	v_lshl_add_u64 v[2:3], v[2:3], 0, s[0:1]
	s_mov_b32 s0, 0xa000
	v_add_co_u32_e32 v4, vcc, s0, v2
	s_mov_b32 s0, 0x15000
	s_nop 0
	v_addc_co_u32_e32 v5, vcc, 0, v3, vcc
	v_add_co_u32_e32 v6, vcc, s0, v2
	s_mov_b32 s0, 0x20000
	s_nop 0
	v_addc_co_u32_e32 v7, vcc, 0, v3, vcc
	v_add_co_u32_e32 v8, vcc, s0, v2
	s_mov_b32 s0, 0x2b000
	s_nop 0
	v_addc_co_u32_e32 v9, vcc, 0, v3, vcc
	v_add_co_u32_e32 v48, vcc, s0, v2
	s_mov_b32 s0, 0x35000
	s_nop 0
	v_addc_co_u32_e32 v49, vcc, 0, v3, vcc
	v_add_co_u32_e32 v50, vcc, s0, v2
	s_mov_b32 s0, 0x40000
	s_nop 0
	v_addc_co_u32_e32 v51, vcc, 0, v3, vcc
	v_add_co_u32_e32 v52, vcc, s0, v2
	s_mov_b32 s0, 0x4b000
	s_nop 0
	v_addc_co_u32_e32 v53, vcc, 0, v3, vcc
	v_add_co_u32_e32 v54, vcc, s0, v2
	s_mov_b32 s0, 0x56000
	s_nop 0
	v_addc_co_u32_e32 v55, vcc, 0, v3, vcc
	global_load_dword v39, v[2:3], off nt
	global_load_dword v47, v[4:5], off offset:3072 nt
	global_load_dword v58, v[6:7], off offset:2048 nt
	global_load_dword v59, v[8:9], off offset:1024 nt
	global_load_dword v60, v[48:49], off nt
	global_load_dword v61, v[50:51], off offset:3072 nt
	global_load_dword v62, v[52:53], off offset:2048 nt
	global_load_dword v63, v[54:55], off offset:1024 nt
	v_add_co_u32_e32 v4, vcc, s0, v2
	s_mov_b32 s0, 0x60000
	s_nop 0
	v_addc_co_u32_e32 v5, vcc, 0, v3, vcc
	v_add_co_u32_e32 v6, vcc, s0, v2
	s_mov_b32 s0, 0x6b000
	s_nop 0
	v_addc_co_u32_e32 v7, vcc, 0, v3, vcc
	v_add_co_u32_e32 v8, vcc, s0, v2
	s_mov_b32 s0, 0x76000
	s_nop 0
	v_addc_co_u32_e32 v9, vcc, 0, v3, vcc
	v_add_co_u32_e32 v48, vcc, s0, v2
	s_mov_b32 s0, 0x81000
	s_nop 0
	v_addc_co_u32_e32 v49, vcc, 0, v3, vcc
	v_add_co_u32_e32 v50, vcc, s0, v2
	s_lshl_b32 s0, s14, 6
	s_nop 0
	v_addc_co_u32_e32 v51, vcc, 0, v3, vcc
	v_add_co_u32_e32 v52, vcc, s57, v2
	s_and_b32 s0, s0, 64
	s_nop 0
	v_addc_co_u32_e32 v53, vcc, 0, v3, vcc
	v_add_co_u32_e32 v54, vcc, s61, v2
	s_lshl_b32 s13, s13, 5
	s_nop 0
	v_addc_co_u32_e32 v55, vcc, 0, v3, vcc
	v_add_co_u32_e32 v56, vcc, s73, v2
	s_bitset1_b32 s0, 7
	s_nop 0
	v_addc_co_u32_e32 v57, vcc, 0, v3, vcc
	global_load_dword v64, v[4:5], off nt
	global_load_dword v65, v[6:7], off offset:3072 nt
	global_load_dword v66, v[8:9], off offset:2048 nt
	global_load_dword v67, v[48:49], off offset:1024 nt
	global_load_dword v68, v[50:51], off nt
	global_load_dword v69, v[52:53], off offset:3072 nt
	global_load_dword v70, v[54:55], off offset:2048 nt
	global_load_dword v71, v[56:57], off offset:1024 nt
	v_add_co_u32_e32 v4, vcc, s74, v2
	s_and_b32 s13, s13, 0x1fc0
	s_nop 0
	v_addc_co_u32_e32 v5, vcc, 0, v3, vcc
	v_add_co_u32_e32 v6, vcc, s75, v2
	s_add_i32 s13, s13, s12
	s_nop 0
	v_addc_co_u32_e32 v7, vcc, 0, v3, vcc
	v_add_co_u32_e32 v8, vcc, s76, v2
	s_lshl_b32 s12, s13, 14
	s_nop 0
	v_addc_co_u32_e32 v9, vcc, 0, v3, vcc
	v_add_co_u32_e32 v48, vcc, s77, v2
	s_nop 1
	v_addc_co_u32_e32 v49, vcc, 0, v3, vcc
	v_add_co_u32_e32 v50, vcc, s78, v2
	s_nop 1
	v_addc_co_u32_e32 v51, vcc, 0, v3, vcc
	v_add_co_u32_e32 v52, vcc, s79, v2
	s_nop 1
	v_addc_co_u32_e32 v53, vcc, 0, v3, vcc
	v_add_co_u32_e32 v54, vcc, s80, v2
	s_nop 1
	v_addc_co_u32_e32 v55, vcc, 0, v3, vcc
	v_add_co_u32_e32 v56, vcc, s81, v2
	s_nop 1
	v_addc_co_u32_e32 v57, vcc, 0, v3, vcc
	global_load_dword v72, v[4:5], off nt
	global_load_dword v73, v[6:7], off offset:3072 nt
	global_load_dword v74, v[8:9], off offset:2048 nt
	global_load_dword v75, v[48:49], off offset:1024 nt
	global_load_dword v76, v[50:51], off nt
	global_load_dword v77, v[52:53], off offset:3072 nt
	global_load_dword v78, v[54:55], off offset:2048 nt
	global_load_dword v79, v[56:57], off offset:1024 nt
	v_add_co_u32_e32 v4, vcc, s82, v2
	s_nop 1
	v_addc_co_u32_e32 v5, vcc, 0, v3, vcc
	v_add_co_u32_e32 v6, vcc, s83, v2
	s_nop 1
	v_addc_co_u32_e32 v7, vcc, 0, v3, vcc
	v_add_co_u32_e32 v8, vcc, s84, v2
	s_nop 1
	v_addc_co_u32_e32 v9, vcc, 0, v3, vcc
	v_add_co_u32_e32 v48, vcc, s85, v2
	s_nop 1
	v_addc_co_u32_e32 v49, vcc, 0, v3, vcc
	v_add_co_u32_e32 v50, vcc, s86, v2
	s_nop 1
	v_addc_co_u32_e32 v51, vcc, 0, v3, vcc
	v_add_co_u32_e32 v52, vcc, s87, v2
	s_nop 1
	v_addc_co_u32_e32 v53, vcc, 0, v3, vcc
	v_add_co_u32_e32 v54, vcc, s88, v2
	s_nop 1
	v_addc_co_u32_e32 v55, vcc, 0, v3, vcc
	v_add_co_u32_e32 v56, vcc, s89, v2
	s_nop 1
	v_addc_co_u32_e32 v57, vcc, 0, v3, vcc
	global_load_dword v80, v[4:5], off nt
	global_load_dword v81, v[6:7], off offset:3072 nt
	global_load_dword v82, v[8:9], off offset:2048 nt
	global_load_dword v83, v[48:49], off offset:1024 nt
	global_load_dword v84, v[50:51], off nt
	global_load_dword v85, v[52:53], off offset:3072 nt
	global_load_dword v86, v[54:55], off offset:2048 nt
	global_load_dword v87, v[56:57], off offset:1024 nt
	v_add_co_u32_e32 v4, vcc, s90, v2
	s_nop 1
	v_addc_co_u32_e32 v5, vcc, 0, v3, vcc
	v_add_co_u32_e32 v6, vcc, s91, v2
	s_nop 1
	v_addc_co_u32_e32 v7, vcc, 0, v3, vcc
	v_add_co_u32_e32 v8, vcc, s92, v2
	s_nop 1
	v_addc_co_u32_e32 v9, vcc, 0, v3, vcc
	v_add_co_u32_e32 v48, vcc, s93, v2
	s_nop 1
	v_addc_co_u32_e32 v49, vcc, 0, v3, vcc
	v_add_co_u32_e32 v50, vcc, s97, v2
	s_nop 1
	v_addc_co_u32_e32 v51, vcc, 0, v3, vcc
	v_add_co_u32_e32 v52, vcc, s62, v2
	s_nop 1
	v_addc_co_u32_e32 v53, vcc, 0, v3, vcc
; template <bool GAIN = false>
; __device__ __forceinline__ void tr_item(const float* W, size_t ldw, int k0, int c0, bf16* WT, int nd0, int K, LAS float* scr, int lane, const float* gk = nullptr, int kd0 = -1) {
;     ...
;     for (int i = 0; i < 64; ++i) scr[i * 65 + lane] = __builtin_nontemporal_load(W + (size_t)(k0 + i) * ldw + c0 + lane);
;     asm volatile("s_waitcnt lgkmcnt(0)" ::: "memory");
	v_add_co_u32_e32 v54, vcc, s63, v2
	s_nop 1
	v_addc_co_u32_e32 v55, vcc, 0, v3, vcc
	v_add_co_u32_e32 v56, vcc, s95, v2
	s_nop 1
	v_addc_co_u32_e32 v57, vcc, 0, v3, vcc
	global_load_dword v88, v[4:5], off nt
	global_load_dword v89, v[6:7], off offset:3072 nt
	global_load_dword v90, v[8:9], off offset:2048 nt
	global_load_dword v91, v[48:49], off offset:1024 nt
	global_load_dword v92, v[50:51], off nt
	global_load_dword v93, v[52:53], off offset:3072 nt
	global_load_dword v94, v[54:55], off offset:2048 nt
	global_load_dword v95, v[56:57], off offset:1024 nt
	v_add_co_u32_e32 v4, vcc, s58, v2
	s_nop 1
	v_addc_co_u32_e32 v5, vcc, 0, v3, vcc
	v_add_co_u32_e32 v6, vcc, s59, v2
	s_nop 1
	v_addc_co_u32_e32 v7, vcc, 0, v3, vcc
	v_add_co_u32_e32 v8, vcc, s3, v2
	s_nop 1
	v_addc_co_u32_e32 v9, vcc, 0, v3, vcc
	v_add_co_u32_e32 v48, vcc, s51, v2
	s_nop 1
	v_addc_co_u32_e32 v49, vcc, 0, v3, vcc
	v_add_co_u32_e32 v50, vcc, s26, v2
	s_nop 1
	v_addc_co_u32_e32 v51, vcc, 0, v3, vcc
	v_add_co_u32_e32 v52, vcc, s33, v2
	s_nop 1
	v_addc_co_u32_e32 v53, vcc, 0, v3, vcc
	v_add_co_u32_e32 v54, vcc, s6, v2
	s_nop 1
	v_addc_co_u32_e32 v55, vcc, 0, v3, vcc
	v_add_co_u32_e32 v56, vcc, s7, v2
	s_nop 1
	v_addc_co_u32_e32 v57, vcc, 0, v3, vcc
	global_load_dword v96, v[4:5], off nt
	global_load_dword v97, v[6:7], off offset:3072 nt
	global_load_dword v98, v[8:9], off offset:2048 nt
	global_load_dword v99, v[48:49], off offset:1024 nt
	global_load_dword v100, v[50:51], off nt
	global_load_dword v101, v[52:53], off offset:3072 nt
	global_load_dword v102, v[54:55], off offset:2048 nt
	global_load_dword v103, v[56:57], off offset:1024 nt
	v_add_co_u32_e32 v4, vcc, s64, v2
	s_nop 1
	v_addc_co_u32_e32 v5, vcc, 0, v3, vcc
	v_add_co_u32_e32 v6, vcc, s65, v2
	s_nop 1
	v_addc_co_u32_e32 v7, vcc, 0, v3, vcc
	v_add_co_u32_e32 v8, vcc, s68, v2
	s_nop 1
	v_addc_co_u32_e32 v9, vcc, 0, v3, vcc
	v_add_co_u32_e32 v48, vcc, s69, v2
	s_nop 1
	v_addc_co_u32_e32 v49, vcc, 0, v3, vcc
	v_add_co_u32_e32 v50, vcc, s96, v2
	s_nop 1
	v_addc_co_u32_e32 v51, vcc, 0, v3, vcc
	v_add_co_u32_e32 v52, vcc, s56, v2
	s_nop 1
	v_addc_co_u32_e32 v53, vcc, 0, v3, vcc
	v_add_co_u32_e32 v54, vcc, s31, v2
	s_nop 1
	v_addc_co_u32_e32 v55, vcc, 0, v3, vcc
	v_add_co_u32_e32 v56, vcc, s35, v2
	s_nop 1
	v_addc_co_u32_e32 v57, vcc, 0, v3, vcc
	global_load_dword v104, v[4:5], off nt
	global_load_dword v105, v[6:7], off offset:3072 nt
	global_load_dword v106, v[8:9], off offset:2048 nt
	global_load_dword v107, v[48:49], off offset:1024 nt
	global_load_dword v108, v[50:51], off nt
	global_load_dword v109, v[52:53], off offset:3072 nt
	global_load_dword v110, v[54:55], off offset:2048 nt
	s_nop 0
	global_load_dword v56, v[56:57], off offset:1024 nt
	v_add_co_u32_e32 v4, vcc, s42, v2
	s_nop 1
	v_addc_co_u32_e32 v5, vcc, 0, v3, vcc
	v_add_co_u32_e32 v6, vcc, s43, v2
	s_nop 1
	v_addc_co_u32_e32 v7, vcc, 0, v3, vcc
	v_add_co_u32_e32 v8, vcc, s44, v2
	s_nop 1
	v_addc_co_u32_e32 v9, vcc, 0, v3, vcc
	v_add_co_u32_e32 v48, vcc, s45, v2
	s_nop 1
	v_addc_co_u32_e32 v49, vcc, 0, v3, vcc
	v_add_co_u32_e32 v50, vcc, s46, v2
	s_nop 1
	v_addc_co_u32_e32 v51, vcc, 0, v3, vcc
	v_add_co_u32_e32 v52, vcc, s47, v2
	s_nop 1
	v_addc_co_u32_e32 v53, vcc, 0, v3, vcc
	v_add_co_u32_e32 v54, vcc, s48, v2
	s_nop 1
	v_addc_co_u32_e32 v55, vcc, 0, v3, vcc
	v_add_co_u32_e32 v2, vcc, s49, v2
	s_nop 1
	v_addc_co_u32_e32 v3, vcc, 0, v3, vcc
	global_load_dword v4, v[4:5], off nt
	s_nop 0
	global_load_dword v5, v[6:7], off offset:3072 nt
	s_nop 0
	global_load_dword v6, v[8:9], off offset:2048 nt
	global_load_dword v7, v[48:49], off offset:1024 nt
	s_nop 0
	global_load_dword v8, v[50:51], off nt
	global_load_dword v9, v[52:53], off offset:3072 nt
	global_load_dword v48, v[54:55], off offset:2048 nt
	s_nop 0
	global_load_dword v2, v[2:3], off offset:1024 nt
	s_waitcnt vmcnt(62)
	ds_write2_b32 v20, v39, v47 offset1:65
	s_waitcnt vmcnt(60)
	ds_write2_b32 v20, v58, v59 offset0:130 offset1:195
	s_waitcnt vmcnt(58)
	ds_write2_b32 v22, v60, v61 offset0:4 offset1:69
	s_waitcnt vmcnt(56)
	ds_write2_b32 v22, v62, v63 offset0:134 offset1:199
	s_waitcnt vmcnt(54)
	ds_write2_b32 v23, v64, v65 offset0:8 offset1:73
	s_waitcnt vmcnt(52)
	ds_write2_b32 v23, v66, v67 offset0:138 offset1:203
	s_waitcnt vmcnt(50)
	ds_write2_b32 v24, v68, v69 offset0:12 offset1:77
	s_waitcnt vmcnt(48)
	ds_write2_b32 v24, v70, v71 offset0:142 offset1:207
	s_waitcnt vmcnt(46)
	ds_write2_b32 v25, v72, v73 offset0:16 offset1:81
	s_waitcnt vmcnt(44)
	ds_write2_b32 v25, v74, v75 offset0:146 offset1:211
	s_waitcnt vmcnt(42)
	ds_write2_b32 v26, v76, v77 offset0:20 offset1:85
	s_waitcnt vmcnt(40)
	ds_write2_b32 v26, v78, v79 offset0:150 offset1:215
	s_waitcnt vmcnt(38)
	ds_write2_b32 v27, v80, v81 offset0:24 offset1:89
	s_waitcnt vmcnt(36)
	ds_write2_b32 v27, v82, v83 offset0:154 offset1:219
	s_waitcnt vmcnt(34)
	ds_write2_b32 v28, v84, v85 offset0:28 offset1:93
	s_waitcnt vmcnt(32)
	ds_write2_b32 v28, v86, v87 offset0:158 offset1:223
	s_waitcnt vmcnt(30)
	ds_write2_b32 v29, v88, v89 offset0:32 offset1:97
	s_waitcnt vmcnt(28)
	ds_write2_b32 v29, v90, v91 offset0:162 offset1:227
	s_waitcnt vmcnt(26)
	ds_write2_b32 v30, v92, v93 offset0:36 offset1:101
	s_waitcnt vmcnt(24)
	ds_write2_b32 v30, v94, v95 offset0:166 offset1:231
	s_waitcnt vmcnt(22)
	ds_write2_b32 v31, v96, v97 offset0:40 offset1:105
	s_waitcnt vmcnt(20)
	ds_write2_b32 v31, v98, v99 offset0:170 offset1:235
	s_waitcnt vmcnt(18)
	ds_write2_b32 v32, v100, v101 offset0:44 offset1:109
	s_waitcnt vmcnt(16)
	ds_write2_b32 v32, v102, v103 offset0:174 offset1:239
	s_waitcnt vmcnt(14)
	ds_write2_b32 v33, v104, v105 offset0:48 offset1:113
	s_waitcnt vmcnt(12)
; #define LAS __attribute__((address_space(3)))
; __host__ __device__ __forceinline__ size_t blk(int r, int k, int K) { return (((size_t)((r >> 8) * (K >> 6) + (k >> 6))) << 14) + (size_t)(((r & 255) << 6) + (k & 63)); }
; __device__ __forceinline__ unsigned pk2(float lo, float hi) { f32x2 v = {lo, hi}; bf16x2_t b = __builtin_convertvector(v, bf16x2_t); return __builtin_bit_cast(unsigned, b); }
; template <bool GAIN = false>
; __device__ __forceinline__ void tr_item(const float* W, size_t ldw, int k0, int c0, bf16* WT, int nd0, int K, LAS float* scr, int lane, const float* gk = nullptr, int kd0 = -1) {
;     ...
;     for (int i = 0; i < 64; ++i) scr[i * 65 + lane] = __builtin_nontemporal_load(W + (size_t)(k0 + i) * ldw + c0 + lane);
;     asm volatile("s_waitcnt lgkmcnt(0)" ::: "memory");
;     const int c = lane & 7;
;     f32x4 g0 = {1.f, 1.f, 1.f, 1.f}, g1 = g0;
;     if (GAIN) { g0 = *(const f32x4*)(gk + k0 + 8 * c); g1 = *(const f32x4*)(gk + k0 + 8 * c + 4); }
; #pragma unroll
;     for (int j = 0; j < 8; ++j) { const int n = (lane >> 3) + 8 * j; const LAS float* s = scr + (8 * c) * 65 + n;
;         u32x4 o; o.x = pk2(s[0 * 65] * g0.x, s[1 * 65] * g0.y); o.y = pk2(s[2 * 65] * g0.z, s[3 * 65] * g0.w); o.z = pk2(s[4 * 65] * g1.x, s[5 * 65] * g1.y); o.w = pk2(s[6 * 65] * g1.z, s[7 * 65] * g1.w);
;         *(u32x4*)(WT + blk(nd0 + n, kd0 + 8 * c, K)) = o; }
;     asm volatile("s_waitcnt lgkmcnt(0)" ::: "memory");
	ds_write2_b32 v33, v106, v107 offset0:178 offset1:243
	s_waitcnt vmcnt(10)
	ds_write2_b32 v34, v108, v109 offset0:52 offset1:117
	s_waitcnt vmcnt(8)
	ds_write2_b32 v34, v110, v56 offset0:182 offset1:247
	s_waitcnt vmcnt(6)
	ds_write2_b32 v35, v4, v5 offset0:56 offset1:121
	s_waitcnt vmcnt(4)
	ds_write2_b32 v35, v6, v7 offset0:186 offset1:251
	s_waitcnt vmcnt(2)
	ds_write2_b32 v36, v8, v9 offset0:60 offset1:125
	s_waitcnt vmcnt(0)
	ds_write2_b32 v36, v48, v2 offset0:190 offset1:255
	s_waitcnt lgkmcnt(0)
	ds_read2_b32 v[6:7], v21 offset0:65 offset1:73
	ds_read2_b32 v[8:9], v21 offset1:8
	ds_read2_b32 v[48:49], v21 offset0:130 offset1:138
	ds_read2_b32 v[50:51], v21 offset0:195 offset1:203
	ds_read2_b32 v[52:53], v37 offset0:4 offset1:12
	ds_read2_b32 v[54:55], v37 offset0:69 offset1:77
	ds_read2_b32 v[56:57], v37 offset0:134 offset1:142
	ds_read2_b32 v[58:59], v37 offset0:199 offset1:207
	s_waitcnt lgkmcnt(6)
	v_cvt_pk_bf16_f32 v2, v8, v6
	v_or_b32_e32 v6, s0, v193
	v_lshlrev_b32_e32 v6, 6, v6
	v_or3_b32 v6, v6, s12, v1
	s_waitcnt lgkmcnt(4)
	v_cvt_pk_bf16_f32 v3, v48, v50
	s_waitcnt lgkmcnt(2)
	v_cvt_pk_bf16_f32 v4, v52, v54
	s_waitcnt lgkmcnt(0)
	v_cvt_pk_bf16_f32 v5, v56, v58
	v_lshlrev_b32_e32 v6, 1, v6
	global_store_dwordx4 v6, v[2:5], s[4:5] nt
	v_or_b32_e32 v6, s0, v40
	v_lshlrev_b32_e32 v6, 6, v6
	v_or3_b32 v6, v6, s12, v1
	v_cvt_pk_bf16_f32 v2, v9, v7
	v_cvt_pk_bf16_f32 v3, v49, v51
	v_cvt_pk_bf16_f32 v4, v53, v55
	v_cvt_pk_bf16_f32 v5, v57, v59
	v_lshlrev_b32_e32 v39, 1, v6
	ds_read2_b32 v[6:7], v21 offset0:16 offset1:24
	ds_read2_b32 v[8:9], v21 offset0:81 offset1:89
	ds_read2_b32 v[48:49], v21 offset0:146 offset1:154
	ds_read2_b32 v[50:51], v21 offset0:211 offset1:219
	ds_read2_b32 v[52:53], v37 offset0:20 offset1:28
	ds_read2_b32 v[54:55], v37 offset0:85 offset1:93
	ds_read2_b32 v[56:57], v37 offset0:150 offset1:158
	ds_read2_b32 v[58:59], v37 offset0:215 offset1:223
	global_store_dwordx4 v39, v[2:5], s[4:5] nt
	s_waitcnt lgkmcnt(6)
	s_nop 0
	v_cvt_pk_bf16_f32 v2, v6, v8
	v_or_b32_e32 v6, s0, v41
	v_lshlrev_b32_e32 v6, 6, v6
	v_or3_b32 v6, v6, s12, v1
	s_waitcnt lgkmcnt(4)
	v_cvt_pk_bf16_f32 v3, v48, v50
	s_waitcnt lgkmcnt(2)
	v_cvt_pk_bf16_f32 v4, v52, v54
	s_waitcnt lgkmcnt(0)
	v_cvt_pk_bf16_f32 v5, v56, v58
	v_lshlrev_b32_e32 v6, 1, v6
	global_store_dwordx4 v6, v[2:5], s[4:5] nt
	v_or_b32_e32 v6, s0, v42
	v_lshlrev_b32_e32 v6, 6, v6
	v_or3_b32 v6, v6, s12, v1
	v_cvt_pk_bf16_f32 v2, v7, v9
	v_cvt_pk_bf16_f32 v3, v49, v51
	v_cvt_pk_bf16_f32 v4, v53, v55
	v_cvt_pk_bf16_f32 v5, v57, v59
	v_lshlrev_b32_e32 v39, 1, v6
	ds_read2_b32 v[6:7], v21 offset0:32 offset1:40
	ds_read2_b32 v[8:9], v21 offset0:97 offset1:105
	ds_read2_b32 v[48:49], v21 offset0:162 offset1:170
	ds_read2_b32 v[50:51], v21 offset0:227 offset1:235
	ds_read2_b32 v[52:53], v37 offset0:36 offset1:44
	ds_read2_b32 v[54:55], v37 offset0:101 offset1:109
	ds_read2_b32 v[56:57], v37 offset0:166 offset1:174
	ds_read2_b32 v[58:59], v37 offset0:231 offset1:239
	global_store_dwordx4 v39, v[2:5], s[4:5] nt
	s_waitcnt lgkmcnt(6)
	s_nop 0
	v_cvt_pk_bf16_f32 v2, v6, v8
	v_or_b32_e32 v6, s0, v43
	v_lshlrev_b32_e32 v6, 6, v6
	v_or3_b32 v6, v6, s12, v1
	s_waitcnt lgkmcnt(4)
	v_cvt_pk_bf16_f32 v3, v48, v50
	s_waitcnt lgkmcnt(2)
	v_cvt_pk_bf16_f32 v4, v52, v54
	s_waitcnt lgkmcnt(0)
	v_cvt_pk_bf16_f32 v5, v56, v58
	v_lshlrev_b32_e32 v6, 1, v6
	global_store_dwordx4 v6, v[2:5], s[4:5] nt
	v_or_b32_e32 v6, s0, v44
	v_lshlrev_b32_e32 v6, 6, v6
	v_or3_b32 v6, v6, s12, v1
	v_cvt_pk_bf16_f32 v2, v7, v9
	v_cvt_pk_bf16_f32 v3, v49, v51
	v_cvt_pk_bf16_f32 v4, v53, v55
	v_cvt_pk_bf16_f32 v5, v57, v59
	v_lshlrev_b32_e32 v39, 1, v6
	ds_read2_b32 v[6:7], v21 offset0:48 offset1:56
	ds_read2_b32 v[8:9], v21 offset0:113 offset1:121
	ds_read2_b32 v[48:49], v21 offset0:178 offset1:186
	ds_read2_b32 v[50:51], v21 offset0:243 offset1:251
	ds_read2_b32 v[52:53], v37 offset0:52 offset1:60
	ds_read2_b32 v[54:55], v37 offset0:117 offset1:125
	ds_read2_b32 v[56:57], v37 offset0:182 offset1:190
	ds_read2_b32 v[58:59], v37 offset0:247 offset1:255
	global_store_dwordx4 v39, v[2:5], s[4:5] nt
	s_waitcnt lgkmcnt(6)
	s_nop 0
	v_cvt_pk_bf16_f32 v2, v6, v8
	v_or_b32_e32 v6, s0, v45
	v_lshlrev_b32_e32 v6, 6, v6
	v_or3_b32 v6, v6, s12, v1
	s_waitcnt lgkmcnt(4)
	v_cvt_pk_bf16_f32 v3, v48, v50
	s_waitcnt lgkmcnt(2)
	v_cvt_pk_bf16_f32 v4, v52, v54
	s_waitcnt lgkmcnt(0)
	v_cvt_pk_bf16_f32 v5, v56, v58
	v_lshlrev_b32_e32 v6, 1, v6
	global_store_dwordx4 v6, v[2:5], s[4:5] nt
	v_or_b32_e32 v6, s0, v46
	v_lshlrev_b32_e32 v6, 6, v6
	v_or3_b32 v6, v6, s12, v1
	v_cvt_pk_bf16_f32 v2, v7, v9
	v_cvt_pk_bf16_f32 v3, v49, v51
	v_cvt_pk_bf16_f32 v4, v53, v55
	v_cvt_pk_bf16_f32 v5, v57, v59
	v_lshlrev_b32_e32 v6, 1, v6
	global_store_dwordx4 v6, v[2:5], s[4:5] nt
	s_waitcnt lgkmcnt(0)
	s_mov_b64 s[12:13], 0
; #define LAS __attribute__((address_space(3)))
; template <bool GAIN = false>
; __device__ __forceinline__ void tr_item(const float* W, size_t ldw, int k0, int c0, bf16* WT, int nd0, int K, LAS float* scr, int lane, const float* gk = nullptr, int kd0 = -1) {
;     if (kd0 < 0) kd0 = k0;
; #pragma unroll
;     for (int i = 0; i < 64; ++i) scr[i * 65 + lane] = __builtin_nontemporal_load(W + (size_t)(k0 + i) * ldw + c0 + lane);
; template <bool GAIN = false>
; __device__ __forceinline__ void tr_w13(const float* W, int which, bf16* WT, LAS float* scr, int item, int lane, const float* gk = nullptr) {
;     const int nblk = FF / 64, kb = item / nblk, nb = item % nblk, n0 = 64 * nb;
;     tr_item<GAIN>(W, FF, 64 * kb, n0, WT, (n0 >> 7) * 256 + which * 128 + (n0 & 127), D, scr, lane, gk);
.LBB0_33:
	s_andn2_b64 vcc, exec, s[12:13]
	s_cbranch_vccnz .LBB0_35
	s_add_i32 s0, s50, 0xaa00
	s_and_b32 s12, s0, 0xffff
	s_mul_i32 s12, s12, 0xbe83
	s_lshr_b32 s12, s12, 23
	s_mul_i32 s13, s12, 0xac
	s_sub_i32 s13, s0, s13
	s_and_b32 s14, s13, 0xffff
	s_lshl_b32 s0, s14, 8
	v_lshl_add_u64 v[2:3], v[12:13], 0, s[0:1]
	s_mul_i32 s0, s12, 0x2b0000
	v_lshl_add_u64 v[2:3], v[2:3], 0, s[0:1]
	s_mov_b32 s0, 0xa000
	v_add_co_u32_e32 v4, vcc, s0, v2
	s_mov_b32 s0, 0x15000
	s_nop 0
	v_addc_co_u32_e32 v5, vcc, 0, v3, vcc
	v_add_co_u32_e32 v6, vcc, s0, v2
	s_mov_b32 s0, 0x20000
	s_nop 0
	v_addc_co_u32_e32 v7, vcc, 0, v3, vcc
	v_add_co_u32_e32 v8, vcc, s0, v2
	s_mov_b32 s0, 0x2b000
	s_nop 0
	v_addc_co_u32_e32 v9, vcc, 0, v3, vcc
	v_add_co_u32_e32 v48, vcc, s0, v2
	s_mov_b32 s0, 0x35000
	s_nop 0
	v_addc_co_u32_e32 v49, vcc, 0, v3, vcc
	v_add_co_u32_e32 v50, vcc, s0, v2
	s_mov_b32 s0, 0x40000
	s_nop 0
	v_addc_co_u32_e32 v51, vcc, 0, v3, vcc
	v_add_co_u32_e32 v52, vcc, s0, v2
	s_mov_b32 s0, 0x4b000
	s_nop 0
	v_addc_co_u32_e32 v53, vcc, 0, v3, vcc
	v_add_co_u32_e32 v54, vcc, s0, v2
	s_mov_b32 s0, 0x56000
	s_nop 0
	v_addc_co_u32_e32 v55, vcc, 0, v3, vcc
	global_load_dword v39, v[2:3], off nt
	global_load_dword v47, v[4:5], off offset:3072 nt
	global_load_dword v58, v[6:7], off offset:2048 nt
	global_load_dword v59, v[8:9], off offset:1024 nt
	global_load_dword v60, v[48:49], off nt
	global_load_dword v61, v[50:51], off offset:3072 nt
	global_load_dword v62, v[52:53], off offset:2048 nt
	global_load_dword v63, v[54:55], off offset:1024 nt
	v_add_co_u32_e32 v4, vcc, s0, v2
	s_mov_b32 s0, 0x60000
	s_nop 0
	v_addc_co_u32_e32 v5, vcc, 0, v3, vcc
	v_add_co_u32_e32 v6, vcc, s0, v2
	s_mov_b32 s0, 0x6b000
	s_nop 0
	v_addc_co_u32_e32 v7, vcc, 0, v3, vcc
	v_add_co_u32_e32 v8, vcc, s0, v2
	s_mov_b32 s0, 0x76000
	s_nop 0
	v_addc_co_u32_e32 v9, vcc, 0, v3, vcc
	v_add_co_u32_e32 v48, vcc, s0, v2
	s_mov_b32 s0, 0x81000
	s_nop 0
	v_addc_co_u32_e32 v49, vcc, 0, v3, vcc
	v_add_co_u32_e32 v50, vcc, s0, v2
	s_lshl_b32 s0, s14, 6
	s_nop 0
	v_addc_co_u32_e32 v51, vcc, 0, v3, vcc
	v_add_co_u32_e32 v52, vcc, s57, v2
	s_lshl_b32 s13, s13, 5
	s_nop 0
	v_addc_co_u32_e32 v53, vcc, 0, v3, vcc
	v_add_co_u32_e32 v54, vcc, s61, v2
	s_and_b32 s0, s0, 64
	s_nop 0
	v_addc_co_u32_e32 v55, vcc, 0, v3, vcc
	v_add_co_u32_e32 v56, vcc, s73, v2
	s_and_b32 s13, s13, 0x1fc0
	s_nop 0
	v_addc_co_u32_e32 v57, vcc, 0, v3, vcc
	global_load_dword v64, v[4:5], off nt
	global_load_dword v65, v[6:7], off offset:3072 nt
	global_load_dword v66, v[8:9], off offset:2048 nt
	global_load_dword v67, v[48:49], off offset:1024 nt
	global_load_dword v68, v[50:51], off nt
	global_load_dword v69, v[52:53], off offset:3072 nt
	global_load_dword v70, v[54:55], off offset:2048 nt
	global_load_dword v71, v[56:57], off offset:1024 nt
	v_add_co_u32_e32 v4, vcc, s74, v2
	s_add_i32 s13, s13, s12
	s_nop 0
	v_addc_co_u32_e32 v5, vcc, 0, v3, vcc
	v_add_co_u32_e32 v6, vcc, s75, v2
	s_lshl_b32 s12, s13, 14
	s_nop 0
	v_addc_co_u32_e32 v7, vcc, 0, v3, vcc
	v_add_co_u32_e32 v8, vcc, s76, v2
	s_nop 1
	v_addc_co_u32_e32 v9, vcc, 0, v3, vcc
	v_add_co_u32_e32 v48, vcc, s77, v2
	s_nop 1
	v_addc_co_u32_e32 v49, vcc, 0, v3, vcc
	v_add_co_u32_e32 v50, vcc, s78, v2
	s_nop 1
	v_addc_co_u32_e32 v51, vcc, 0, v3, vcc
	v_add_co_u32_e32 v52, vcc, s79, v2
	s_nop 1
	v_addc_co_u32_e32 v53, vcc, 0, v3, vcc
	v_add_co_u32_e32 v54, vcc, s80, v2
	s_nop 1
	v_addc_co_u32_e32 v55, vcc, 0, v3, vcc
	v_add_co_u32_e32 v56, vcc, s81, v2
	s_nop 1
	v_addc_co_u32_e32 v57, vcc, 0, v3, vcc
	global_load_dword v72, v[4:5], off nt
	global_load_dword v73, v[6:7], off offset:3072 nt
	global_load_dword v74, v[8:9], off offset:2048 nt
	global_load_dword v75, v[48:49], off offset:1024 nt
	global_load_dword v76, v[50:51], off nt
	global_load_dword v77, v[52:53], off offset:3072 nt
	global_load_dword v78, v[54:55], off offset:2048 nt
	global_load_dword v79, v[56:57], off offset:1024 nt
	v_add_co_u32_e32 v4, vcc, s82, v2
	s_nop 1
	v_addc_co_u32_e32 v5, vcc, 0, v3, vcc
	v_add_co_u32_e32 v6, vcc, s83, v2
	s_nop 1
	v_addc_co_u32_e32 v7, vcc, 0, v3, vcc
	v_add_co_u32_e32 v8, vcc, s84, v2
	s_nop 1
	v_addc_co_u32_e32 v9, vcc, 0, v3, vcc
	v_add_co_u32_e32 v48, vcc, s85, v2
	s_nop 1
	v_addc_co_u32_e32 v49, vcc, 0, v3, vcc
	v_add_co_u32_e32 v50, vcc, s86, v2
	s_nop 1
	v_addc_co_u32_e32 v51, vcc, 0, v3, vcc
	v_add_co_u32_e32 v52, vcc, s87, v2
	s_nop 1
	v_addc_co_u32_e32 v53, vcc, 0, v3, vcc
	v_add_co_u32_e32 v54, vcc, s88, v2
	s_nop 1
	v_addc_co_u32_e32 v55, vcc, 0, v3, vcc
	v_add_co_u32_e32 v56, vcc, s89, v2
	s_nop 1
	v_addc_co_u32_e32 v57, vcc, 0, v3, vcc
	global_load_dword v80, v[4:5], off nt
	global_load_dword v81, v[6:7], off offset:3072 nt
	global_load_dword v82, v[8:9], off offset:2048 nt
	global_load_dword v83, v[48:49], off offset:1024 nt
	global_load_dword v84, v[50:51], off nt
	global_load_dword v85, v[52:53], off offset:3072 nt
	global_load_dword v86, v[54:55], off offset:2048 nt
	global_load_dword v87, v[56:57], off offset:1024 nt
	v_add_co_u32_e32 v4, vcc, s90, v2
	s_nop 1
	v_addc_co_u32_e32 v5, vcc, 0, v3, vcc
	v_add_co_u32_e32 v6, vcc, s91, v2
	s_nop 1
	v_addc_co_u32_e32 v7, vcc, 0, v3, vcc
	v_add_co_u32_e32 v8, vcc, s92, v2
	s_nop 1
	v_addc_co_u32_e32 v9, vcc, 0, v3, vcc
	v_add_co_u32_e32 v48, vcc, s93, v2
	s_nop 1
	v_addc_co_u32_e32 v49, vcc, 0, v3, vcc
	v_add_co_u32_e32 v50, vcc, s97, v2
	s_nop 1
	v_addc_co_u32_e32 v51, vcc, 0, v3, vcc
	v_add_co_u32_e32 v52, vcc, s62, v2
	s_nop 1
	v_addc_co_u32_e32 v53, vcc, 0, v3, vcc
	v_add_co_u32_e32 v54, vcc, s63, v2
	s_nop 1
	v_addc_co_u32_e32 v55, vcc, 0, v3, vcc
	v_add_co_u32_e32 v56, vcc, s95, v2
	s_nop 1
; template <bool GAIN = false>
; __device__ __forceinline__ void tr_item(const float* W, size_t ldw, int k0, int c0, bf16* WT, int nd0, int K, LAS float* scr, int lane, const float* gk = nullptr, int kd0 = -1) {
;     ...
;     for (int i = 0; i < 64; ++i) scr[i * 65 + lane] = __builtin_nontemporal_load(W + (size_t)(k0 + i) * ldw + c0 + lane);
	v_addc_co_u32_e32 v57, vcc, 0, v3, vcc
	global_load_dword v88, v[4:5], off nt
	global_load_dword v89, v[6:7], off offset:3072 nt
	global_load_dword v90, v[8:9], off offset:2048 nt
	global_load_dword v91, v[48:49], off offset:1024 nt
	global_load_dword v92, v[50:51], off nt
	global_load_dword v93, v[52:53], off offset:3072 nt
	global_load_dword v94, v[54:55], off offset:2048 nt
	global_load_dword v95, v[56:57], off offset:1024 nt
	v_add_co_u32_e32 v4, vcc, s58, v2
	s_nop 1
	v_addc_co_u32_e32 v5, vcc, 0, v3, vcc
	v_add_co_u32_e32 v6, vcc, s59, v2
	s_nop 1
	v_addc_co_u32_e32 v7, vcc, 0, v3, vcc
	v_add_co_u32_e32 v8, vcc, s3, v2
	s_nop 1
	v_addc_co_u32_e32 v9, vcc, 0, v3, vcc
	v_add_co_u32_e32 v48, vcc, s51, v2
	s_nop 1
	v_addc_co_u32_e32 v49, vcc, 0, v3, vcc
	v_add_co_u32_e32 v50, vcc, s26, v2
	s_nop 1
	v_addc_co_u32_e32 v51, vcc, 0, v3, vcc
	v_add_co_u32_e32 v52, vcc, s33, v2
	s_nop 1
	v_addc_co_u32_e32 v53, vcc, 0, v3, vcc
	v_add_co_u32_e32 v54, vcc, s6, v2
	s_nop 1
	v_addc_co_u32_e32 v55, vcc, 0, v3, vcc
	v_add_co_u32_e32 v56, vcc, s7, v2
	s_nop 1
	v_addc_co_u32_e32 v57, vcc, 0, v3, vcc
	global_load_dword v96, v[4:5], off nt
	global_load_dword v97, v[6:7], off offset:3072 nt
	global_load_dword v98, v[8:9], off offset:2048 nt
	global_load_dword v99, v[48:49], off offset:1024 nt
	global_load_dword v100, v[50:51], off nt
	global_load_dword v101, v[52:53], off offset:3072 nt
	global_load_dword v102, v[54:55], off offset:2048 nt
	global_load_dword v103, v[56:57], off offset:1024 nt
	v_add_co_u32_e32 v4, vcc, s64, v2
	s_nop 1
	v_addc_co_u32_e32 v5, vcc, 0, v3, vcc
	v_add_co_u32_e32 v6, vcc, s65, v2
	s_nop 1
	v_addc_co_u32_e32 v7, vcc, 0, v3, vcc
	v_add_co_u32_e32 v8, vcc, s68, v2
	s_nop 1
	v_addc_co_u32_e32 v9, vcc, 0, v3, vcc
	v_add_co_u32_e32 v48, vcc, s69, v2
	s_nop 1
	v_addc_co_u32_e32 v49, vcc, 0, v3, vcc
	v_add_co_u32_e32 v50, vcc, s96, v2
	s_nop 1
	v_addc_co_u32_e32 v51, vcc, 0, v3, vcc
	v_add_co_u32_e32 v52, vcc, s56, v2
	s_nop 1
	v_addc_co_u32_e32 v53, vcc, 0, v3, vcc
	v_add_co_u32_e32 v54, vcc, s31, v2
	s_nop 1
	v_addc_co_u32_e32 v55, vcc, 0, v3, vcc
	v_add_co_u32_e32 v56, vcc, s35, v2
	s_nop 1
	v_addc_co_u32_e32 v57, vcc, 0, v3, vcc
	global_load_dword v104, v[4:5], off nt
	global_load_dword v105, v[6:7], off offset:3072 nt
	global_load_dword v106, v[8:9], off offset:2048 nt
	global_load_dword v107, v[48:49], off offset:1024 nt
	global_load_dword v108, v[50:51], off nt
	global_load_dword v109, v[52:53], off offset:3072 nt
	global_load_dword v110, v[54:55], off offset:2048 nt
	s_nop 0
	global_load_dword v56, v[56:57], off offset:1024 nt
	v_add_co_u32_e32 v4, vcc, s42, v2
	s_nop 1
	v_addc_co_u32_e32 v5, vcc, 0, v3, vcc
	v_add_co_u32_e32 v6, vcc, s43, v2
	s_nop 1
	v_addc_co_u32_e32 v7, vcc, 0, v3, vcc
	v_add_co_u32_e32 v8, vcc, s44, v2
	s_nop 1
	v_addc_co_u32_e32 v9, vcc, 0, v3, vcc
	v_add_co_u32_e32 v48, vcc, s45, v2
	s_nop 1
	v_addc_co_u32_e32 v49, vcc, 0, v3, vcc
	v_add_co_u32_e32 v50, vcc, s46, v2
	s_nop 1
	v_addc_co_u32_e32 v51, vcc, 0, v3, vcc
	v_add_co_u32_e32 v52, vcc, s47, v2
	s_nop 1
	v_addc_co_u32_e32 v53, vcc, 0, v3, vcc
	v_add_co_u32_e32 v54, vcc, s48, v2
	s_nop 1
	v_addc_co_u32_e32 v55, vcc, 0, v3, vcc
	v_add_co_u32_e32 v2, vcc, s49, v2
	s_nop 1
	v_addc_co_u32_e32 v3, vcc, 0, v3, vcc
	global_load_dword v4, v[4:5], off nt
	s_nop 0
	global_load_dword v5, v[6:7], off offset:3072 nt
	s_nop 0
	global_load_dword v6, v[8:9], off offset:2048 nt
	global_load_dword v7, v[48:49], off offset:1024 nt
	s_nop 0
	global_load_dword v8, v[50:51], off nt
	global_load_dword v9, v[52:53], off offset:3072 nt
	global_load_dword v48, v[54:55], off offset:2048 nt
	s_nop 0
	global_load_dword v2, v[2:3], off offset:1024 nt
	s_waitcnt vmcnt(62)
	ds_write2_b32 v20, v39, v47 offset1:65
	s_waitcnt vmcnt(60)
	ds_write2_b32 v20, v58, v59 offset0:130 offset1:195
	s_waitcnt vmcnt(58)
	ds_write2_b32 v22, v60, v61 offset0:4 offset1:69
	s_waitcnt vmcnt(56)
	ds_write2_b32 v22, v62, v63 offset0:134 offset1:199
	s_waitcnt vmcnt(54)
	ds_write2_b32 v23, v64, v65 offset0:8 offset1:73
	s_waitcnt vmcnt(52)
	ds_write2_b32 v23, v66, v67 offset0:138 offset1:203
	s_waitcnt vmcnt(50)
	ds_write2_b32 v24, v68, v69 offset0:12 offset1:77
	s_waitcnt vmcnt(48)
	ds_write2_b32 v24, v70, v71 offset0:142 offset1:207
	s_waitcnt vmcnt(46)
	ds_write2_b32 v25, v72, v73 offset0:16 offset1:81
	s_waitcnt vmcnt(44)
	ds_write2_b32 v25, v74, v75 offset0:146 offset1:211
	s_waitcnt vmcnt(42)
	ds_write2_b32 v26, v76, v77 offset0:20 offset1:85
	s_waitcnt vmcnt(40)
	ds_write2_b32 v26, v78, v79 offset0:150 offset1:215
	s_waitcnt vmcnt(38)
	ds_write2_b32 v27, v80, v81 offset0:24 offset1:89
	s_waitcnt vmcnt(36)
	ds_write2_b32 v27, v82, v83 offset0:154 offset1:219
	s_waitcnt vmcnt(34)
	ds_write2_b32 v28, v84, v85 offset0:28 offset1:93
	s_waitcnt vmcnt(32)
	ds_write2_b32 v28, v86, v87 offset0:158 offset1:223
	s_waitcnt vmcnt(30)
	ds_write2_b32 v29, v88, v89 offset0:32 offset1:97
	s_waitcnt vmcnt(28)
	ds_write2_b32 v29, v90, v91 offset0:162 offset1:227
	s_waitcnt vmcnt(26)
	ds_write2_b32 v30, v92, v93 offset0:36 offset1:101
	s_waitcnt vmcnt(24)
	ds_write2_b32 v30, v94, v95 offset0:166 offset1:231
	s_waitcnt vmcnt(22)
; #define LAS __attribute__((address_space(3)))
; __host__ __device__ __forceinline__ size_t blk(int r, int k, int K) { return (((size_t)((r >> 8) * (K >> 6) + (k >> 6))) << 14) + (size_t)(((r & 255) << 6) + (k & 63)); }
; __device__ __forceinline__ unsigned pk2(float lo, float hi) { f32x2 v = {lo, hi}; bf16x2_t b = __builtin_convertvector(v, bf16x2_t); return __builtin_bit_cast(unsigned, b); }
; template <bool GAIN = false>
; __device__ __forceinline__ void tr_item(const float* W, size_t ldw, int k0, int c0, bf16* WT, int nd0, int K, LAS float* scr, int lane, const float* gk = nullptr, int kd0 = -1) {
;     ...
;     for (int i = 0; i < 64; ++i) scr[i * 65 + lane] = __builtin_nontemporal_load(W + (size_t)(k0 + i) * ldw + c0 + lane);
;     asm volatile("s_waitcnt lgkmcnt(0)" ::: "memory");
;     const int c = lane & 7;
;     f32x4 g0 = {1.f, 1.f, 1.f, 1.f}, g1 = g0;
;     if (GAIN) { g0 = *(const f32x4*)(gk + k0 + 8 * c); g1 = *(const f32x4*)(gk + k0 + 8 * c + 4); }
; #pragma unroll
;     for (int j = 0; j < 8; ++j) { const int n = (lane >> 3) + 8 * j; const LAS float* s = scr + (8 * c) * 65 + n;
;         u32x4 o; o.x = pk2(s[0 * 65] * g0.x, s[1 * 65] * g0.y); o.y = pk2(s[2 * 65] * g0.z, s[3 * 65] * g0.w); o.z = pk2(s[4 * 65] * g1.x, s[5 * 65] * g1.y); o.w = pk2(s[6 * 65] * g1.z, s[7 * 65] * g1.w);
;         *(u32x4*)(WT + blk(nd0 + n, kd0 + 8 * c, K)) = o; }
;     asm volatile("s_waitcnt lgkmcnt(0)" ::: "memory");
	ds_write2_b32 v31, v96, v97 offset0:40 offset1:105
	s_waitcnt vmcnt(20)
	ds_write2_b32 v31, v98, v99 offset0:170 offset1:235
	s_waitcnt vmcnt(18)
	ds_write2_b32 v32, v100, v101 offset0:44 offset1:109
	s_waitcnt vmcnt(16)
	ds_write2_b32 v32, v102, v103 offset0:174 offset1:239
	s_waitcnt vmcnt(14)
	ds_write2_b32 v33, v104, v105 offset0:48 offset1:113
	s_waitcnt vmcnt(12)
	ds_write2_b32 v33, v106, v107 offset0:178 offset1:243
	s_waitcnt vmcnt(10)
	ds_write2_b32 v34, v108, v109 offset0:52 offset1:117
	s_waitcnt vmcnt(8)
	ds_write2_b32 v34, v110, v56 offset0:182 offset1:247
	s_waitcnt vmcnt(6)
	ds_write2_b32 v35, v4, v5 offset0:56 offset1:121
	s_waitcnt vmcnt(4)
	ds_write2_b32 v35, v6, v7 offset0:186 offset1:251
	s_waitcnt vmcnt(2)
	ds_write2_b32 v36, v8, v9 offset0:60 offset1:125
	s_waitcnt vmcnt(0)
	ds_write2_b32 v36, v48, v2 offset0:190 offset1:255
	s_waitcnt lgkmcnt(0)
	ds_read2_b32 v[6:7], v21 offset0:65 offset1:73
	ds_read2_b32 v[8:9], v21 offset1:8
	ds_read2_b32 v[48:49], v21 offset0:130 offset1:138
	ds_read2_b32 v[50:51], v21 offset0:195 offset1:203
	ds_read2_b32 v[52:53], v37 offset0:4 offset1:12
	ds_read2_b32 v[54:55], v37 offset0:69 offset1:77
	ds_read2_b32 v[56:57], v37 offset0:134 offset1:142
	ds_read2_b32 v[58:59], v37 offset0:199 offset1:207
	s_waitcnt lgkmcnt(6)
	v_cvt_pk_bf16_f32 v2, v8, v6
	v_or_b32_e32 v6, s0, v193
	v_lshlrev_b32_e32 v6, 6, v6
	v_or3_b32 v6, v6, s12, v1
	s_waitcnt lgkmcnt(4)
	v_cvt_pk_bf16_f32 v3, v48, v50
	s_waitcnt lgkmcnt(2)
	v_cvt_pk_bf16_f32 v4, v52, v54
	s_waitcnt lgkmcnt(0)
	v_cvt_pk_bf16_f32 v5, v56, v58
	v_lshlrev_b32_e32 v6, 1, v6
	global_store_dwordx4 v6, v[2:5], s[4:5] nt
	v_or_b32_e32 v6, s0, v40
	v_lshlrev_b32_e32 v6, 6, v6
	v_or3_b32 v6, v6, s12, v1
	v_cvt_pk_bf16_f32 v2, v9, v7
	v_cvt_pk_bf16_f32 v3, v49, v51
	v_cvt_pk_bf16_f32 v4, v53, v55
	v_cvt_pk_bf16_f32 v5, v57, v59
	v_lshlrev_b32_e32 v39, 1, v6
	ds_read2_b32 v[6:7], v21 offset0:16 offset1:24
	ds_read2_b32 v[8:9], v21 offset0:81 offset1:89
	ds_read2_b32 v[48:49], v21 offset0:146 offset1:154
	ds_read2_b32 v[50:51], v21 offset0:211 offset1:219
	ds_read2_b32 v[52:53], v37 offset0:20 offset1:28
	ds_read2_b32 v[54:55], v37 offset0:85 offset1:93
	ds_read2_b32 v[56:57], v37 offset0:150 offset1:158
	ds_read2_b32 v[58:59], v37 offset0:215 offset1:223
	global_store_dwordx4 v39, v[2:5], s[4:5] nt
	s_waitcnt lgkmcnt(6)
	s_nop 0
	v_cvt_pk_bf16_f32 v2, v6, v8
	v_or_b32_e32 v6, s0, v41
	v_lshlrev_b32_e32 v6, 6, v6
	v_or3_b32 v6, v6, s12, v1
	s_waitcnt lgkmcnt(4)
	v_cvt_pk_bf16_f32 v3, v48, v50
	s_waitcnt lgkmcnt(2)
	v_cvt_pk_bf16_f32 v4, v52, v54
	s_waitcnt lgkmcnt(0)
	v_cvt_pk_bf16_f32 v5, v56, v58
	v_lshlrev_b32_e32 v6, 1, v6
	global_store_dwordx4 v6, v[2:5], s[4:5] nt
	v_or_b32_e32 v6, s0, v42
	v_lshlrev_b32_e32 v6, 6, v6
	v_or3_b32 v6, v6, s12, v1
	v_cvt_pk_bf16_f32 v2, v7, v9
	v_cvt_pk_bf16_f32 v3, v49, v51
	v_cvt_pk_bf16_f32 v4, v53, v55
	v_cvt_pk_bf16_f32 v5, v57, v59
	v_lshlrev_b32_e32 v39, 1, v6
	ds_read2_b32 v[6:7], v21 offset0:32 offset1:40
	ds_read2_b32 v[8:9], v21 offset0:97 offset1:105
	ds_read2_b32 v[48:49], v21 offset0:162 offset1:170
	ds_read2_b32 v[50:51], v21 offset0:227 offset1:235
	ds_read2_b32 v[52:53], v37 offset0:36 offset1:44
	ds_read2_b32 v[54:55], v37 offset0:101 offset1:109
	ds_read2_b32 v[56:57], v37 offset0:166 offset1:174
	ds_read2_b32 v[58:59], v37 offset0:231 offset1:239
	global_store_dwordx4 v39, v[2:5], s[4:5] nt
	s_waitcnt lgkmcnt(6)
	s_nop 0
	v_cvt_pk_bf16_f32 v2, v6, v8
	v_or_b32_e32 v6, s0, v43
	v_lshlrev_b32_e32 v6, 6, v6
	v_or3_b32 v6, v6, s12, v1
	s_waitcnt lgkmcnt(4)
	v_cvt_pk_bf16_f32 v3, v48, v50
	s_waitcnt lgkmcnt(2)
	v_cvt_pk_bf16_f32 v4, v52, v54
	s_waitcnt lgkmcnt(0)
	v_cvt_pk_bf16_f32 v5, v56, v58
	v_lshlrev_b32_e32 v6, 1, v6
	global_store_dwordx4 v6, v[2:5], s[4:5] nt
	v_or_b32_e32 v6, s0, v44
	v_lshlrev_b32_e32 v6, 6, v6
	v_or3_b32 v6, v6, s12, v1
	v_cvt_pk_bf16_f32 v2, v7, v9
	v_cvt_pk_bf16_f32 v3, v49, v51
	v_cvt_pk_bf16_f32 v4, v53, v55
	v_cvt_pk_bf16_f32 v5, v57, v59
	v_lshlrev_b32_e32 v39, 1, v6
	ds_read2_b32 v[6:7], v21 offset0:48 offset1:56
	ds_read2_b32 v[8:9], v21 offset0:113 offset1:121
	ds_read2_b32 v[48:49], v21 offset0:178 offset1:186
	ds_read2_b32 v[50:51], v21 offset0:243 offset1:251
	ds_read2_b32 v[52:53], v37 offset0:52 offset1:60
	ds_read2_b32 v[54:55], v37 offset0:117 offset1:125
	ds_read2_b32 v[56:57], v37 offset0:182 offset1:190
	ds_read2_b32 v[58:59], v37 offset0:247 offset1:255
	global_store_dwordx4 v39, v[2:5], s[4:5] nt
	s_waitcnt lgkmcnt(6)
	s_nop 0
	v_cvt_pk_bf16_f32 v2, v6, v8
	v_or_b32_e32 v6, s0, v45
	v_lshlrev_b32_e32 v6, 6, v6
	v_or3_b32 v6, v6, s12, v1
	s_waitcnt lgkmcnt(4)
	v_cvt_pk_bf16_f32 v3, v48, v50
	s_waitcnt lgkmcnt(2)
	v_cvt_pk_bf16_f32 v4, v52, v54
	s_waitcnt lgkmcnt(0)
	v_cvt_pk_bf16_f32 v5, v56, v58
	v_lshlrev_b32_e32 v6, 1, v6
	global_store_dwordx4 v6, v[2:5], s[4:5] nt
	v_or_b32_e32 v6, s0, v46
	v_lshlrev_b32_e32 v6, 6, v6
	v_or3_b32 v6, v6, s12, v1
	v_cvt_pk_bf16_f32 v2, v7, v9
	v_cvt_pk_bf16_f32 v3, v49, v51
	v_cvt_pk_bf16_f32 v4, v53, v55
	v_cvt_pk_bf16_f32 v5, v57, v59
	v_lshlrev_b32_e32 v6, 1, v6
	global_store_dwordx4 v6, v[2:5], s[4:5] nt
	s_waitcnt lgkmcnt(0)

; #define LAS __attribute__((address_space(3)))
; template <bool GAIN = false>
; __device__ __forceinline__ void tr_item(const float* W, size_t ldw, int k0, int c0, bf16* WT, int nd0, int K, LAS float* scr, int lane, const float* gk = nullptr, int kd0 = -1) {
;     if (kd0 < 0) kd0 = k0;
; #pragma unroll
;     for (int i = 0; i < 64; ++i) scr[i * 65 + lane] = __builtin_nontemporal_load(W + (size_t)(k0 + i) * ldw + c0 + lane);
; template <bool GAIN = false>
; __device__ __forceinline__ void tr_w13(const float* W, int which, bf16* WT, LAS float* scr, int item, int lane, const float* gk = nullptr) {
;     const int nblk = FF / 64, kb = item / nblk, nb = item % nblk, n0 = 64 * nb;
;     tr_item<GAIN>(W, FF, 64 * kb, n0, WT, (n0 >> 7) * 256 + which * 128 + (n0 & 127), D, scr, lane, gk);
.LBB0_36:
	s_andn2_b64 vcc, exec, s[12:13]
	s_cbranch_vccnz .LBB0_38
	s_add_i32 s0, s50, 0xd500
	s_and_b32 s12, s0, 0xffff
	s_mul_i32 s12, s12, 0xbe83
	s_lshr_b32 s12, s12, 23
	s_mul_i32 s13, s12, 0xac
	s_sub_i32 s0, s0, s13
	s_and_b32 s13, s0, 0xffff
	s_lshl_b32 s0, s13, 8
	v_lshl_add_u64 v[2:3], v[14:15], 0, s[0:1]
	s_mul_i32 s0, s12, 0x2b0000
	v_lshl_add_u64 v[2:3], v[2:3], 0, s[0:1]
	s_mov_b32 s0, 0xa000
	v_add_co_u32_e32 v4, vcc, s0, v2
	s_mov_b32 s0, 0x15000
	s_nop 0
	v_addc_co_u32_e32 v5, vcc, 0, v3, vcc
	v_add_co_u32_e32 v6, vcc, s0, v2
	s_mov_b32 s0, 0x20000
	s_nop 0
	v_addc_co_u32_e32 v7, vcc, 0, v3, vcc
	v_add_co_u32_e32 v8, vcc, s0, v2
	s_mov_b32 s0, 0x2b000
	s_nop 0
	v_addc_co_u32_e32 v9, vcc, 0, v3, vcc
	v_add_co_u32_e32 v48, vcc, s0, v2
	s_mov_b32 s0, 0x35000
	s_nop 0
	v_addc_co_u32_e32 v49, vcc, 0, v3, vcc
	v_add_co_u32_e32 v50, vcc, s0, v2
	s_mov_b32 s0, 0x40000
	s_nop 0
	v_addc_co_u32_e32 v51, vcc, 0, v3, vcc
	v_add_co_u32_e32 v52, vcc, s0, v2
	s_mov_b32 s0, 0x4b000
	s_nop 0
	v_addc_co_u32_e32 v53, vcc, 0, v3, vcc
	v_add_co_u32_e32 v54, vcc, s0, v2
	s_mov_b32 s0, 0x56000
	s_nop 0
	v_addc_co_u32_e32 v55, vcc, 0, v3, vcc
	global_load_dword v39, v[2:3], off nt
	global_load_dword v47, v[4:5], off offset:3072 nt
	global_load_dword v58, v[6:7], off offset:2048 nt
	global_load_dword v59, v[8:9], off offset:1024 nt
	global_load_dword v60, v[48:49], off nt
	global_load_dword v61, v[50:51], off offset:3072 nt
	global_load_dword v62, v[52:53], off offset:2048 nt
	global_load_dword v63, v[54:55], off offset:1024 nt
	v_add_co_u32_e32 v4, vcc, s0, v2
	s_mov_b32 s0, 0x60000
	s_nop 0
	v_addc_co_u32_e32 v5, vcc, 0, v3, vcc
	v_add_co_u32_e32 v6, vcc, s0, v2
	s_mov_b32 s0, 0x6b000
	s_nop 0
	v_addc_co_u32_e32 v7, vcc, 0, v3, vcc
	v_add_co_u32_e32 v8, vcc, s0, v2
	s_mov_b32 s0, 0x76000
	s_nop 0
	v_addc_co_u32_e32 v9, vcc, 0, v3, vcc
	v_add_co_u32_e32 v48, vcc, s0, v2
	s_mov_b32 s0, 0x81000
	s_nop 0
	v_addc_co_u32_e32 v49, vcc, 0, v3, vcc
	v_add_co_u32_e32 v50, vcc, s0, v2
	s_lshl_b32 s0, s12, 8
	s_nop 0
	v_addc_co_u32_e32 v51, vcc, 0, v3, vcc
	v_add_co_u32_e32 v52, vcc, s57, v2
	s_lshl_b32 s14, s13, 7
	s_nop 0
	v_addc_co_u32_e32 v53, vcc, 0, v3, vcc
	v_add_co_u32_e32 v54, vcc, s61, v2
	s_nop 1
	v_addc_co_u32_e32 v55, vcc, 0, v3, vcc
	v_add_co_u32_e32 v56, vcc, s73, v2
	s_nop 1
	v_addc_co_u32_e32 v57, vcc, 0, v3, vcc
	global_load_dword v64, v[4:5], off nt
	global_load_dword v65, v[6:7], off offset:3072 nt
	global_load_dword v66, v[8:9], off offset:2048 nt
	global_load_dword v67, v[48:49], off offset:1024 nt
	global_load_dword v68, v[50:51], off nt
	global_load_dword v69, v[52:53], off offset:3072 nt
	global_load_dword v70, v[54:55], off offset:2048 nt
	global_load_dword v71, v[56:57], off offset:1024 nt
	v_add_co_u32_e32 v4, vcc, s74, v2
	s_nop 1
	v_addc_co_u32_e32 v5, vcc, 0, v3, vcc
	v_add_co_u32_e32 v6, vcc, s75, v2
	s_nop 1
	v_addc_co_u32_e32 v7, vcc, 0, v3, vcc
	v_add_co_u32_e32 v8, vcc, s76, v2
	s_nop 1
	v_addc_co_u32_e32 v9, vcc, 0, v3, vcc
	v_add_co_u32_e32 v48, vcc, s77, v2
	s_nop 1
	v_addc_co_u32_e32 v49, vcc, 0, v3, vcc
	v_add_co_u32_e32 v50, vcc, s78, v2
	s_nop 1
	v_addc_co_u32_e32 v51, vcc, 0, v3, vcc
	v_add_co_u32_e32 v52, vcc, s79, v2
	s_nop 1
	v_addc_co_u32_e32 v53, vcc, 0, v3, vcc
	v_add_co_u32_e32 v54, vcc, s80, v2
	s_nop 1
	v_addc_co_u32_e32 v55, vcc, 0, v3, vcc
	v_add_co_u32_e32 v56, vcc, s81, v2
	s_nop 1
	v_addc_co_u32_e32 v57, vcc, 0, v3, vcc
	global_load_dword v72, v[4:5], off nt
	global_load_dword v73, v[6:7], off offset:3072 nt
	global_load_dword v74, v[8:9], off offset:2048 nt
	global_load_dword v75, v[48:49], off offset:1024 nt
	global_load_dword v76, v[50:51], off nt
	global_load_dword v77, v[52:53], off offset:3072 nt
	global_load_dword v78, v[54:55], off offset:2048 nt
	global_load_dword v79, v[56:57], off offset:1024 nt
	v_add_co_u32_e32 v4, vcc, s82, v2
	s_nop 1
	v_addc_co_u32_e32 v5, vcc, 0, v3, vcc
	v_add_co_u32_e32 v6, vcc, s83, v2
	s_nop 1
	v_addc_co_u32_e32 v7, vcc, 0, v3, vcc
	v_add_co_u32_e32 v8, vcc, s84, v2
	s_nop 1
	v_addc_co_u32_e32 v9, vcc, 0, v3, vcc
	v_add_co_u32_e32 v48, vcc, s85, v2
	s_nop 1
	v_addc_co_u32_e32 v49, vcc, 0, v3, vcc
	v_add_co_u32_e32 v50, vcc, s86, v2
	s_nop 1
	v_addc_co_u32_e32 v51, vcc, 0, v3, vcc
	v_add_co_u32_e32 v52, vcc, s87, v2
	s_nop 1
	v_addc_co_u32_e32 v53, vcc, 0, v3, vcc
	v_add_co_u32_e32 v54, vcc, s88, v2
	s_nop 1
	v_addc_co_u32_e32 v55, vcc, 0, v3, vcc
	v_add_co_u32_e32 v56, vcc, s89, v2
	s_nop 1
	v_addc_co_u32_e32 v57, vcc, 0, v3, vcc
	global_load_dword v80, v[4:5], off nt
	global_load_dword v81, v[6:7], off offset:3072 nt
	global_load_dword v82, v[8:9], off offset:2048 nt
	global_load_dword v83, v[48:49], off offset:1024 nt
	global_load_dword v84, v[50:51], off nt
	global_load_dword v85, v[52:53], off offset:3072 nt
	global_load_dword v86, v[54:55], off offset:2048 nt
	global_load_dword v87, v[56:57], off offset:1024 nt
	v_add_co_u32_e32 v4, vcc, s90, v2
	s_nop 1
	v_addc_co_u32_e32 v5, vcc, 0, v3, vcc
	v_add_co_u32_e32 v6, vcc, s91, v2
	s_nop 1
	v_addc_co_u32_e32 v7, vcc, 0, v3, vcc
	v_add_co_u32_e32 v8, vcc, s92, v2
	s_nop 1
	v_addc_co_u32_e32 v9, vcc, 0, v3, vcc
	v_add_co_u32_e32 v48, vcc, s93, v2
	s_nop 1
	v_addc_co_u32_e32 v49, vcc, 0, v3, vcc
	v_add_co_u32_e32 v50, vcc, s97, v2
	s_nop 1
	v_addc_co_u32_e32 v51, vcc, 0, v3, vcc
	v_add_co_u32_e32 v52, vcc, s62, v2
	s_nop 1
	v_addc_co_u32_e32 v53, vcc, 0, v3, vcc
	v_add_co_u32_e32 v54, vcc, s63, v2
	s_nop 1
	v_addc_co_u32_e32 v55, vcc, 0, v3, vcc
	v_add_co_u32_e32 v56, vcc, s95, v2
	s_nop 1
	v_addc_co_u32_e32 v57, vcc, 0, v3, vcc
	global_load_dword v88, v[4:5], off nt
	global_load_dword v89, v[6:7], off offset:3072 nt
; template <bool GAIN = false>
; __device__ __forceinline__ void tr_item(const float* W, size_t ldw, int k0, int c0, bf16* WT, int nd0, int K, LAS float* scr, int lane, const float* gk = nullptr, int kd0 = -1) {
;     ...
;     for (int i = 0; i < 64; ++i) scr[i * 65 + lane] = __builtin_nontemporal_load(W + (size_t)(k0 + i) * ldw + c0 + lane);
;     asm volatile("s_waitcnt lgkmcnt(0)" ::: "memory");
	global_load_dword v90, v[8:9], off offset:2048 nt
	global_load_dword v91, v[48:49], off offset:1024 nt
	global_load_dword v92, v[50:51], off nt
	global_load_dword v93, v[52:53], off offset:3072 nt
	global_load_dword v94, v[54:55], off offset:2048 nt
	global_load_dword v95, v[56:57], off offset:1024 nt
	v_add_co_u32_e32 v4, vcc, s58, v2
	s_nop 1
	v_addc_co_u32_e32 v5, vcc, 0, v3, vcc
	v_add_co_u32_e32 v6, vcc, s59, v2
	s_nop 1
	v_addc_co_u32_e32 v7, vcc, 0, v3, vcc
	v_add_co_u32_e32 v8, vcc, s3, v2
	s_nop 1
	v_addc_co_u32_e32 v9, vcc, 0, v3, vcc
	v_add_co_u32_e32 v48, vcc, s51, v2
	s_nop 1
	v_addc_co_u32_e32 v49, vcc, 0, v3, vcc
	v_add_co_u32_e32 v50, vcc, s26, v2
	s_nop 1
	v_addc_co_u32_e32 v51, vcc, 0, v3, vcc
	v_add_co_u32_e32 v52, vcc, s33, v2
	s_nop 1
	v_addc_co_u32_e32 v53, vcc, 0, v3, vcc
	v_add_co_u32_e32 v54, vcc, s6, v2
	s_nop 1
	v_addc_co_u32_e32 v55, vcc, 0, v3, vcc
	v_add_co_u32_e32 v56, vcc, s7, v2
	s_nop 1
	v_addc_co_u32_e32 v57, vcc, 0, v3, vcc
	global_load_dword v96, v[4:5], off nt
	global_load_dword v97, v[6:7], off offset:3072 nt
	global_load_dword v98, v[8:9], off offset:2048 nt
	global_load_dword v99, v[48:49], off offset:1024 nt
	global_load_dword v100, v[50:51], off nt
	global_load_dword v101, v[52:53], off offset:3072 nt
	global_load_dword v102, v[54:55], off offset:2048 nt
	global_load_dword v103, v[56:57], off offset:1024 nt
	v_add_co_u32_e32 v4, vcc, s64, v2
	s_nop 1
	v_addc_co_u32_e32 v5, vcc, 0, v3, vcc
	v_add_co_u32_e32 v6, vcc, s65, v2
	s_nop 1
	v_addc_co_u32_e32 v7, vcc, 0, v3, vcc
	v_add_co_u32_e32 v8, vcc, s68, v2
	s_nop 1
	v_addc_co_u32_e32 v9, vcc, 0, v3, vcc
	v_add_co_u32_e32 v48, vcc, s69, v2
	s_nop 1
	v_addc_co_u32_e32 v49, vcc, 0, v3, vcc
	v_add_co_u32_e32 v50, vcc, s96, v2
	s_nop 1
	v_addc_co_u32_e32 v51, vcc, 0, v3, vcc
	v_add_co_u32_e32 v52, vcc, s56, v2
	s_nop 1
	v_addc_co_u32_e32 v53, vcc, 0, v3, vcc
	v_add_co_u32_e32 v54, vcc, s31, v2
	s_nop 1
	v_addc_co_u32_e32 v55, vcc, 0, v3, vcc
	v_add_co_u32_e32 v56, vcc, s35, v2
	s_nop 1
	v_addc_co_u32_e32 v57, vcc, 0, v3, vcc
	global_load_dword v104, v[4:5], off nt
	global_load_dword v105, v[6:7], off offset:3072 nt
	global_load_dword v106, v[8:9], off offset:2048 nt
	global_load_dword v107, v[48:49], off offset:1024 nt
	global_load_dword v108, v[50:51], off nt
	global_load_dword v109, v[52:53], off offset:3072 nt
	global_load_dword v110, v[54:55], off offset:2048 nt
	s_nop 0
	global_load_dword v56, v[56:57], off offset:1024 nt
	v_add_co_u32_e32 v4, vcc, s42, v2
	s_nop 1
	v_addc_co_u32_e32 v5, vcc, 0, v3, vcc
	v_add_co_u32_e32 v6, vcc, s43, v2
	s_nop 1
	v_addc_co_u32_e32 v7, vcc, 0, v3, vcc
	v_add_co_u32_e32 v8, vcc, s44, v2
	s_nop 1
	v_addc_co_u32_e32 v9, vcc, 0, v3, vcc
	v_add_co_u32_e32 v48, vcc, s45, v2
	s_nop 1
	v_addc_co_u32_e32 v49, vcc, 0, v3, vcc
	v_add_co_u32_e32 v50, vcc, s46, v2
	s_nop 1
	v_addc_co_u32_e32 v51, vcc, 0, v3, vcc
	v_add_co_u32_e32 v52, vcc, s47, v2
	s_nop 1
	v_addc_co_u32_e32 v53, vcc, 0, v3, vcc
	v_add_co_u32_e32 v54, vcc, s48, v2
	s_nop 1
	v_addc_co_u32_e32 v55, vcc, 0, v3, vcc
	v_add_co_u32_e32 v2, vcc, s49, v2
	s_nop 1
	v_addc_co_u32_e32 v3, vcc, 0, v3, vcc
	global_load_dword v4, v[4:5], off nt
	s_nop 0
	global_load_dword v5, v[6:7], off offset:3072 nt
	s_nop 0
	global_load_dword v6, v[8:9], off offset:2048 nt
	global_load_dword v7, v[48:49], off offset:1024 nt
	s_nop 0
	global_load_dword v8, v[50:51], off nt
	global_load_dword v9, v[52:53], off offset:3072 nt
	global_load_dword v48, v[54:55], off offset:2048 nt
	s_nop 0
	global_load_dword v2, v[2:3], off offset:1024 nt
	s_waitcnt vmcnt(62)
	ds_write2_b32 v20, v39, v47 offset1:65
	s_waitcnt vmcnt(60)
	ds_write2_b32 v20, v58, v59 offset0:130 offset1:195
	s_waitcnt vmcnt(58)
	ds_write2_b32 v22, v60, v61 offset0:4 offset1:69
	s_waitcnt vmcnt(56)
	ds_write2_b32 v22, v62, v63 offset0:134 offset1:199
	s_waitcnt vmcnt(54)
	ds_write2_b32 v23, v64, v65 offset0:8 offset1:73
	s_waitcnt vmcnt(52)
	ds_write2_b32 v23, v66, v67 offset0:138 offset1:203
	s_waitcnt vmcnt(50)
	ds_write2_b32 v24, v68, v69 offset0:12 offset1:77
	s_waitcnt vmcnt(48)
	ds_write2_b32 v24, v70, v71 offset0:142 offset1:207
	s_waitcnt vmcnt(46)
	ds_write2_b32 v25, v72, v73 offset0:16 offset1:81
	s_waitcnt vmcnt(44)
	ds_write2_b32 v25, v74, v75 offset0:146 offset1:211
	s_waitcnt vmcnt(42)
	ds_write2_b32 v26, v76, v77 offset0:20 offset1:85
	s_waitcnt vmcnt(40)
	ds_write2_b32 v26, v78, v79 offset0:150 offset1:215
	s_waitcnt vmcnt(38)
	ds_write2_b32 v27, v80, v81 offset0:24 offset1:89
	s_waitcnt vmcnt(36)
	ds_write2_b32 v27, v82, v83 offset0:154 offset1:219
	s_waitcnt vmcnt(34)
	ds_write2_b32 v28, v84, v85 offset0:28 offset1:93
	s_waitcnt vmcnt(32)
	ds_write2_b32 v28, v86, v87 offset0:158 offset1:223
	s_waitcnt vmcnt(30)
	ds_write2_b32 v29, v88, v89 offset0:32 offset1:97
	s_waitcnt vmcnt(28)
	ds_write2_b32 v29, v90, v91 offset0:162 offset1:227
	s_waitcnt vmcnt(26)
	ds_write2_b32 v30, v92, v93 offset0:36 offset1:101
	s_waitcnt vmcnt(24)
	ds_write2_b32 v30, v94, v95 offset0:166 offset1:231
	s_waitcnt vmcnt(22)
	ds_write2_b32 v31, v96, v97 offset0:40 offset1:105
	s_waitcnt vmcnt(20)
	ds_write2_b32 v31, v98, v99 offset0:170 offset1:235
	s_waitcnt vmcnt(18)
	ds_write2_b32 v32, v100, v101 offset0:44 offset1:109
	s_waitcnt vmcnt(16)
	ds_write2_b32 v32, v102, v103 offset0:174 offset1:239
	s_waitcnt vmcnt(14)
	ds_write2_b32 v33, v104, v105 offset0:48 offset1:113
	s_waitcnt vmcnt(12)
	ds_write2_b32 v33, v106, v107 offset0:178 offset1:243
	s_waitcnt vmcnt(10)
	ds_write2_b32 v34, v108, v109 offset0:52 offset1:117
	s_waitcnt vmcnt(8)
	ds_write2_b32 v34, v110, v56 offset0:182 offset1:247
	s_waitcnt vmcnt(6)
; #define LAS __attribute__((address_space(3)))
; __host__ __device__ __forceinline__ size_t blk(int r, int k, int K) { return (((size_t)((r >> 8) * (K >> 6) + (k >> 6))) << 14) + (size_t)(((r & 255) << 6) + (k & 63)); }
; __device__ __forceinline__ unsigned pk2(float lo, float hi) { f32x2 v = {lo, hi}; bf16x2_t b = __builtin_convertvector(v, bf16x2_t); return __builtin_bit_cast(unsigned, b); }
; template <bool GAIN = false>
; __device__ __forceinline__ void tr_item(const float* W, size_t ldw, int k0, int c0, bf16* WT, int nd0, int K, LAS float* scr, int lane, const float* gk = nullptr, int kd0 = -1) {
;     ...
;     for (int i = 0; i < 64; ++i) scr[i * 65 + lane] = __builtin_nontemporal_load(W + (size_t)(k0 + i) * ldw + c0 + lane);
;     asm volatile("s_waitcnt lgkmcnt(0)" ::: "memory");
;     const int c = lane & 7;
;     f32x4 g0 = {1.f, 1.f, 1.f, 1.f}, g1 = g0;
;     if (GAIN) { g0 = *(const f32x4*)(gk + k0 + 8 * c); g1 = *(const f32x4*)(gk + k0 + 8 * c + 4); }
; #pragma unroll
;     for (int j = 0; j < 8; ++j) { const int n = (lane >> 3) + 8 * j; const LAS float* s = scr + (8 * c) * 65 + n;
;         u32x4 o; o.x = pk2(s[0 * 65] * g0.x, s[1 * 65] * g0.y); o.y = pk2(s[2 * 65] * g0.z, s[3 * 65] * g0.w); o.z = pk2(s[4 * 65] * g1.x, s[5 * 65] * g1.y); o.w = pk2(s[6 * 65] * g1.z, s[7 * 65] * g1.w);
;         *(u32x4*)(WT + blk(nd0 + n, kd0 + 8 * c, K)) = o; }
	ds_write2_b32 v35, v4, v5 offset0:56 offset1:121
	s_waitcnt vmcnt(4)
	ds_write2_b32 v35, v6, v7 offset0:186 offset1:251
	s_waitcnt vmcnt(2)
	ds_write2_b32 v36, v8, v9 offset0:60 offset1:125
	s_waitcnt vmcnt(0)
	ds_write2_b32 v36, v48, v2 offset0:190 offset1:255
	s_waitcnt lgkmcnt(0)
	v_lshl_add_u64 v[2:3], v[16:17], 0, s[0:1]
	global_load_dwordx4 v[6:9], v[2:3], off
	s_nop 0
	global_load_dwordx4 v[2:5], v[2:3], off offset:16
	ds_read2_b32 v[52:53], v21 offset1:8
	ds_read2_b32 v[54:55], v21 offset0:65 offset1:73
	ds_read2_b32 v[56:57], v21 offset0:130 offset1:138
	ds_read2_b32 v[58:59], v21 offset0:195 offset1:203
	s_lshl_b32 s0, s13, 6
	s_and_b32 s0, s0, 64
	ds_read2_b32 v[60:61], v37 offset0:4 offset1:12
	ds_read2_b32 v[62:63], v37 offset0:69 offset1:77
	ds_read2_b32 v[64:65], v37 offset0:134 offset1:142
	ds_read2_b32 v[66:67], v37 offset0:199 offset1:207
	s_or_b32 s0, s0, s14
	s_bitset1_b32 s0, 7
	s_lshl_b32 s13, s13, 5
	s_waitcnt lgkmcnt(7)
	v_mov_b32_e32 v48, v52
	s_waitcnt lgkmcnt(6)
	v_mov_b32_e32 v49, v54
	s_waitcnt lgkmcnt(5)
	v_mov_b32_e32 v50, v56
	s_waitcnt lgkmcnt(4)
	v_mov_b32_e32 v51, v58
	v_or_b32_e32 v39, s0, v193
	s_and_b32 s13, s13, 0x1fc0
	s_add_i32 s13, s13, s12
	v_lshlrev_b32_e32 v39, 6, v39
	s_movk_i32 s12, 0x31c0
	s_waitcnt lgkmcnt(1)
	v_mov_b32_e32 v68, v64
	s_waitcnt lgkmcnt(0)
	v_mov_b32_e32 v69, v66
	v_and_or_b32 v39, v39, s12, v1
	s_lshl_b32 s12, s13, 15
	v_readlane_b32 s13, v255, 13
	s_add_u32 s12, s13, s12
	v_readlane_b32 s13, v255, 14
	s_addc_u32 s13, s13, 0
	v_lshlrev_b32_e32 v39, 1, v39
	v_mov_b32_e32 v54, v53
	v_mov_b32_e32 v58, v57
	v_mov_b32_e32 v66, v65
	s_movk_i32 s14, 0x33c0
	ds_read2_b32 v[56:57], v21 offset0:146 offset1:154
	s_waitcnt vmcnt(1)
	v_pk_mul_f32 v[48:49], v[6:7], v[48:49]
	v_pk_mul_f32 v[50:51], v[8:9], v[50:51]
	v_cvt_pk_bf16_f32 v48, v48, v49
	v_cvt_pk_bf16_f32 v49, v50, v51
	v_mov_b32_e32 v50, v60
	v_mov_b32_e32 v51, v62
	s_waitcnt vmcnt(0)
	v_pk_mul_f32 v[50:51], v[2:3], v[50:51]
	v_pk_mul_f32 v[68:69], v[4:5], v[68:69]
	v_cvt_pk_bf16_f32 v50, v50, v51
	v_cvt_pk_bf16_f32 v51, v68, v69
	global_store_dwordx4 v39, v[48:51], s[12:13] nt
	v_or_b32_e32 v39, s0, v40
	v_mov_b32_e32 v62, v61
	v_pk_mul_f32 v[48:49], v[6:7], v[54:55]
	v_pk_mul_f32 v[50:51], v[8:9], v[58:59]
	v_lshlrev_b32_e32 v39, 6, v39
	v_cvt_pk_bf16_f32 v48, v48, v49
	v_cvt_pk_bf16_f32 v49, v50, v51
	v_pk_mul_f32 v[50:51], v[2:3], v[62:63]
	v_pk_mul_f32 v[52:53], v[4:5], v[66:67]
	v_and_or_b32 v39, v39, s14, v1
	v_cvt_pk_bf16_f32 v50, v50, v51
	v_cvt_pk_bf16_f32 v51, v52, v53
	ds_read2_b32 v[52:53], v21 offset0:16 offset1:24
	ds_read2_b32 v[54:55], v21 offset0:81 offset1:89
	v_lshlrev_b32_e32 v39, 1, v39
	ds_read2_b32 v[58:59], v21 offset0:211 offset1:219
	global_store_dwordx4 v39, v[48:51], s[12:13] nt
	ds_read2_b32 v[60:61], v37 offset0:20 offset1:28
	ds_read2_b32 v[62:63], v37 offset0:85 offset1:93
	ds_read2_b32 v[64:65], v37 offset0:150 offset1:158
	ds_read2_b32 v[66:67], v37 offset0:215 offset1:223
	s_waitcnt lgkmcnt(6)
	v_mov_b32_e32 v48, v52
	s_waitcnt lgkmcnt(5)
	v_mov_b32_e32 v49, v54
	v_mov_b32_e32 v50, v56
	s_waitcnt lgkmcnt(4)
	v_mov_b32_e32 v51, v58
	v_pk_mul_f32 v[48:49], v[6:7], v[48:49]
	v_pk_mul_f32 v[50:51], v[8:9], v[50:51]
	v_or_b32_e32 v39, s0, v41
	v_cvt_pk_bf16_f32 v48, v48, v49
	v_cvt_pk_bf16_f32 v49, v50, v51
	s_waitcnt lgkmcnt(3)
	v_mov_b32_e32 v50, v60
	s_waitcnt lgkmcnt(2)
	v_mov_b32_e32 v51, v62
	s_waitcnt lgkmcnt(1)
	v_mov_b32_e32 v68, v64
	s_waitcnt lgkmcnt(0)
; #define LAS __attribute__((address_space(3)))
; __host__ __device__ __forceinline__ size_t blk(int r, int k, int K) { return (((size_t)((r >> 8) * (K >> 6) + (k >> 6))) << 14) + (size_t)(((r & 255) << 6) + (k & 63)); }
; __device__ __forceinline__ unsigned pk2(float lo, float hi) { f32x2 v = {lo, hi}; bf16x2_t b = __builtin_convertvector(v, bf16x2_t); return __builtin_bit_cast(unsigned, b); }
; template <bool GAIN = false>
; __device__ __forceinline__ void tr_item(const float* W, size_t ldw, int k0, int c0, bf16* WT, int nd0, int K, LAS float* scr, int lane, const float* gk = nullptr, int kd0 = -1) {
;     ...
;     for (int j = 0; j < 8; ++j) { const int n = (lane >> 3) + 8 * j; const LAS float* s = scr + (8 * c) * 65 + n;
;         u32x4 o; o.x = pk2(s[0 * 65] * g0.x, s[1 * 65] * g0.y); o.y = pk2(s[2 * 65] * g0.z, s[3 * 65] * g0.w); o.z = pk2(s[4 * 65] * g1.x, s[5 * 65] * g1.y); o.w = pk2(s[6 * 65] * g1.z, s[7 * 65] * g1.w);
;         *(u32x4*)(WT + blk(nd0 + n, kd0 + 8 * c, K)) = o; }
	v_mov_b32_e32 v69, v66
	v_lshlrev_b32_e32 v39, 6, v39
	s_movk_i32 s14, 0x35c0
	v_pk_mul_f32 v[50:51], v[2:3], v[50:51]
	v_pk_mul_f32 v[68:69], v[4:5], v[68:69]
	v_and_or_b32 v39, v39, s14, v1
	v_cvt_pk_bf16_f32 v50, v50, v51
	v_cvt_pk_bf16_f32 v51, v68, v69
	v_lshlrev_b32_e32 v39, 1, v39
	global_store_dwordx4 v39, v[48:51], s[12:13] nt
	v_mov_b32_e32 v54, v53
	v_mov_b32_e32 v58, v57
	v_or_b32_e32 v39, s0, v42
	v_pk_mul_f32 v[48:49], v[6:7], v[54:55]
	v_pk_mul_f32 v[50:51], v[8:9], v[58:59]
	v_mov_b32_e32 v62, v61
	v_mov_b32_e32 v66, v65
	v_lshlrev_b32_e32 v39, 6, v39
	s_movk_i32 s14, 0x37c0
	v_cvt_pk_bf16_f32 v48, v48, v49
	v_cvt_pk_bf16_f32 v49, v50, v51
	v_pk_mul_f32 v[50:51], v[2:3], v[62:63]
	v_pk_mul_f32 v[52:53], v[4:5], v[66:67]
	v_and_or_b32 v39, v39, s14, v1
	v_cvt_pk_bf16_f32 v50, v50, v51
	v_cvt_pk_bf16_f32 v51, v52, v53
	ds_read2_b32 v[52:53], v21 offset0:32 offset1:40
	ds_read2_b32 v[54:55], v21 offset0:97 offset1:105
	v_lshlrev_b32_e32 v39, 1, v39
	ds_read2_b32 v[56:57], v21 offset0:162 offset1:170
	ds_read2_b32 v[58:59], v21 offset0:227 offset1:235
	global_store_dwordx4 v39, v[48:51], s[12:13] nt
	ds_read2_b32 v[60:61], v37 offset0:36 offset1:44
	ds_read2_b32 v[62:63], v37 offset0:101 offset1:109
	ds_read2_b32 v[64:65], v37 offset0:166 offset1:174
	ds_read2_b32 v[66:67], v37 offset0:231 offset1:239
	s_waitcnt lgkmcnt(7)
	v_mov_b32_e32 v48, v52
	s_waitcnt lgkmcnt(6)
	v_mov_b32_e32 v49, v54
	s_waitcnt lgkmcnt(5)
	v_mov_b32_e32 v50, v56
	s_waitcnt lgkmcnt(4)
	v_mov_b32_e32 v51, v58
	v_pk_mul_f32 v[48:49], v[6:7], v[48:49]
	v_pk_mul_f32 v[50:51], v[8:9], v[50:51]
	v_or_b32_e32 v39, s0, v43
	v_cvt_pk_bf16_f32 v48, v48, v49
	v_cvt_pk_bf16_f32 v49, v50, v51
	s_waitcnt lgkmcnt(3)
	v_mov_b32_e32 v50, v60
	s_waitcnt lgkmcnt(2)
	v_mov_b32_e32 v51, v62
	s_waitcnt lgkmcnt(1)
	v_mov_b32_e32 v68, v64
	s_waitcnt lgkmcnt(0)
	v_mov_b32_e32 v69, v66
	v_lshlrev_b32_e32 v39, 6, v39
	s_movk_i32 s14, 0x39c0
	v_pk_mul_f32 v[50:51], v[2:3], v[50:51]
	v_pk_mul_f32 v[68:69], v[4:5], v[68:69]
	v_and_or_b32 v39, v39, s14, v1
	v_cvt_pk_bf16_f32 v50, v50, v51
	v_cvt_pk_bf16_f32 v51, v68, v69
	v_lshlrev_b32_e32 v39, 1, v39
	v_mov_b32_e32 v54, v53
	v_mov_b32_e32 v58, v57
	global_store_dwordx4 v39, v[48:51], s[12:13] nt
	v_mov_b32_e32 v62, v61
	v_mov_b32_e32 v66, v65
	v_pk_mul_f32 v[48:49], v[6:7], v[54:55]
	v_pk_mul_f32 v[50:51], v[8:9], v[58:59]
	v_or_b32_e32 v39, s0, v44
	v_cvt_pk_bf16_f32 v48, v48, v49
	v_cvt_pk_bf16_f32 v49, v50, v51
	v_pk_mul_f32 v[50:51], v[2:3], v[62:63]
	v_pk_mul_f32 v[52:53], v[4:5], v[66:67]
	v_lshlrev_b32_e32 v39, 6, v39
	s_movk_i32 s14, 0x3bc0
	v_cvt_pk_bf16_f32 v50, v50, v51
	v_cvt_pk_bf16_f32 v51, v52, v53
	ds_read2_b32 v[52:53], v21 offset0:48 offset1:56
	v_and_or_b32 v39, v39, s14, v1
	ds_read2_b32 v[54:55], v21 offset0:113 offset1:121
	ds_read2_b32 v[56:57], v21 offset0:178 offset1:186
	ds_read2_b32 v[58:59], v21 offset0:243 offset1:251
	v_lshlrev_b32_e32 v39, 1, v39
	global_store_dwordx4 v39, v[48:51], s[12:13] nt
	ds_read2_b32 v[60:61], v37 offset0:52 offset1:60
	ds_read2_b32 v[62:63], v37 offset0:117 offset1:125
	ds_read2_b32 v[64:65], v37 offset0:182 offset1:190
	ds_read2_b32 v[66:67], v37 offset0:247 offset1:255
	s_waitcnt lgkmcnt(7)
	v_mov_b32_e32 v48, v52
	s_waitcnt lgkmcnt(6)
	v_mov_b32_e32 v49, v54
	s_waitcnt lgkmcnt(5)
	v_mov_b32_e32 v50, v56
	s_waitcnt lgkmcnt(4)
	v_mov_b32_e32 v51, v58
	v_pk_mul_f32 v[48:49], v[6:7], v[48:49]
	v_pk_mul_f32 v[50:51], v[8:9], v[50:51]
	v_cvt_pk_bf16_f32 v48, v48, v49
	v_cvt_pk_bf16_f32 v49, v50, v51
	s_waitcnt lgkmcnt(3)
	v_mov_b32_e32 v50, v60
	s_waitcnt lgkmcnt(2)
	v_mov_b32_e32 v51, v62
	v_mov_b32_e32 v54, v53
	v_mov_b32_e32 v58, v57
	v_mov_b32_e32 v62, v61
	v_pk_mul_f32 v[50:51], v[2:3], v[50:51]
	s_waitcnt lgkmcnt(0)
	v_mov_b32_e32 v69, v66
	v_pk_mul_f32 v[6:7], v[6:7], v[54:55]
	v_pk_mul_f32 v[8:9], v[8:9], v[58:59]
	v_pk_mul_f32 v[2:3], v[2:3], v[62:63]
	v_mov_b32_e32 v66, v65
	v_cvt_pk_bf16_f32 v6, v6, v7
	v_cvt_pk_bf16_f32 v7, v8, v9
	v_cvt_pk_bf16_f32 v8, v2, v3
	v_pk_mul_f32 v[2:3], v[4:5], v[66:67]
	v_or_b32_e32 v39, s0, v45
	v_cvt_pk_bf16_f32 v9, v2, v3
	v_or_b32_e32 v2, s0, v46
	v_mov_b32_e32 v68, v64
	v_lshlrev_b32_e32 v39, 6, v39
	s_movk_i32 s14, 0x3dc0
	v_lshlrev_b32_e32 v2, 6, v2
	s_movk_i32 s0, 0x3fc0
	v_pk_mul_f32 v[68:69], v[4:5], v[68:69]
	v_and_or_b32 v39, v39, s14, v1
	v_and_or_b32 v2, v2, s0, v1
	v_cvt_pk_bf16_f32 v50, v50, v51
	v_cvt_pk_bf16_f32 v51, v68, v69
	v_lshlrev_b32_e32 v39, 1, v39
	v_lshlrev_b32_e32 v2, 1, v2
	global_store_dwordx4 v39, v[48:51], s[12:13] nt
	global_store_dwordx4 v2, v[6:9], s[12:13] nt
	s_waitcnt lgkmcnt(0)

; #define LAS __attribute__((address_space(3)))
; template <bool GAIN = false>
; __device__ __forceinline__ void tr_item(const float* W, size_t ldw, int k0, int c0, bf16* WT, int nd0, int K, LAS float* scr, int lane, const float* gk = nullptr, int kd0 = -1) {
;     ...
;     for (int i = 0; i < 64; ++i) scr[i * 65 + lane] = __builtin_nontemporal_load(W + (size_t)(k0 + i) * ldw + c0 + lane);
; template <bool GAIN = false>
; __device__ __forceinline__ void tr_w13(const float* W, int which, bf16* WT, LAS float* scr, int item, int lane, const float* gk = nullptr) {
;     const int nblk = FF / 64, kb = item / nblk, nb = item % nblk, n0 = 64 * nb;
;     tr_item<GAIN>(W, FF, 64 * kb, n0, WT, (n0 >> 7) * 256 + which * 128 + (n0 & 127), D, scr, lane, gk);
.LBB0_39:
	s_andn2_b64 vcc, exec, s[12:13]
	s_cbranch_vccnz .LBB0_28
	s_mul_hi_i32 s0, s50, 0x2fa0be83
	s_lshr_b32 s12, s0, 31
	s_ashr_i32 s0, s0, 5
	s_add_i32 s0, s0, s12
	s_mul_i32 s12, s0, 0xffffd500
	s_add_i32 s12, s24, s12
	s_lshl_b32 s14, s0, 6
	s_ashr_i32 s13, s12, 31
	v_lshl_add_u64 v[2:3], s[12:13], 2, v[18:19]
	s_or_b32 s13, s14, 1
	v_mad_i64_i32 v[6:7], vcc, s13, v38, v[2:3]
	s_or_b32 s13, s14, 2
	v_mad_i64_i32 v[8:9], vcc, s13, v38, v[2:3]
	s_or_b32 s13, s14, 3
	v_mad_i64_i32 v[48:49], vcc, s13, v38, v[2:3]
	s_or_b32 s13, s14, 4
	v_mad_i64_i32 v[50:51], vcc, s13, v38, v[2:3]
	s_or_b32 s13, s14, 5
	v_mad_i64_i32 v[52:53], vcc, s13, v38, v[2:3]
	s_or_b32 s13, s14, 6
	v_mad_i64_i32 v[54:55], vcc, s13, v38, v[2:3]
	s_or_b32 s13, s14, 7
	v_mad_i64_i32 v[4:5], vcc, s14, v38, v[2:3]
	v_mad_i64_i32 v[56:57], vcc, s13, v38, v[2:3]
	s_or_b32 s13, s14, 8
	global_load_dword v39, v[4:5], off nt
	global_load_dword v47, v[6:7], off nt
	global_load_dword v58, v[8:9], off nt
	global_load_dword v59, v[48:49], off nt
	global_load_dword v60, v[50:51], off nt
	global_load_dword v61, v[52:53], off nt
	global_load_dword v62, v[54:55], off nt
	global_load_dword v63, v[56:57], off nt
	v_mad_i64_i32 v[4:5], vcc, s13, v38, v[2:3]
	s_or_b32 s13, s14, 9
	v_mad_i64_i32 v[6:7], vcc, s13, v38, v[2:3]
	s_or_b32 s13, s14, 10
	v_mad_i64_i32 v[8:9], vcc, s13, v38, v[2:3]
	s_or_b32 s13, s14, 11
	v_mad_i64_i32 v[48:49], vcc, s13, v38, v[2:3]
	s_or_b32 s13, s14, 12
	v_mad_i64_i32 v[50:51], vcc, s13, v38, v[2:3]
	s_or_b32 s13, s14, 13
	v_mad_i64_i32 v[52:53], vcc, s13, v38, v[2:3]
	s_or_b32 s13, s14, 14
	v_mad_i64_i32 v[54:55], vcc, s13, v38, v[2:3]
	s_or_b32 s13, s14, 15
	v_mad_i64_i32 v[56:57], vcc, s13, v38, v[2:3]
	s_or_b32 s13, s14, 16
	global_load_dword v64, v[4:5], off nt
	global_load_dword v65, v[6:7], off nt
	global_load_dword v66, v[8:9], off nt
	global_load_dword v67, v[48:49], off nt
	global_load_dword v68, v[50:51], off nt
	global_load_dword v69, v[52:53], off nt
	global_load_dword v70, v[54:55], off nt
	global_load_dword v71, v[56:57], off nt
	v_mad_i64_i32 v[4:5], vcc, s13, v38, v[2:3]
	s_or_b32 s13, s14, 17
	v_mad_i64_i32 v[6:7], vcc, s13, v38, v[2:3]
	s_or_b32 s13, s14, 18
	v_mad_i64_i32 v[8:9], vcc, s13, v38, v[2:3]
	s_or_b32 s13, s14, 19
	v_mad_i64_i32 v[48:49], vcc, s13, v38, v[2:3]
	s_or_b32 s13, s14, 20
	v_mad_i64_i32 v[50:51], vcc, s13, v38, v[2:3]
	s_or_b32 s13, s14, 21
	v_mad_i64_i32 v[52:53], vcc, s13, v38, v[2:3]
	s_or_b32 s13, s14, 22
	v_mad_i64_i32 v[54:55], vcc, s13, v38, v[2:3]
	s_or_b32 s13, s14, 23
	v_mad_i64_i32 v[56:57], vcc, s13, v38, v[2:3]
	s_or_b32 s13, s14, 24
	global_load_dword v72, v[4:5], off nt
	global_load_dword v73, v[6:7], off nt
	global_load_dword v74, v[8:9], off nt
	global_load_dword v75, v[48:49], off nt
	global_load_dword v76, v[50:51], off nt
	global_load_dword v77, v[52:53], off nt
	global_load_dword v78, v[54:55], off nt
	global_load_dword v79, v[56:57], off nt
	v_mad_i64_i32 v[4:5], vcc, s13, v38, v[2:3]
	s_or_b32 s13, s14, 25
	v_mad_i64_i32 v[6:7], vcc, s13, v38, v[2:3]
	s_or_b32 s13, s14, 26
	v_mad_i64_i32 v[8:9], vcc, s13, v38, v[2:3]
	s_or_b32 s13, s14, 27
	v_mad_i64_i32 v[48:49], vcc, s13, v38, v[2:3]
	s_or_b32 s13, s14, 28
	v_mad_i64_i32 v[50:51], vcc, s13, v38, v[2:3]
	s_or_b32 s13, s14, 29
	v_mad_i64_i32 v[52:53], vcc, s13, v38, v[2:3]
	s_or_b32 s13, s14, 30
	v_mad_i64_i32 v[54:55], vcc, s13, v38, v[2:3]
	s_or_b32 s13, s14, 31
	v_mad_i64_i32 v[56:57], vcc, s13, v38, v[2:3]
	s_or_b32 s13, s14, 32
	global_load_dword v80, v[4:5], off nt
	global_load_dword v81, v[6:7], off nt
	global_load_dword v82, v[8:9], off nt
	global_load_dword v83, v[48:49], off nt
	global_load_dword v84, v[50:51], off nt
	global_load_dword v85, v[52:53], off nt
	global_load_dword v86, v[54:55], off nt
	global_load_dword v87, v[56:57], off nt
	v_mad_i64_i32 v[4:5], vcc, s13, v38, v[2:3]
	s_or_b32 s13, s14, 33
	v_mad_i64_i32 v[6:7], vcc, s13, v38, v[2:3]
	s_or_b32 s13, s14, 34
	v_mad_i64_i32 v[8:9], vcc, s13, v38, v[2:3]
	s_or_b32 s13, s14, 35
	v_mad_i64_i32 v[48:49], vcc, s13, v38, v[2:3]
	s_or_b32 s13, s14, 36
	v_mad_i64_i32 v[50:51], vcc, s13, v38, v[2:3]
	s_or_b32 s13, s14, 37
	v_mad_i64_i32 v[52:53], vcc, s13, v38, v[2:3]
	s_or_b32 s13, s14, 38
	v_mad_i64_i32 v[54:55], vcc, s13, v38, v[2:3]
	s_or_b32 s13, s14, 39
	v_mad_i64_i32 v[56:57], vcc, s13, v38, v[2:3]
	s_or_b32 s13, s14, 40
	global_load_dword v88, v[4:5], off nt
	global_load_dword v89, v[6:7], off nt
	global_load_dword v90, v[8:9], off nt
	global_load_dword v91, v[48:49], off nt
	global_load_dword v92, v[50:51], off nt
	global_load_dword v93, v[52:53], off nt
	global_load_dword v94, v[54:55], off nt
	global_load_dword v95, v[56:57], off nt
	v_mad_i64_i32 v[4:5], vcc, s13, v38, v[2:3]
	s_or_b32 s13, s14, 41
	v_mad_i64_i32 v[6:7], vcc, s13, v38, v[2:3]
	s_or_b32 s13, s14, 42
	v_mad_i64_i32 v[8:9], vcc, s13, v38, v[2:3]
	s_or_b32 s13, s14, 43
	v_mad_i64_i32 v[48:49], vcc, s13, v38, v[2:3]
	s_or_b32 s13, s14, 44
	v_mad_i64_i32 v[50:51], vcc, s13, v38, v[2:3]
	s_or_b32 s13, s14, 45
	v_mad_i64_i32 v[52:53], vcc, s13, v38, v[2:3]
	s_or_b32 s13, s14, 46
	v_mad_i64_i32 v[54:55], vcc, s13, v38, v[2:3]
	s_or_b32 s13, s14, 47
	v_mad_i64_i32 v[56:57], vcc, s13, v38, v[2:3]
	s_or_b32 s13, s14, 48
	global_load_dword v96, v[4:5], off nt
	global_load_dword v97, v[6:7], off nt
	global_load_dword v98, v[8:9], off nt
	global_load_dword v99, v[48:49], off nt
	global_load_dword v100, v[50:51], off nt
	global_load_dword v101, v[52:53], off nt
	global_load_dword v102, v[54:55], off nt
	global_load_dword v103, v[56:57], off nt
	v_mad_i64_i32 v[4:5], vcc, s13, v38, v[2:3]
	s_or_b32 s13, s14, 49
; #define LAS __attribute__((address_space(3)))
; __host__ __device__ __forceinline__ size_t blk(int r, int k, int K) { return (((size_t)((r >> 8) * (K >> 6) + (k >> 6))) << 14) + (size_t)(((r & 255) << 6) + (k & 63)); }
; __device__ __forceinline__ unsigned pk2(float lo, float hi) { f32x2 v = {lo, hi}; bf16x2_t b = __builtin_convertvector(v, bf16x2_t); return __builtin_bit_cast(unsigned, b); }
; template <bool GAIN = false>
; __device__ __forceinline__ void tr_item(const float* W, size_t ldw, int k0, int c0, bf16* WT, int nd0, int K, LAS float* scr, int lane, const float* gk = nullptr, int kd0 = -1) {
;     ...
;     for (int i = 0; i < 64; ++i) scr[i * 65 + lane] = __builtin_nontemporal_load(W + (size_t)(k0 + i) * ldw + c0 + lane);
;     asm volatile("s_waitcnt lgkmcnt(0)" ::: "memory");
;     const int c = lane & 7;
;     f32x4 g0 = {1.f, 1.f, 1.f, 1.f}, g1 = g0;
;     if (GAIN) { g0 = *(const f32x4*)(gk + k0 + 8 * c); g1 = *(const f32x4*)(gk + k0 + 8 * c + 4); }
; #pragma unroll
;     for (int j = 0; j < 8; ++j) { const int n = (lane >> 3) + 8 * j; const LAS float* s = scr + (8 * c) * 65 + n;
;         u32x4 o; o.x = pk2(s[0 * 65] * g0.x, s[1 * 65] * g0.y); o.y = pk2(s[2 * 65] * g0.z, s[3 * 65] * g0.w); o.z = pk2(s[4 * 65] * g1.x, s[5 * 65] * g1.y); o.w = pk2(s[6 * 65] * g1.z, s[7 * 65] * g1.w);
;         *(u32x4*)(WT + blk(nd0 + n, kd0 + 8 * c, K)) = o; }
	v_mad_i64_i32 v[6:7], vcc, s13, v38, v[2:3]
	s_or_b32 s13, s14, 50
	v_mad_i64_i32 v[8:9], vcc, s13, v38, v[2:3]
	s_or_b32 s13, s14, 51
	v_mad_i64_i32 v[48:49], vcc, s13, v38, v[2:3]
	s_or_b32 s13, s14, 52
	v_mad_i64_i32 v[50:51], vcc, s13, v38, v[2:3]
	s_or_b32 s13, s14, 53
	v_mad_i64_i32 v[52:53], vcc, s13, v38, v[2:3]
	s_or_b32 s13, s14, 54
	v_mad_i64_i32 v[54:55], vcc, s13, v38, v[2:3]
	s_or_b32 s13, s14, 55
	v_mad_i64_i32 v[56:57], vcc, s13, v38, v[2:3]
	s_or_b32 s13, s14, 56
	global_load_dword v104, v[4:5], off nt
	global_load_dword v105, v[6:7], off nt
	global_load_dword v106, v[8:9], off nt
	global_load_dword v107, v[48:49], off nt
	global_load_dword v108, v[50:51], off nt
	global_load_dword v109, v[52:53], off nt
	global_load_dword v110, v[54:55], off nt
	s_nop 0
	global_load_dword v56, v[56:57], off nt
	v_mad_i64_i32 v[4:5], vcc, s13, v38, v[2:3]
	s_or_b32 s13, s14, 57
	v_mad_i64_i32 v[6:7], vcc, s13, v38, v[2:3]
	s_or_b32 s13, s14, 58
	v_mad_i64_i32 v[8:9], vcc, s13, v38, v[2:3]
	s_or_b32 s13, s14, 59
	v_mad_i64_i32 v[48:49], vcc, s13, v38, v[2:3]
	s_or_b32 s13, s14, 60
	v_mad_i64_i32 v[50:51], vcc, s13, v38, v[2:3]
	s_or_b32 s13, s14, 61
	v_mad_i64_i32 v[52:53], vcc, s13, v38, v[2:3]
	s_or_b32 s13, s14, 62
	v_mad_i64_i32 v[54:55], vcc, s13, v38, v[2:3]
	s_or_b32 s13, s14, 63
	v_mad_i64_i32 v[2:3], vcc, s13, v38, v[2:3]
	global_load_dword v4, v[4:5], off nt
	s_nop 0
	global_load_dword v5, v[6:7], off nt
	s_nop 0
	global_load_dword v6, v[8:9], off nt
	global_load_dword v7, v[48:49], off nt
	s_nop 0
	global_load_dword v8, v[50:51], off nt
	global_load_dword v9, v[52:53], off nt
	global_load_dword v48, v[54:55], off nt
	s_nop 0
	global_load_dword v2, v[2:3], off nt
	s_ashr_i32 s15, s14, 31
	s_waitcnt vmcnt(62)
	ds_write2_b32 v20, v39, v47 offset1:65
	s_waitcnt vmcnt(60)
	ds_write2_b32 v20, v58, v59 offset0:130 offset1:195
	s_waitcnt vmcnt(58)
	ds_write2_b32 v22, v60, v61 offset0:4 offset1:69
	s_waitcnt vmcnt(56)
	ds_write2_b32 v22, v62, v63 offset0:134 offset1:199
	s_waitcnt vmcnt(54)
	ds_write2_b32 v23, v64, v65 offset0:8 offset1:73
	s_waitcnt vmcnt(52)
	ds_write2_b32 v23, v66, v67 offset0:138 offset1:203
	s_waitcnt vmcnt(50)
	ds_write2_b32 v24, v68, v69 offset0:12 offset1:77
	s_waitcnt vmcnt(48)
	ds_write2_b32 v24, v70, v71 offset0:142 offset1:207
	s_waitcnt vmcnt(46)
	ds_write2_b32 v25, v72, v73 offset0:16 offset1:81
	s_waitcnt vmcnt(44)
	ds_write2_b32 v25, v74, v75 offset0:146 offset1:211
	s_waitcnt vmcnt(42)
	ds_write2_b32 v26, v76, v77 offset0:20 offset1:85
	s_waitcnt vmcnt(40)
	ds_write2_b32 v26, v78, v79 offset0:150 offset1:215
	s_waitcnt vmcnt(38)
	ds_write2_b32 v27, v80, v81 offset0:24 offset1:89
	s_waitcnt vmcnt(36)
	ds_write2_b32 v27, v82, v83 offset0:154 offset1:219
	s_waitcnt vmcnt(34)
	ds_write2_b32 v28, v84, v85 offset0:28 offset1:93
	s_waitcnt vmcnt(32)
	ds_write2_b32 v28, v86, v87 offset0:158 offset1:223
	s_waitcnt vmcnt(30)
	ds_write2_b32 v29, v88, v89 offset0:32 offset1:97
	s_waitcnt vmcnt(28)
	ds_write2_b32 v29, v90, v91 offset0:162 offset1:227
	s_waitcnt vmcnt(26)
	ds_write2_b32 v30, v92, v93 offset0:36 offset1:101
	s_waitcnt vmcnt(24)
	ds_write2_b32 v30, v94, v95 offset0:166 offset1:231
	s_waitcnt vmcnt(22)
	ds_write2_b32 v31, v96, v97 offset0:40 offset1:105
	s_waitcnt vmcnt(20)
	ds_write2_b32 v31, v98, v99 offset0:170 offset1:235
	s_waitcnt vmcnt(18)
	ds_write2_b32 v32, v100, v101 offset0:44 offset1:109
	s_waitcnt vmcnt(16)
	ds_write2_b32 v32, v102, v103 offset0:174 offset1:239
	s_waitcnt vmcnt(14)
	ds_write2_b32 v33, v104, v105 offset0:48 offset1:113
	s_waitcnt vmcnt(12)
	ds_write2_b32 v33, v106, v107 offset0:178 offset1:243
	s_waitcnt vmcnt(10)
	ds_write2_b32 v34, v108, v109 offset0:52 offset1:117
	s_waitcnt vmcnt(8)
	ds_write2_b32 v34, v110, v56 offset0:182 offset1:247
	s_waitcnt vmcnt(6)
	ds_write2_b32 v35, v4, v5 offset0:56 offset1:121
	s_waitcnt vmcnt(4)
	ds_write2_b32 v35, v6, v7 offset0:186 offset1:251
	s_waitcnt vmcnt(2)
	ds_write2_b32 v36, v8, v9 offset0:60 offset1:125
	s_waitcnt vmcnt(0)
	ds_write2_b32 v36, v48, v2 offset0:190 offset1:255
	s_waitcnt lgkmcnt(0)
	v_lshl_add_u64 v[2:3], s[14:15], 2, v[16:17]
	global_load_dwordx4 v[6:9], v[2:3], off
	s_nop 0
	global_load_dwordx4 v[2:5], v[2:3], off offset:16
	ds_read2_b32 v[52:53], v21 offset1:8
	ds_read2_b32 v[54:55], v21 offset0:65 offset1:73
	ds_read2_b32 v[56:57], v21 offset0:130 offset1:138
	ds_read2_b32 v[58:59], v21 offset0:195 offset1:203
	s_and_b32 s14, s12, 64
	ds_read2_b32 v[60:61], v37 offset0:4 offset1:12
	ds_read2_b32 v[62:63], v37 offset0:69 offset1:77
	ds_read2_b32 v[64:65], v37 offset0:134 offset1:142
	ds_read2_b32 v[66:67], v37 offset0:199 offset1:207
	s_mul_i32 s12, s0, 0xffffea80
	s_add_i32 s12, s29, s12
	s_andn2_b32 s12, s12, 63
	s_waitcnt lgkmcnt(7)
	v_mov_b32_e32 v48, v52
	s_waitcnt lgkmcnt(6)
	v_mov_b32_e32 v49, v54
	s_waitcnt lgkmcnt(5)
	v_mov_b32_e32 v50, v56
	s_waitcnt lgkmcnt(4)
	v_mov_b32_e32 v51, v58
	s_add_i32 s12, s12, s0
	s_ashr_i32 s13, s12, 31
	s_waitcnt lgkmcnt(1)
	v_mov_b32_e32 v68, v64
	s_waitcnt lgkmcnt(0)
	v_mov_b32_e32 v69, v66
	s_lshl_b64 s[12:13], s[12:13], 15
	v_readlane_b32 s0, v255, 13
	v_or_b32_e32 v39, s14, v193
	s_add_u32 s12, s0, s12
	v_readlane_b32 s0, v255, 14
	v_lshlrev_b32_e32 v47, 1, v1
	s_addc_u32 s13, s0, s13
	v_lshl_or_b32 v39, v39, 7, v47
	v_mov_b32_e32 v54, v53
	v_mov_b32_e32 v58, v57
	v_mov_b32_e32 v66, v65
	ds_read2_b32 v[56:57], v21 offset0:146 offset1:154
	s_movk_i32 s0, 0x15c0
	s_waitcnt vmcnt(1)
	v_pk_mul_f32 v[48:49], v[6:7], v[48:49]
	v_pk_mul_f32 v[50:51], v[8:9], v[50:51]
	v_cvt_pk_bf16_f32 v48, v48, v49
	v_cvt_pk_bf16_f32 v49, v50, v51
	v_mov_b32_e32 v50, v60
	v_mov_b32_e32 v51, v62
	s_waitcnt vmcnt(0)
; #define LAS __attribute__((address_space(3)))
; __host__ __device__ __forceinline__ size_t blk(int r, int k, int K) { return (((size_t)((r >> 8) * (K >> 6) + (k >> 6))) << 14) + (size_t)(((r & 255) << 6) + (k & 63)); }
; __device__ __forceinline__ unsigned pk2(float lo, float hi) { f32x2 v = {lo, hi}; bf16x2_t b = __builtin_convertvector(v, bf16x2_t); return __builtin_bit_cast(unsigned, b); }
; template <bool GAIN = false>
; __device__ __forceinline__ void tr_item(const float* W, size_t ldw, int k0, int c0, bf16* WT, int nd0, int K, LAS float* scr, int lane, const float* gk = nullptr, int kd0 = -1) {
;     ...
;     for (int j = 0; j < 8; ++j) { const int n = (lane >> 3) + 8 * j; const LAS float* s = scr + (8 * c) * 65 + n;
;         u32x4 o; o.x = pk2(s[0 * 65] * g0.x, s[1 * 65] * g0.y); o.y = pk2(s[2 * 65] * g0.z, s[3 * 65] * g0.w); o.z = pk2(s[4 * 65] * g1.x, s[5 * 65] * g1.y); o.w = pk2(s[6 * 65] * g1.z, s[7 * 65] * g1.w);
;         *(u32x4*)(WT + blk(nd0 + n, kd0 + 8 * c, K)) = o; }
	v_pk_mul_f32 v[50:51], v[2:3], v[50:51]
	v_pk_mul_f32 v[68:69], v[4:5], v[68:69]
	v_cvt_pk_bf16_f32 v50, v50, v51
	v_cvt_pk_bf16_f32 v51, v68, v69
	global_store_dwordx4 v39, v[48:51], s[12:13] nt
	v_mov_b32_e32 v62, v61
	v_pk_mul_f32 v[52:53], v[4:5], v[66:67]
	v_pk_mul_f32 v[48:49], v[6:7], v[54:55]
	v_pk_mul_f32 v[50:51], v[8:9], v[58:59]
	v_cvt_pk_bf16_f32 v48, v48, v49
	v_cvt_pk_bf16_f32 v49, v50, v51
	v_pk_mul_f32 v[50:51], v[2:3], v[62:63]
	v_or_b32_e32 v39, s14, v40
	v_cvt_pk_bf16_f32 v50, v50, v51
	v_cvt_pk_bf16_f32 v51, v52, v53
	ds_read2_b32 v[52:53], v21 offset0:16 offset1:24
	ds_read2_b32 v[54:55], v21 offset0:81 offset1:89
	v_lshl_or_b32 v39, v39, 7, v47
	ds_read2_b32 v[58:59], v21 offset0:211 offset1:219
	global_store_dwordx4 v39, v[48:51], s[12:13] nt
	ds_read2_b32 v[60:61], v37 offset0:20 offset1:28
	ds_read2_b32 v[62:63], v37 offset0:85 offset1:93
	ds_read2_b32 v[64:65], v37 offset0:150 offset1:158
	ds_read2_b32 v[66:67], v37 offset0:215 offset1:223
	s_waitcnt lgkmcnt(6)
	v_mov_b32_e32 v48, v52
	s_waitcnt lgkmcnt(5)
	v_mov_b32_e32 v49, v54
	v_mov_b32_e32 v50, v56
	s_waitcnt lgkmcnt(4)
	v_mov_b32_e32 v51, v58
	v_pk_mul_f32 v[48:49], v[6:7], v[48:49]
	v_pk_mul_f32 v[50:51], v[8:9], v[50:51]
	v_or_b32_e32 v39, s14, v41
	v_cvt_pk_bf16_f32 v48, v48, v49
	v_cvt_pk_bf16_f32 v49, v50, v51
	s_waitcnt lgkmcnt(3)
	v_mov_b32_e32 v50, v60
	s_waitcnt lgkmcnt(2)
	v_mov_b32_e32 v51, v62
	s_waitcnt lgkmcnt(1)
	v_mov_b32_e32 v68, v64
	s_waitcnt lgkmcnt(0)
	v_mov_b32_e32 v69, v66
	v_lshlrev_b32_e32 v39, 6, v39
	v_pk_mul_f32 v[50:51], v[2:3], v[50:51]
	v_pk_mul_f32 v[68:69], v[4:5], v[68:69]
	v_and_or_b32 v39, v39, s0, v1
	v_cvt_pk_bf16_f32 v50, v50, v51
	v_cvt_pk_bf16_f32 v51, v68, v69
	v_lshlrev_b32_e32 v39, 1, v39
	v_mov_b32_e32 v54, v53
	v_mov_b32_e32 v58, v57
	global_store_dwordx4 v39, v[48:51], s[12:13] nt
	v_mov_b32_e32 v62, v61
	v_mov_b32_e32 v66, v65
	v_pk_mul_f32 v[48:49], v[6:7], v[54:55]
	v_pk_mul_f32 v[50:51], v[8:9], v[58:59]
	v_cvt_pk_bf16_f32 v48, v48, v49
	v_cvt_pk_bf16_f32 v49, v50, v51
	v_pk_mul_f32 v[50:51], v[2:3], v[62:63]
	v_pk_mul_f32 v[52:53], v[4:5], v[66:67]
	v_or_b32_e32 v39, s14, v42
	v_cvt_pk_bf16_f32 v50, v50, v51
	v_cvt_pk_bf16_f32 v51, v52, v53
	ds_read2_b32 v[52:53], v21 offset0:32 offset1:40
	ds_read2_b32 v[54:55], v21 offset0:97 offset1:105
	v_lshl_or_b32 v39, v39, 7, v47
	ds_read2_b32 v[56:57], v21 offset0:162 offset1:170
	ds_read2_b32 v[58:59], v21 offset0:227 offset1:235
	global_store_dwordx4 v39, v[48:51], s[12:13] nt
	ds_read2_b32 v[60:61], v37 offset0:36 offset1:44
	ds_read2_b32 v[62:63], v37 offset0:101 offset1:109
	ds_read2_b32 v[64:65], v37 offset0:166 offset1:174
	ds_read2_b32 v[66:67], v37 offset0:231 offset1:239
	s_waitcnt lgkmcnt(7)
	v_mov_b32_e32 v48, v52
	s_waitcnt lgkmcnt(6)
	v_mov_b32_e32 v49, v54
	s_waitcnt lgkmcnt(5)
	v_mov_b32_e32 v50, v56
	s_waitcnt lgkmcnt(4)
	v_mov_b32_e32 v51, v58
	v_pk_mul_f32 v[48:49], v[6:7], v[48:49]
	v_pk_mul_f32 v[50:51], v[8:9], v[50:51]
	v_or_b32_e32 v39, s14, v43
	v_cvt_pk_bf16_f32 v48, v48, v49
	v_cvt_pk_bf16_f32 v49, v50, v51
	s_waitcnt lgkmcnt(3)
	v_mov_b32_e32 v50, v60
	s_waitcnt lgkmcnt(2)
	v_mov_b32_e32 v51, v62
	s_waitcnt lgkmcnt(1)
	v_mov_b32_e32 v68, v64
	s_waitcnt lgkmcnt(0)
	v_mov_b32_e32 v69, v66
	v_lshlrev_b32_e32 v39, 6, v39
	s_movk_i32 s0, 0x19c0
	v_pk_mul_f32 v[50:51], v[2:3], v[50:51]
	v_pk_mul_f32 v[68:69], v[4:5], v[68:69]
	v_and_or_b32 v39, v39, s0, v1
	v_cvt_pk_bf16_f32 v50, v50, v51
	v_cvt_pk_bf16_f32 v51, v68, v69
	v_lshlrev_b32_e32 v39, 1, v39
	v_mov_b32_e32 v54, v53
	v_mov_b32_e32 v58, v57
	global_store_dwordx4 v39, v[48:51], s[12:13] nt
	v_mov_b32_e32 v62, v61
	v_mov_b32_e32 v66, v65
	v_pk_mul_f32 v[48:49], v[6:7], v[54:55]
	v_pk_mul_f32 v[50:51], v[8:9], v[58:59]
	v_or_b32_e32 v39, s14, v44
	v_cvt_pk_bf16_f32 v48, v48, v49
	v_cvt_pk_bf16_f32 v49, v50, v51
	v_pk_mul_f32 v[50:51], v[2:3], v[62:63]
	v_pk_mul_f32 v[52:53], v[4:5], v[66:67]
	v_lshlrev_b32_e32 v39, 6, v39
	s_movk_i32 s0, 0x1bc0
	v_cvt_pk_bf16_f32 v50, v50, v51
	v_cvt_pk_bf16_f32 v51, v52, v53
	ds_read2_b32 v[52:53], v21 offset0:48 offset1:56
	v_and_or_b32 v39, v39, s0, v1
	ds_read2_b32 v[54:55], v21 offset0:113 offset1:121
	ds_read2_b32 v[56:57], v21 offset0:178 offset1:186
	ds_read2_b32 v[58:59], v21 offset0:243 offset1:251
	v_lshlrev_b32_e32 v39, 1, v39
	global_store_dwordx4 v39, v[48:51], s[12:13] nt
	ds_read2_b32 v[60:61], v37 offset0:52 offset1:60
	ds_read2_b32 v[62:63], v37 offset0:117 offset1:125
	ds_read2_b32 v[64:65], v37 offset0:182 offset1:190
	ds_read2_b32 v[66:67], v37 offset0:247 offset1:255
	s_waitcnt lgkmcnt(7)
	v_mov_b32_e32 v48, v52
	s_waitcnt lgkmcnt(6)
	v_mov_b32_e32 v49, v54
	s_waitcnt lgkmcnt(5)
	v_mov_b32_e32 v50, v56
	s_waitcnt lgkmcnt(4)
	v_mov_b32_e32 v51, v58
	v_pk_mul_f32 v[48:49], v[6:7], v[48:49]
	v_pk_mul_f32 v[50:51], v[8:9], v[50:51]
	v_cvt_pk_bf16_f32 v48, v48, v49
	v_cvt_pk_bf16_f32 v49, v50, v51
	s_waitcnt lgkmcnt(3)
	v_mov_b32_e32 v50, v60
	s_waitcnt lgkmcnt(2)
	v_mov_b32_e32 v51, v62
	v_mov_b32_e32 v54, v53
	v_mov_b32_e32 v58, v57
	v_mov_b32_e32 v62, v61
	v_pk_mul_f32 v[50:51], v[2:3], v[50:51]
	s_waitcnt lgkmcnt(0)
	v_mov_b32_e32 v69, v66
	v_or_b32_e32 v39, s14, v45
	v_pk_mul_f32 v[6:7], v[6:7], v[54:55]
	v_pk_mul_f32 v[8:9], v[8:9], v[58:59]
	v_pk_mul_f32 v[2:3], v[2:3], v[62:63]
	v_mov_b32_e32 v66, v65
	v_mov_b32_e32 v68, v64
	v_lshlrev_b32_e32 v39, 6, v39
	s_movk_i32 s0, 0x1dc0
	v_cvt_pk_bf16_f32 v6, v6, v7
	v_cvt_pk_bf16_f32 v7, v8, v9
	v_cvt_pk_bf16_f32 v8, v2, v3
	v_pk_mul_f32 v[2:3], v[4:5], v[66:67]
	v_pk_mul_f32 v[68:69], v[4:5], v[68:69]
	v_and_or_b32 v39, v39, s0, v1
	v_cvt_pk_bf16_f32 v9, v2, v3
	v_or_b32_e32 v2, s14, v46
	v_cvt_pk_bf16_f32 v50, v50, v51
	v_cvt_pk_bf16_f32 v51, v68, v69
	v_lshlrev_b32_e32 v39, 1, v39
	v_lshl_or_b32 v2, v2, 7, v47
	global_store_dwordx4 v39, v[48:51], s[12:13] nt
	global_store_dwordx4 v2, v[6:9], s[12:13] nt
	s_waitcnt lgkmcnt(0)
	s_branch .LBB0_28

;     const f32x4* xr = (const f32x4*)xrow + lane; const f32x4* gr = (const f32x4*)g + lane;
;     f32x4 v[16]; float s = 0.f;
; #pragma unroll
;     for (int j = 0; j < 16; ++j) { v[j] = __builtin_nontemporal_load(xr + 64 * j); s += (v[j].x * v[j].x + v[j].y * v[j].y) + (v[j].z * v[j].z + v[j].w * v[j].w); }
.LBB0_53:
	v_add_co_u32_e64 v82, s[0:1], s6, v126
	v_add_co_u32_e32 v128, vcc, 0xffffd000, v126
	s_nop 0
	v_addc_co_u32_e64 v83, s[0:1], -1, v127, s[0:1]
	v_add_co_u32_e64 v84, s[0:1], s7, v126
	global_load_dwordx4 v[2:5], v[126:127], off offset:-3072 nt
	global_load_dwordx4 v[6:9], v[126:127], off offset:-2048 nt
	global_load_dwordx4 v[10:13], v[126:127], off offset:-1024 nt
	global_load_dwordx4 v[14:17], v[126:127], off nt
	global_load_dwordx4 v[18:21], v[100:101], off
	global_load_dwordx4 v[22:25], v[100:101], off offset:1024
	global_load_dwordx4 v[26:29], v[100:101], off offset:2048
	global_load_dwordx4 v[30:33], v[100:101], off offset:3072
	global_load_dwordx4 v[34:37], v[102:103], off
	global_load_dwordx4 v[38:41], v[104:105], off
	global_load_dwordx4 v[42:45], v[106:107], off
	global_load_dwordx4 v[46:49], v[108:109], off
	global_load_dwordx4 v[50:53], v[110:111], off
	global_load_dwordx4 v[54:57], v[112:113], off
	global_load_dwordx4 v[58:61], v[114:115], off
	global_load_dwordx4 v[62:65], v[116:117], off
	global_load_dwordx4 v[66:69], v[118:119], off
	global_load_dwordx4 v[70:73], v[120:121], off
	global_load_dwordx4 v[74:77], v[122:123], off
	global_load_dwordx4 v[78:81], v[124:125], off
	v_addc_co_u32_e64 v85, s[0:1], -1, v127, s[0:1]
	global_load_dwordx4 v[170:173], v[82:83], off offset:-3072 nt
	global_load_dwordx4 v[174:177], v[82:83], off offset:-2048 nt
	global_load_dwordx4 v[180:183], v[82:83], off offset:-1024 nt
	global_load_dwordx4 v[184:187], v[82:83], off nt
	global_load_dwordx4 v[94:97], v[84:85], off offset:-3072 nt
	global_load_dwordx4 v[90:93], v[84:85], off offset:-2048 nt
	global_load_dwordx4 v[86:89], v[84:85], off offset:-1024 nt
	s_nop 0
	global_load_dwordx4 v[82:85], v[126:127], off offset:-4096 nt
	v_addc_co_u32_e32 v129, vcc, -1, v127, vcc
	global_load_dwordx4 v[188:191], v[128:129], off offset:-3072 nt
	global_load_dwordx4 v[196:199], v[128:129], off offset:-2048 nt
	global_load_dwordx4 v[200:203], v[128:129], off offset:-1024 nt
	global_load_dwordx4 v[204:207], v[128:129], off nt
	s_ashr_i32 s0, s13, 2
	s_andn2_b32 s0, s0, 63
	s_and_b32 s1, s3, 0x3fc0
	v_or_b32_e32 v128, s0, v160
	v_or_b32_e32 v98, s1, v1
	v_or_b32_e32 v130, 4, v128
	v_or_b32_e32 v132, 8, v128
	v_or_b32_e32 v134, 12, v128
	v_or_b32_e32 v136, 16, v128
	v_or_b32_e32 v138, 20, v128
	v_or_b32_e32 v140, 24, v128
	v_or_b32_e32 v142, 28, v128
	v_or_b32_e32 v144, 32, v128
	v_or_b32_e32 v146, 36, v128
	v_or_b32_e32 v148, 40, v128
	v_or_b32_e32 v150, 44, v128
	v_or_b32_e32 v152, 48, v128
	v_or_b32_e32 v154, 52, v128
	v_or_b32_e32 v156, 56, v128
	v_or_b32_e32 v208, 60, v128
	v_lshlrev_b32_e32 v98, 1, v98
	v_ashrrev_i32_e32 v129, 31, v128
	v_ashrrev_i32_e32 v131, 31, v130
	v_ashrrev_i32_e32 v133, 31, v132
	v_ashrrev_i32_e32 v135, 31, v134
	v_ashrrev_i32_e32 v137, 31, v136
	v_ashrrev_i32_e32 v139, 31, v138
	v_ashrrev_i32_e32 v141, 31, v140
	v_ashrrev_i32_e32 v143, 31, v142
	v_ashrrev_i32_e32 v145, 31, v144
	v_ashrrev_i32_e32 v147, 31, v146
	v_ashrrev_i32_e32 v149, 31, v148
	v_ashrrev_i32_e32 v151, 31, v150
	v_ashrrev_i32_e32 v153, 31, v152
	v_ashrrev_i32_e32 v155, 31, v154
	v_ashrrev_i32_e32 v157, 31, v156
	v_ashrrev_i32_e32 v209, 31, v208
	v_lshl_add_u64 v[158:159], s[66:67], 0, v[98:99]
	v_lshlrev_b64 v[128:129], 15, v[128:129]
	v_lshlrev_b64 v[130:131], 15, v[130:131]
	v_lshlrev_b64 v[132:133], 15, v[132:133]
	v_lshlrev_b64 v[134:135], 15, v[134:135]
	v_lshlrev_b64 v[136:137], 15, v[136:137]
	v_lshlrev_b64 v[138:139], 15, v[138:139]
	v_lshlrev_b64 v[140:141], 15, v[140:141]
	v_lshlrev_b64 v[142:143], 15, v[142:143]
	v_lshlrev_b64 v[144:145], 15, v[144:145]
	v_lshlrev_b64 v[146:147], 15, v[146:147]
	v_lshlrev_b64 v[148:149], 15, v[148:149]
	v_lshlrev_b64 v[150:151], 15, v[150:151]
	v_lshlrev_b64 v[152:153], 15, v[152:153]
	v_lshlrev_b64 v[154:155], 15, v[154:155]
	v_lshlrev_b64 v[156:157], 15, v[156:157]
	v_lshlrev_b64 v[208:209], 15, v[208:209]
	v_lshl_add_u64 v[128:129], v[158:159], 0, v[128:129]
	v_lshl_add_u64 v[130:131], v[158:159], 0, v[130:131]
	s_waitcnt vmcnt(29)
	v_mul_f32_e32 v98, v11, v11
	v_lshl_add_u64 v[132:133], v[158:159], 0, v[132:133]
	v_lshl_add_u64 v[134:135], v[158:159], 0, v[134:135]
	v_lshl_add_u64 v[136:137], v[158:159], 0, v[136:137]
	v_lshl_add_u64 v[138:139], v[158:159], 0, v[138:139]
	v_lshl_add_u64 v[140:141], v[158:159], 0, v[140:141]
	v_lshl_add_u64 v[142:143], v[158:159], 0, v[142:143]
	v_lshl_add_u64 v[144:145], v[158:159], 0, v[144:145]
	v_lshl_add_u64 v[146:147], v[158:159], 0, v[146:147]
	v_lshl_add_u64 v[148:149], v[158:159], 0, v[148:149]
	v_lshl_add_u64 v[150:151], v[158:159], 0, v[150:151]
	v_lshl_add_u64 v[152:153], v[158:159], 0, v[152:153]
	v_lshl_add_u64 v[154:155], v[158:159], 0, v[154:155]
	v_lshl_add_u64 v[156:157], v[158:159], 0, v[156:157]
	v_lshl_add_u64 v[158:159], v[158:159], 0, v[208:209]
	v_pk_mul_f32 v[208:209], v[8:9], v[8:9]
	v_pk_mul_f32 v[210:211], v[6:7], v[6:7]
	s_waitcnt vmcnt(28)
	v_mul_f32_e32 v219, v16, v16
	v_mul_f32_e32 v212, v13, v13
	s_waitcnt vmcnt(11)
	v_pk_mul_f32 v[214:215], v[172:173], v[172:173]
	v_pk_mul_f32 v[216:217], v[170:171], v[170:171]
	s_waitcnt vmcnt(10)
	v_mul_f32_e32 v218, v175, v175
	s_waitcnt vmcnt(8)
	v_pk_mul_f32 v[222:223], v[186:187], v[186:187]
	v_pk_mul_f32 v[224:225], v[184:185], v[184:185]
	s_waitcnt vmcnt(5)
	v_pk_mul_f32 v[230:231], v[88:89], v[88:89]
	v_pk_mul_f32 v[232:233], v[86:87], v[86:87]
	v_pk_fma_f32 v[242:243], v[10:11], v[10:11], v[98:99] op_sel_hi:[1,1,0]
	v_mul_f32_e32 v221, v17, v17
	v_mul_f32_e32 v227, v182, v182
	v_mul_f32_e32 v229, v183, v183
	v_mul_f32_e32 v220, v177, v177
	v_mul_f32_e32 v226, v95, v95
	v_mul_f32_e32 v228, v97, v97
	v_pk_mov_b32 v[234:235], v[210:211], v[208:209] op_sel:[1,0]
	v_mov_b32_e32 v211, v209
	s_waitcnt vmcnt(3)
; __device__ __forceinline__ float wave_sum(float v) {
;     ...
;     for (int o = 1; o < 64; o <<= 1) v += __shfl_xor(v, o);
;     ...
;     for (int j = 0; j < 16; ++j) { v[j] = __builtin_nontemporal_load(xr + 64 * j); s += (v[j].x * v[j].x + v[j].y * v[j].y) + (v[j].z * v[j].z + v[j].w * v[j].w); }
;     const float rstd = 1.0f / sqrtf(wave_sum(s) * (1.0f / D) + RMS_EPS);
	v_pk_mul_f32 v[208:209], v[190:191], v[190:191]
	v_pk_mul_f32 v[236:237], v[188:189], v[188:189]
	s_waitcnt vmcnt(2)
	v_pk_mul_f32 v[238:239], v[198:199], v[198:199]
	v_pk_mov_b32 v[240:241], v[216:217], v[214:215] op_sel:[1,0]
	v_mov_b32_e32 v217, v215
	v_pk_mov_b32 v[214:215], v[224:225], v[222:223] op_sel:[1,0]
	v_mov_b32_e32 v225, v223
	v_pk_mov_b32 v[222:223], v[232:233], v[230:231] op_sel:[1,0]
	v_mov_b32_e32 v233, v231
	v_pk_mul_f32 v[230:231], v[196:197], v[196:197]
	v_pk_fma_f32 v[212:213], v[12:13], v[12:13], v[212:213] op_sel_hi:[1,1,0]
	v_mov_b32_e32 v243, v219
	v_pk_fma_f32 v[218:219], v[174:175], v[174:175], v[218:219] op_sel_hi:[1,1,0]
	v_mul_f32_e32 v244, v92, v92
	v_mul_f32_e32 v245, v93, v93
	v_pk_add_f32 v[210:211], v[234:235], v[210:211]
	v_pk_mov_b32 v[234:235], v[236:237], v[208:209] op_sel:[1,0]
	v_mov_b32_e32 v237, v209
	v_pk_mov_b32 v[208:209], v[230:231], v[238:239] op_sel:[1,0]
	v_mov_b32_e32 v231, v239
	v_mov_b32_e32 v213, v221
	v_mov_b32_e32 v219, v227
	v_pk_fma_f32 v[220:221], v[176:177], v[176:177], v[220:221] op_sel_hi:[1,1,0]
	v_pk_add_f32 v[214:215], v[214:215], v[224:225]
	v_pk_fma_f32 v[224:225], v[94:95], v[94:95], v[226:227] op_sel_hi:[1,1,0]
	v_pk_fma_f32 v[226:227], v[96:97], v[96:97], v[228:229] op_sel_hi:[1,1,0]
	v_mov_b32_e32 v221, v229
	s_waitcnt vmcnt(1)
	v_mul_f32_e32 v98, v201, v201
	v_mov_b32_e32 v225, v244
	v_mov_b32_e32 v227, v245
	v_mul_f32_e32 v228, v203, v203
	v_pk_add_f32 v[222:223], v[222:223], v[232:233]
	v_pk_add_f32 v[232:233], v[234:235], v[236:237]
	v_pk_add_f32 v[208:209], v[208:209], v[230:231]
	s_waitcnt vmcnt(0)
	v_mul_f32_e32 v253, v204, v204
	v_mul_f32_e32 v254, v205, v205
	v_mul_f32_e32 v194, v206, v206
	v_mul_f32_e32 v178, v207, v207
	v_pk_fma_f32 v[244:245], v[200:201], v[200:201], v[98:99] op_sel_hi:[1,1,0]
	v_pk_fma_f32 v[228:229], v[202:203], v[202:203], v[228:229] op_sel_hi:[1,1,0]
	v_pk_add_f32 v[218:219], v[218:219], v[220:221]
	v_pk_add_f32 v[220:221], v[224:225], v[226:227]
	v_pk_add_f32 v[226:227], v[232:233], v[232:233] op_sel:[0,1] op_sel_hi:[1,0]
	v_pk_add_f32 v[208:209], v[208:209], v[208:209] op_sel:[0,1] op_sel_hi:[1,0]
	v_mov_b32_e32 v245, v194
	v_mov_b32_e32 v229, v178
	v_mov_b32_e32 v227, v253
	v_mov_b32_e32 v209, v254
	v_pk_add_f32 v[228:229], v[244:245], v[228:229]
	v_pk_add_f32 v[208:209], v[226:227], v[208:209]
	v_pk_add_f32 v[216:217], v[240:241], v[216:217]
	v_pk_add_f32 v[208:209], v[208:209], v[228:229]
	v_mul_f32_e32 v249, v180, v180
	v_mul_f32_e32 v250, v181, v181
	v_pk_add_f32 v[216:217], v[216:217], v[216:217] op_sel:[0,1] op_sel_hi:[1,0]
	v_pk_add_f32 v[208:209], v[208:209], v[208:209] op_sel:[0,1] op_sel_hi:[1,0]
	v_mov_b32_e32 v217, v250
	v_mov_b32_e32 v209, v249
	v_pk_add_f32 v[208:209], v[208:209], v[216:217]
	v_mul_f32_e32 v251, v90, v90
	v_pk_add_f32 v[208:209], v[208:209], v[218:219]
	v_mul_f32_e32 v252, v91, v91
	v_pk_add_f32 v[214:215], v[214:215], v[214:215] op_sel:[0,1] op_sel_hi:[1,0]
	v_pk_add_f32 v[208:209], v[208:209], v[208:209] op_sel:[0,1] op_sel_hi:[1,0]
	v_mov_b32_e32 v215, v252
	v_mov_b32_e32 v209, v251
	v_pk_add_f32 v[208:209], v[208:209], v[214:215]
	v_mul_f32_e32 v238, v83, v83
	v_mul_f32_e32 v240, v85, v85
	v_pk_add_f32 v[208:209], v[208:209], v[220:221]
	v_mul_f32_e32 v169, v2, v2
	v_mul_f32_e32 v179, v3, v3
	v_mul_f32_e32 v195, v4, v4
	v_mul_f32_e32 v246, v5, v5
	v_pk_fma_f32 v[238:239], v[82:83], v[82:83], v[238:239] op_sel_hi:[1,1,0]
	v_pk_fma_f32 v[240:241], v[84:85], v[84:85], v[240:241] op_sel_hi:[1,1,0]
	v_pk_add_f32 v[222:223], v[222:223], v[222:223] op_sel:[0,1] op_sel_hi:[1,0]
	v_pk_add_f32 v[208:209], v[208:209], v[208:209] op_sel:[0,1] op_sel_hi:[1,0]
	v_mov_b32_e32 v239, v195
	v_mov_b32_e32 v241, v246
	v_mov_b32_e32 v223, v179
	v_mov_b32_e32 v209, v169
	v_pk_add_f32 v[224:225], v[238:239], v[240:241]
	v_pk_add_f32 v[208:209], v[208:209], v[222:223]
	v_mul_f32_e32 v247, v14, v14
	v_pk_add_f32 v[208:209], v[208:209], v[224:225]
	v_mul_f32_e32 v248, v15, v15
	v_pk_add_f32 v[210:211], v[210:211], v[210:211] op_sel:[0,1] op_sel_hi:[1,0]
	v_pk_add_f32 v[208:209], v[208:209], v[208:209] op_sel:[0,1] op_sel_hi:[1,0]
	v_mov_b32_e32 v211, v248
	v_mov_b32_e32 v209, v247
	v_pk_add_f32 v[212:213], v[242:243], v[212:213]
	v_pk_add_f32 v[208:209], v[208:209], v[210:211]
	s_add_i32 s13, s13, s94
	v_pk_add_f32 v[208:209], v[208:209], v[212:213]
	s_add_i32 s3, s3, s72
	v_add_f32_e32 v98, v208, v209
	ds_bpermute_b32 v169, v161, v98
	v_lshl_add_u64 v[126:127], v[126:127], 0, s[10:11]
	s_cmpk_lt_i32 s13, 0x2000
	s_waitcnt lgkmcnt(0)
	v_add_f32_e32 v98, v98, v169
	ds_bpermute_b32 v169, v162, v98
	s_waitcnt lgkmcnt(0)
	v_add_f32_e32 v98, v98, v169
	ds_bpermute_b32 v169, v163, v98
	s_waitcnt lgkmcnt(0)
	v_add_f32_e32 v98, v98, v169
	ds_bpermute_b32 v169, v164, v98
	s_waitcnt lgkmcnt(0)
	v_add_f32_e32 v98, v98, v169
	ds_bpermute_b32 v169, v165, v98
	s_waitcnt lgkmcnt(0)
	v_add_f32_e32 v98, v98, v169
	ds_bpermute_b32 v169, v166, v98
	s_waitcnt lgkmcnt(0)
; __host__ __device__ __forceinline__ size_t blk(int r, int k, int K) { return (((size_t)((r >> 8) * (K >> 6) + (k >> 6))) << 14) + (size_t)(((r & 255) << 6) + (k & 63)); }
; __device__ __forceinline__ unsigned pk2(float lo, float hi) { f32x2 v = {lo, hi}; bf16x2_t b = __builtin_convertvector(v, bf16x2_t); return __builtin_bit_cast(unsigned, b); }
;     ...
;     const float rstd = 1.0f / sqrtf(wave_sum(s) * (1.0f / D) + RMS_EPS);
; #pragma unroll
;     for (int j = 0; j < 16; ++j) v[j] = v[j] * rstd * gr[64 * j];
;     if (MODE == 2) {
; #pragma unroll
;         for (int j = 0; j < 16; ++j) ((f32x4*)orow + lane)[64 * j] = v[j];
;     } else {
; #pragma unroll
;         for (int j = 0; j < 16; ++j) { u32x2 w; w.x = pk2(v[j].x, v[j].y); w.y = pk2(v[j].z, v[j].w); *(u32x2*)(hrow + blk(mrow, 4 * lane + 256 * j, D)) = w; }
	v_add_f32_e32 v98, v98, v169
	v_fmamk_f32 v98, v98, 0x39800000, v167
	v_mul_f32_e32 v169, 0x4f800000, v98
	v_cmp_gt_f32_e32 vcc, s12, v98
	s_nop 1
	v_cndmask_b32_e32 v98, v98, v169, vcc
	v_sqrt_f32_e32 v169, v98
	s_nop 0
	v_add_u32_e32 v178, -1, v169
	v_add_u32_e32 v179, 1, v169
	v_fma_f32 v194, -v178, v169, v98
	v_fma_f32 v195, -v179, v169, v98
	v_cmp_ge_f32_e64 s[0:1], 0, v194
	s_nop 1
	v_cndmask_b32_e64 v169, v169, v178, s[0:1]
	v_cmp_lt_f32_e64 s[0:1], 0, v195
	s_nop 1
	v_cndmask_b32_e64 v169, v169, v179, s[0:1]
	v_mul_f32_e32 v178, 0x37800000, v169
	v_cndmask_b32_e32 v169, v169, v178, vcc
	v_cmp_class_f32_e32 vcc, v98, v168
	s_nop 1
	v_cndmask_b32_e32 v98, v169, v98, vcc
	v_div_scale_f32 v169, s[0:1], v98, v98, 1.0
	v_rcp_f32_e32 v179, v169
	v_div_scale_f32 v178, vcc, 1.0, v98, 1.0
	v_fma_f32 v194, -v169, v179, 1.0
	v_fmac_f32_e32 v179, v194, v179
	v_mul_f32_e32 v194, v178, v179
	v_fma_f32 v195, -v169, v194, v178
	v_fmac_f32_e32 v194, v195, v179
	v_fma_f32 v169, -v169, v194, v178
	v_div_fmas_f32 v169, v169, v179, v194
	v_div_fixup_f32 v98, v169, v98, 1.0
	v_pk_mul_f32 v[188:189], v[188:189], v[98:99] op_sel_hi:[1,0]
	v_pk_mul_f32 v[190:191], v[190:191], v[98:99] op_sel_hi:[1,0]
	v_pk_mul_f32 v[196:197], v[196:197], v[98:99] op_sel_hi:[1,0]
	v_pk_mul_f32 v[198:199], v[198:199], v[98:99] op_sel_hi:[1,0]
	v_pk_mul_f32 v[200:201], v[200:201], v[98:99] op_sel_hi:[1,0]
	v_pk_mul_f32 v[202:203], v[202:203], v[98:99] op_sel_hi:[1,0]
	v_pk_mul_f32 v[204:205], v[204:205], v[98:99] op_sel_hi:[1,0]
	v_pk_mul_f32 v[206:207], v[206:207], v[98:99] op_sel_hi:[1,0]
	v_pk_mul_f32 v[170:171], v[170:171], v[98:99] op_sel_hi:[1,0]
	v_pk_mul_f32 v[172:173], v[172:173], v[98:99] op_sel_hi:[1,0]
	v_pk_mul_f32 v[174:175], v[174:175], v[98:99] op_sel_hi:[1,0]
	v_pk_mul_f32 v[176:177], v[176:177], v[98:99] op_sel_hi:[1,0]
	v_pk_mul_f32 v[180:181], v[180:181], v[98:99] op_sel_hi:[1,0]
	v_pk_mul_f32 v[182:183], v[182:183], v[98:99] op_sel_hi:[1,0]
	v_pk_mul_f32 v[184:185], v[184:185], v[98:99] op_sel_hi:[1,0]
	v_pk_mul_f32 v[186:187], v[186:187], v[98:99] op_sel_hi:[1,0]
	v_pk_mul_f32 v[94:95], v[94:95], v[98:99] op_sel_hi:[1,0]
	v_pk_mul_f32 v[96:97], v[96:97], v[98:99] op_sel_hi:[1,0]
	v_pk_mul_f32 v[90:91], v[90:91], v[98:99] op_sel_hi:[1,0]
	v_pk_mul_f32 v[92:93], v[92:93], v[98:99] op_sel_hi:[1,0]
	v_pk_mul_f32 v[86:87], v[86:87], v[98:99] op_sel_hi:[1,0]
	v_pk_mul_f32 v[88:89], v[88:89], v[98:99] op_sel_hi:[1,0]
	v_pk_mul_f32 v[82:83], v[82:83], v[98:99] op_sel_hi:[1,0]
	v_pk_mul_f32 v[84:85], v[84:85], v[98:99] op_sel_hi:[1,0]
	v_pk_mul_f32 v[2:3], v[2:3], v[98:99] op_sel_hi:[1,0]
	v_pk_mul_f32 v[4:5], v[4:5], v[98:99] op_sel_hi:[1,0]
	v_pk_mul_f32 v[6:7], v[6:7], v[98:99] op_sel_hi:[1,0]
	v_pk_mul_f32 v[8:9], v[8:9], v[98:99] op_sel_hi:[1,0]
	v_pk_mul_f32 v[10:11], v[10:11], v[98:99] op_sel_hi:[1,0]
	v_pk_mul_f32 v[12:13], v[12:13], v[98:99] op_sel_hi:[1,0]
	v_pk_mul_f32 v[14:15], v[14:15], v[98:99] op_sel_hi:[1,0]
	v_pk_mul_f32 v[16:17], v[16:17], v[98:99] op_sel_hi:[1,0]
	v_pk_mul_f32 v[20:21], v[20:21], v[190:191]
	v_pk_mul_f32 v[18:19], v[18:19], v[188:189]
	v_pk_mul_f32 v[24:25], v[24:25], v[198:199]
	v_pk_mul_f32 v[22:23], v[22:23], v[196:197]
	v_pk_mul_f32 v[28:29], v[28:29], v[202:203]
	v_pk_mul_f32 v[26:27], v[26:27], v[200:201]
	v_pk_mul_f32 v[32:33], v[32:33], v[206:207]
	v_pk_mul_f32 v[30:31], v[30:31], v[204:205]
	v_pk_mul_f32 v[36:37], v[36:37], v[172:173]
	v_pk_mul_f32 v[34:35], v[34:35], v[170:171]
	v_pk_mul_f32 v[40:41], v[40:41], v[176:177]
	v_pk_mul_f32 v[38:39], v[38:39], v[174:175]
	v_pk_mul_f32 v[44:45], v[44:45], v[182:183]
	v_pk_mul_f32 v[42:43], v[42:43], v[180:181]
	v_pk_mul_f32 v[48:49], v[48:49], v[186:187]
	v_pk_mul_f32 v[46:47], v[46:47], v[184:185]
	v_pk_mul_f32 v[52:53], v[52:53], v[96:97]
	v_pk_mul_f32 v[50:51], v[50:51], v[94:95]
	v_pk_mul_f32 v[56:57], v[92:93], v[56:57]
	v_pk_mul_f32 v[54:55], v[90:91], v[54:55]
	v_pk_mul_f32 v[60:61], v[88:89], v[60:61]
	v_pk_mul_f32 v[58:59], v[86:87], v[58:59]
	v_pk_mul_f32 v[64:65], v[84:85], v[64:65]
	v_pk_mul_f32 v[62:63], v[82:83], v[62:63]
	v_pk_mul_f32 v[4:5], v[4:5], v[68:69]
	v_pk_mul_f32 v[2:3], v[2:3], v[66:67]
	v_pk_mul_f32 v[8:9], v[8:9], v[72:73]
	v_pk_mul_f32 v[6:7], v[6:7], v[70:71]
	v_pk_mul_f32 v[12:13], v[12:13], v[76:77]
	v_pk_mul_f32 v[10:11], v[10:11], v[74:75]
	v_pk_mul_f32 v[16:17], v[16:17], v[80:81]
	v_pk_mul_f32 v[14:15], v[14:15], v[78:79]
	v_cvt_pk_bf16_f32 v18, v18, v19
	v_cvt_pk_bf16_f32 v19, v20, v21
	v_cvt_pk_bf16_f32 v20, v22, v23
	v_cvt_pk_bf16_f32 v21, v24, v25
	v_cvt_pk_bf16_f32 v22, v26, v27
	v_cvt_pk_bf16_f32 v23, v28, v29
	v_cvt_pk_bf16_f32 v24, v30, v31
	v_cvt_pk_bf16_f32 v25, v32, v33
	v_cvt_pk_bf16_f32 v26, v34, v35
	v_cvt_pk_bf16_f32 v27, v36, v37
	v_cvt_pk_bf16_f32 v28, v38, v39
	v_cvt_pk_bf16_f32 v29, v40, v41
	v_cvt_pk_bf16_f32 v30, v42, v43
	v_cvt_pk_bf16_f32 v31, v44, v45
	v_cvt_pk_bf16_f32 v32, v46, v47
	v_cvt_pk_bf16_f32 v33, v48, v49
	v_cvt_pk_bf16_f32 v34, v50, v51
	v_cvt_pk_bf16_f32 v35, v52, v53
	v_cvt_pk_bf16_f32 v36, v54, v55
	v_cvt_pk_bf16_f32 v37, v56, v57
	v_cvt_pk_bf16_f32 v38, v58, v59
	v_cvt_pk_bf16_f32 v39, v60, v61
	v_cvt_pk_bf16_f32 v40, v62, v63
	v_cvt_pk_bf16_f32 v41, v64, v65
	v_cvt_pk_bf16_f32 v2, v2, v3
	v_cvt_pk_bf16_f32 v3, v4, v5
	v_cvt_pk_bf16_f32 v4, v6, v7
	v_cvt_pk_bf16_f32 v5, v8, v9
	v_cvt_pk_bf16_f32 v6, v10, v11
	v_cvt_pk_bf16_f32 v7, v12, v13
	v_cvt_pk_bf16_f32 v8, v14, v15
	v_cvt_pk_bf16_f32 v9, v16, v17
	global_store_dwordx2 v[128:129], v[18:19], off nt
	global_store_dwordx2 v[130:131], v[20:21], off nt
	global_store_dwordx2 v[132:133], v[22:23], off nt
	global_store_dwordx2 v[134:135], v[24:25], off nt
	global_store_dwordx2 v[136:137], v[26:27], off nt
	global_store_dwordx2 v[138:139], v[28:29], off nt
	global_store_dwordx2 v[140:141], v[30:31], off nt
	global_store_dwordx2 v[142:143], v[32:33], off nt
	global_store_dwordx2 v[144:145], v[34:35], off nt
	global_store_dwordx2 v[146:147], v[36:37], off nt
	global_store_dwordx2 v[148:149], v[38:39], off nt
	global_store_dwordx2 v[150:151], v[40:41], off nt
	global_store_dwordx2 v[152:153], v[2:3], off nt
	global_store_dwordx2 v[154:155], v[4:5], off nt
	global_store_dwordx2 v[156:157], v[6:7], off nt
	global_store_dwordx2 v[158:159], v[8:9], off nt
	s_cbranch_scc1 .LBB0_53
	v_readlane_b32 s95, v255, 25
	v_lshlrev_b32_e32 v252, 2, v0
	v_lshlrev_b32_e32 v251, 3, v0
